# additionally: the mid-block s_setprio 0 / s_setprio 1 pair inside every 32-MFMA block of the GEMM K-loops removed
# speedup vs baseline: 1.0615x; 1.0011x over previous
; #define PG8_STAGE(bufoff, gbase, voff) do { _Pragma("unroll") for (int _i = 0; _i < 2; ++_i) \
;         __builtin_amdgcn_global_load_lds((const unsigned*)((const char*)(gbase) + (voff)[_i]), (PG8_LAS unsigned*)(lds + (bufoff) + ldsw + _i * 8192), 16, 0, 0); } while (0)
; #define PG8_LDA(dst, b, h) do { _Pragma("unroll") for (int m = 0; m < 4; ++m) _Pragma("unroll") for (int k = 0; k < 2; ++k) dst[m][k] = *(const PG8_LAS bf16x8*)(lds + PG8_SA(b, h) + aoff + m * 2048 + k * 1024); } while (0)
; #define PG8_LDB(dst, b, h) do { _Pragma("unroll") for (int n = 0; n < 2; ++n) _Pragma("unroll") for (int k = 0; k < 2; ++k) dst[n][k] = *(const PG8_LAS bf16x8*)(lds + PG8_SB(b, h) + boff + n * 2048 + k * 1024); } while (0)
; #define PG8_MMA(ai, bj, At, Bt) do { __builtin_amdgcn_s_setprio(1); _Pragma("unroll") for (int m = 0; m < 4; ++m) _Pragma("unroll") for (int n = 0; n < 2; ++n) _Pragma("unroll") for (int k = 0; k < 2; ++k) \
;         acc[ai][bj][m][n] = __builtin_amdgcn_mfma_f32_16x16x32_bf16(Bt[n][k], At[m][k], acc[ai][bj][m][n], 0, 0, 0); __builtin_amdgcn_s_setprio(0); } while (0)
; #define PG8_WAIT_V(n) asm volatile("s_waitcnt vmcnt(" #n ")" ::: "memory")
; #define PG8_WAIT_L(n) asm volatile("s_waitcnt lgkmcnt(" #n ")" ::: "memory")
; #define PG8_BAR __builtin_amdgcn_s_barrier()
; #define PG8_SCHED __builtin_amdgcn_sched_barrier(0)
; template <class Epi, class Sched, bool ALIGN_EPI = false, bool SP2 = false>
; __device__ __forceinline__ void gemm_phase(PG8_LAS unsigned char* lds, const Gemm g, const Sched& S, const Epi& E) {
;     ...
;             PG8_LDB(B0, 0, 0); PG8_LDB(B1, 0, 1); PG8_SCHED; PG8_LDA(At, 0, 0); PG8_STAGE(PG8_SA(1, 1), a1 + hstep, voffA);
;             PG8_WAIT_V(8); PG8_WAIT_L(0); PG8_BAR; PG8_MMA(0, 0, At, B0); PG8_MMA(0, 1, At, B1); PG8_BAR; PG8_SCHED;
;             PG8_LDA(At, 0, 1); PG8_STAGE(PG8_SB(0, 0), b2, voffB); PG8_STAGE(PG8_SB(0, 1), b2 + hstep, voffB); PG8_STAGE(PG8_SA(0, 0), a2, voffA);
;             PG8_WAIT_V(8); PG8_WAIT_L(0); PG8_BAR; PG8_MMA(1, 0, At, B0); PG8_MMA(1, 1, At, B1); PG8_BAR; PG8_SCHED;
.LBB0_162:
	s_add_u32 s10, s44, 0xfffc0080
	s_addc_u32 s11, s45, -1
	s_add_i32 s60, 16, 0x10000
	s_cmp_eq_u32 s59, 12
	s_cselect_b32 s49, s27, s11
	s_cselect_b32 s48, s34, s10
	s_cselect_b32 s47, s25, s58
	s_cselect_b32 s46, s35, s57
	s_add_i32 s10, 16, 0x14000
	v_add_u32_e32 v102, s60, v183
	v_add_u32_e32 v180, s10, v183
	ds_read_b128 v[90:93], v102
	ds_read_b128 v[94:97], v102 offset:1024
	ds_read_b128 v[98:101], v102 offset:2048
	ds_read_b128 v[102:105], v102 offset:3072
	ds_read_b128 v[158:161], v180
	ds_read_b128 v[176:179], v180 offset:1024
	ds_read_b128 v[186:189], v180 offset:2048
	ds_read_b128 v[190:193], v180 offset:3072
	v_lshl_add_u64 v[180:181], s[44:45], 0, v[156:157]
	s_add_i32 m0, s7, 0xc000
	ds_read_b128 v[194:197], v185
	ds_read_b128 v[198:201], v185 offset:1024
	ds_read_b128 v[202:205], v185 offset:2048
	ds_read_b128 v[206:209], v185 offset:3072
	ds_read_b128 v[210:213], v185 offset:4096
	ds_read_b128 v[214:217], v185 offset:5120
	ds_read_b128 v[218:221], v185 offset:6144
	ds_read_b128 v[222:225], v185 offset:7168
	global_load_lds_dwordx4 v[180:181], off
	v_lshl_add_u64 v[180:181], s[44:45], 0, v[154:155]
	s_add_i32 m0, s7, 0xe000
	s_nop 0
	global_load_lds_dwordx4 v[180:181], off
	s_waitcnt vmcnt(8)
	s_waitcnt lgkmcnt(0)
	s_setprio 1
	s_barrier
	v_mfma_f32_16x16x32_bf16 v[142:145], v[90:93], v[194:197], v[142:145]
	v_mfma_f32_16x16x32_bf16 v[138:141], v[98:101], v[194:197], v[138:141]
	v_mfma_f32_16x16x32_bf16 v[126:129], v[90:93], v[202:205], v[126:129]
	v_mfma_f32_16x16x32_bf16 v[122:125], v[98:101], v[202:205], v[122:125]
	v_mfma_f32_16x16x32_bf16 v[110:113], v[90:93], v[210:213], v[110:113]
	v_mfma_f32_16x16x32_bf16 v[106:109], v[98:101], v[210:213], v[106:109]
	v_mfma_f32_16x16x32_bf16 v[78:81], v[90:93], v[218:221], v[78:81]
	v_mfma_f32_16x16x32_bf16 v[74:77], v[98:101], v[218:221], v[74:77]
	v_mfma_f32_16x16x32_bf16 v[142:145], v[94:97], v[198:201], v[142:145]
	v_mfma_f32_16x16x32_bf16 v[138:141], v[102:105], v[198:201], v[138:141]
	v_mfma_f32_16x16x32_bf16 v[126:129], v[94:97], v[206:209], v[126:129]
	v_mfma_f32_16x16x32_bf16 v[122:125], v[102:105], v[206:209], v[122:125]
	v_mfma_f32_16x16x32_bf16 v[110:113], v[94:97], v[214:217], v[110:113]
	v_mfma_f32_16x16x32_bf16 v[106:109], v[102:105], v[214:217], v[106:109]
	v_mfma_f32_16x16x32_bf16 v[78:81], v[94:97], v[222:225], v[78:81]
	v_mfma_f32_16x16x32_bf16 v[74:77], v[102:105], v[222:225], v[74:77]
	v_mfma_f32_16x16x32_bf16 v[134:137], v[158:161], v[194:197], v[134:137]
	v_mfma_f32_16x16x32_bf16 v[130:133], v[186:189], v[194:197], v[130:133]
	v_mfma_f32_16x16x32_bf16 v[118:121], v[158:161], v[202:205], v[118:121]
	v_mfma_f32_16x16x32_bf16 v[114:117], v[186:189], v[202:205], v[114:117]
	v_mfma_f32_16x16x32_bf16 v[86:89], v[158:161], v[210:213], v[86:89]
	v_mfma_f32_16x16x32_bf16 v[82:85], v[186:189], v[210:213], v[82:85]
	v_mfma_f32_16x16x32_bf16 v[70:73], v[158:161], v[218:221], v[70:73]
	v_mfma_f32_16x16x32_bf16 v[66:69], v[186:189], v[218:221], v[66:69]
	v_mfma_f32_16x16x32_bf16 v[134:137], v[176:179], v[198:201], v[134:137]
	v_mfma_f32_16x16x32_bf16 v[130:133], v[190:193], v[198:201], v[130:133]
	v_mfma_f32_16x16x32_bf16 v[118:121], v[176:179], v[206:209], v[118:121]
	v_mfma_f32_16x16x32_bf16 v[114:117], v[190:193], v[206:209], v[114:117]
	v_mfma_f32_16x16x32_bf16 v[86:89], v[176:179], v[214:217], v[86:89]
	v_mfma_f32_16x16x32_bf16 v[82:85], v[190:193], v[214:217], v[82:85]
	v_mfma_f32_16x16x32_bf16 v[70:73], v[176:179], v[222:225], v[70:73]
	v_mfma_f32_16x16x32_bf16 v[66:69], v[190:193], v[222:225], v[66:69]
	s_barrier
	s_setprio 0
	s_add_i32 s11, s60, s6
	v_lshl_add_u64 v[180:181], s[46:47], 0, v[0:1]
	s_mov_b32 m0, s11
	ds_read_b128 v[194:197], v185 offset:16384
	ds_read_b128 v[198:201], v185 offset:17408
	ds_read_b128 v[202:205], v185 offset:18432
	ds_read_b128 v[206:209], v185 offset:19456
	ds_read_b128 v[210:213], v185 offset:20480
	ds_read_b128 v[214:217], v185 offset:21504
	ds_read_b128 v[218:221], v185 offset:22528
	ds_read_b128 v[222:225], v185 offset:23552
	global_load_lds_dwordx4 v[180:181], off
	s_add_i32 m0, s11, 0x2000
	s_add_u32 s60, s46, 0x40000
	v_lshl_add_u64 v[226:227], s[46:47], 0, v[146:147]
	s_addc_u32 s61, s47, 0
	s_add_i32 s10, s10, s6
	global_load_lds_dwordx4 v[226:227], off
	v_lshl_add_u64 v[238:239], s[60:61], 0, v[0:1]
	s_mov_b32 m0, s10
	v_lshl_add_u64 v[240:241], s[48:49], 0, v[148:149]
	global_load_lds_dwordx4 v[238:239], off
	v_lshl_add_u64 v[238:239], s[60:61], 0, v[146:147]
	s_add_i32 m0, s10, 0x2000
	s_nop 0
	global_load_lds_dwordx4 v[238:239], off
	v_lshl_add_u64 v[238:239], s[48:49], 0, v[150:151]
	s_mov_b32 m0, s7
	s_nop 0
	global_load_lds_dwordx4 v[238:239], off
	s_mov_b32 m0, s8
	s_nop 0
	global_load_lds_dwordx4 v[240:241], off
	s_waitcnt vmcnt(8)
	s_waitcnt lgkmcnt(0)
	s_setprio 1
	s_barrier
; #define PG8_STAGE(bufoff, gbase, voff) do { _Pragma("unroll") for (int _i = 0; _i < 2; ++_i) \
;         __builtin_amdgcn_global_load_lds((const unsigned*)((const char*)(gbase) + (voff)[_i]), (PG8_LAS unsigned*)(lds + (bufoff) + ldsw + _i * 8192), 16, 0, 0); } while (0)
; #define PG8_LDA(dst, b, h) do { _Pragma("unroll") for (int m = 0; m < 4; ++m) _Pragma("unroll") for (int k = 0; k < 2; ++k) dst[m][k] = *(const PG8_LAS bf16x8*)(lds + PG8_SA(b, h) + aoff + m * 2048 + k * 1024); } while (0)
; #define PG8_LDB(dst, b, h) do { _Pragma("unroll") for (int n = 0; n < 2; ++n) _Pragma("unroll") for (int k = 0; k < 2; ++k) dst[n][k] = *(const PG8_LAS bf16x8*)(lds + PG8_SB(b, h) + boff + n * 2048 + k * 1024); } while (0)
; #define PG8_MMA(ai, bj, At, Bt) do { __builtin_amdgcn_s_setprio(1); _Pragma("unroll") for (int m = 0; m < 4; ++m) _Pragma("unroll") for (int n = 0; n < 2; ++n) _Pragma("unroll") for (int k = 0; k < 2; ++k) \
;         acc[ai][bj][m][n] = __builtin_amdgcn_mfma_f32_16x16x32_bf16(Bt[n][k], At[m][k], acc[ai][bj][m][n], 0, 0, 0); __builtin_amdgcn_s_setprio(0); } while (0)
; #define PG8_WAIT_V(n) asm volatile("s_waitcnt vmcnt(" #n ")" ::: "memory")
; #define PG8_WAIT_L(n) asm volatile("s_waitcnt lgkmcnt(" #n ")" ::: "memory")
; #define PG8_BAR __builtin_amdgcn_s_barrier()
; #define PG8_SCHED __builtin_amdgcn_sched_barrier(0)
; template <class Epi, class Sched, bool ALIGN_EPI = false, bool SP2 = false>
; __device__ __forceinline__ void gemm_phase(PG8_LAS unsigned char* lds, const Gemm g, const Sched& S, const Epi& E) {
;     ...
;             PG8_WAIT_V(8); PG8_WAIT_L(0); PG8_BAR; PG8_MMA(1, 0, At, B0); PG8_MMA(1, 1, At, B1); PG8_BAR; PG8_SCHED;
;             PG8_LDB(B0, 1, 0); PG8_LDB(B1, 1, 1); PG8_SCHED; PG8_LDA(At, 1, 0); PG8_STAGE(PG8_SA(0, 1), a2 + hstep, voffA);
;             PG8_WAIT_V(8); PG8_WAIT_L(0); PG8_BAR; PG8_MMA(0, 0, At, B0); PG8_MMA(0, 1, At, B1); PG8_BAR; PG8_SCHED;
	v_mfma_f32_16x16x32_bf16 v[62:65], v[90:93], v[194:197], v[62:65]
	v_mfma_f32_16x16x32_bf16 v[58:61], v[98:101], v[194:197], v[58:61]
	v_mfma_f32_16x16x32_bf16 v[46:49], v[90:93], v[202:205], v[46:49]
	v_mfma_f32_16x16x32_bf16 v[42:45], v[98:101], v[202:205], v[42:45]
	v_mfma_f32_16x16x32_bf16 v[30:33], v[90:93], v[210:213], v[30:33]
	v_mfma_f32_16x16x32_bf16 v[26:29], v[98:101], v[210:213], v[26:29]
	v_mfma_f32_16x16x32_bf16 v[14:17], v[90:93], v[218:221], v[14:17]
	v_mfma_f32_16x16x32_bf16 v[10:13], v[98:101], v[218:221], v[10:13]
	v_mfma_f32_16x16x32_bf16 v[62:65], v[94:97], v[198:201], v[62:65]
	v_mfma_f32_16x16x32_bf16 v[58:61], v[102:105], v[198:201], v[58:61]
	v_mfma_f32_16x16x32_bf16 v[46:49], v[94:97], v[206:209], v[46:49]
	v_mfma_f32_16x16x32_bf16 v[42:45], v[102:105], v[206:209], v[42:45]
	v_mfma_f32_16x16x32_bf16 v[30:33], v[94:97], v[214:217], v[30:33]
	v_mfma_f32_16x16x32_bf16 v[26:29], v[102:105], v[214:217], v[26:29]
	v_mfma_f32_16x16x32_bf16 v[14:17], v[94:97], v[222:225], v[14:17]
	v_mfma_f32_16x16x32_bf16 v[10:13], v[102:105], v[222:225], v[10:13]
	v_mfma_f32_16x16x32_bf16 v[54:57], v[158:161], v[194:197], v[54:57]
	v_mfma_f32_16x16x32_bf16 v[50:53], v[186:189], v[194:197], v[50:53]
	v_mfma_f32_16x16x32_bf16 v[38:41], v[158:161], v[202:205], v[38:41]
	v_mfma_f32_16x16x32_bf16 v[34:37], v[186:189], v[202:205], v[34:37]
	v_mfma_f32_16x16x32_bf16 v[22:25], v[158:161], v[210:213], v[22:25]
	v_mfma_f32_16x16x32_bf16 v[18:21], v[186:189], v[210:213], v[18:21]
	v_mfma_f32_16x16x32_bf16 v[6:9], v[158:161], v[218:221], v[6:9]
	v_mfma_f32_16x16x32_bf16 v[2:5], v[186:189], v[218:221], v[2:5]
	v_mfma_f32_16x16x32_bf16 v[54:57], v[176:179], v[198:201], v[54:57]
	v_mfma_f32_16x16x32_bf16 v[50:53], v[190:193], v[198:201], v[50:53]
	v_mfma_f32_16x16x32_bf16 v[38:41], v[176:179], v[206:209], v[38:41]
	v_mfma_f32_16x16x32_bf16 v[34:37], v[190:193], v[206:209], v[34:37]
	v_mfma_f32_16x16x32_bf16 v[22:25], v[176:179], v[214:217], v[22:25]
	v_mfma_f32_16x16x32_bf16 v[18:21], v[190:193], v[214:217], v[18:21]
	v_mfma_f32_16x16x32_bf16 v[6:9], v[176:179], v[222:225], v[6:9]
	v_mfma_f32_16x16x32_bf16 v[2:5], v[190:193], v[222:225], v[2:5]
	s_barrier
	s_setprio 0
	s_add_i32 s10, 16, 0x18000
	s_add_i32 s11, 16, 0x1c000
	v_add_u32_e32 v102, s10, v183
	v_add_u32_e32 v190, s11, v183
	ds_read_b128 v[90:93], v102
	ds_read_b128 v[94:97], v102 offset:1024
	ds_read_b128 v[98:101], v102 offset:2048
	ds_read_b128 v[102:105], v102 offset:3072
	ds_read_b128 v[158:161], v190
	ds_read_b128 v[176:179], v190 offset:1024
	ds_read_b128 v[186:189], v190 offset:2048
	ds_read_b128 v[190:193], v190 offset:3072
	s_add_u32 s48, s48, 0x40000
	s_addc_u32 s49, s49, 0
	s_mov_b32 m0, s9
	v_lshl_add_u64 v[242:243], s[48:49], 0, v[150:151]
	ds_read_b128 v[194:197], v185 offset:32768
	ds_read_b128 v[198:201], v185 offset:33792
	ds_read_b128 v[202:205], v185 offset:34816
	ds_read_b128 v[206:209], v185 offset:35840
	ds_read_b128 v[210:213], v185 offset:36864
	ds_read_b128 v[214:217], v185 offset:37888
	ds_read_b128 v[218:221], v185 offset:38912
	ds_read_b128 v[222:225], v185 offset:39936
	global_load_lds_dwordx4 v[242:243], off
	v_lshl_add_u64 v[242:243], s[48:49], 0, v[148:149]
	s_mov_b32 m0, s50
	s_nop 0
	global_load_lds_dwordx4 v[242:243], off
	s_waitcnt vmcnt(8)
	s_waitcnt lgkmcnt(0)
	s_setprio 1
	s_barrier
	v_mfma_f32_16x16x32_bf16 v[142:145], v[90:93], v[194:197], v[142:145]
	v_mfma_f32_16x16x32_bf16 v[138:141], v[98:101], v[194:197], v[138:141]
	v_mfma_f32_16x16x32_bf16 v[126:129], v[90:93], v[202:205], v[126:129]
	v_mfma_f32_16x16x32_bf16 v[122:125], v[98:101], v[202:205], v[122:125]
	v_mfma_f32_16x16x32_bf16 v[110:113], v[90:93], v[210:213], v[110:113]
	v_mfma_f32_16x16x32_bf16 v[106:109], v[98:101], v[210:213], v[106:109]
	v_mfma_f32_16x16x32_bf16 v[78:81], v[90:93], v[218:221], v[78:81]
	v_mfma_f32_16x16x32_bf16 v[74:77], v[98:101], v[218:221], v[74:77]
	v_mfma_f32_16x16x32_bf16 v[142:145], v[94:97], v[198:201], v[142:145]
	v_mfma_f32_16x16x32_bf16 v[138:141], v[102:105], v[198:201], v[138:141]
	v_mfma_f32_16x16x32_bf16 v[126:129], v[94:97], v[206:209], v[126:129]
	v_mfma_f32_16x16x32_bf16 v[122:125], v[102:105], v[206:209], v[122:125]
	v_mfma_f32_16x16x32_bf16 v[110:113], v[94:97], v[214:217], v[110:113]
	v_mfma_f32_16x16x32_bf16 v[106:109], v[102:105], v[214:217], v[106:109]
	v_mfma_f32_16x16x32_bf16 v[78:81], v[94:97], v[222:225], v[78:81]
	v_mfma_f32_16x16x32_bf16 v[74:77], v[102:105], v[222:225], v[74:77]
	v_mfma_f32_16x16x32_bf16 v[134:137], v[158:161], v[194:197], v[134:137]
	v_mfma_f32_16x16x32_bf16 v[130:133], v[186:189], v[194:197], v[130:133]
	v_mfma_f32_16x16x32_bf16 v[118:121], v[158:161], v[202:205], v[118:121]
	v_mfma_f32_16x16x32_bf16 v[114:117], v[186:189], v[202:205], v[114:117]
	v_mfma_f32_16x16x32_bf16 v[86:89], v[158:161], v[210:213], v[86:89]
	v_mfma_f32_16x16x32_bf16 v[82:85], v[186:189], v[210:213], v[82:85]
	v_mfma_f32_16x16x32_bf16 v[70:73], v[158:161], v[218:221], v[70:73]
	v_mfma_f32_16x16x32_bf16 v[66:69], v[186:189], v[218:221], v[66:69]
	v_mfma_f32_16x16x32_bf16 v[134:137], v[176:179], v[198:201], v[134:137]
	v_mfma_f32_16x16x32_bf16 v[130:133], v[190:193], v[198:201], v[130:133]
	v_mfma_f32_16x16x32_bf16 v[118:121], v[176:179], v[206:209], v[118:121]
	v_mfma_f32_16x16x32_bf16 v[114:117], v[190:193], v[206:209], v[114:117]
	v_mfma_f32_16x16x32_bf16 v[86:89], v[176:179], v[214:217], v[86:89]
	v_mfma_f32_16x16x32_bf16 v[82:85], v[190:193], v[214:217], v[82:85]
	v_mfma_f32_16x16x32_bf16 v[70:73], v[176:179], v[222:225], v[70:73]
	v_mfma_f32_16x16x32_bf16 v[66:69], v[190:193], v[222:225], v[66:69]
	s_barrier
; #define PG8_STAGE(bufoff, gbase, voff) do { _Pragma("unroll") for (int _i = 0; _i < 2; ++_i) \
;         __builtin_amdgcn_global_load_lds((const unsigned*)((const char*)(gbase) + (voff)[_i]), (PG8_LAS unsigned*)(lds + (bufoff) + ldsw + _i * 8192), 16, 0, 0); } while (0)
; #define PG8_LDA(dst, b, h) do { _Pragma("unroll") for (int m = 0; m < 4; ++m) _Pragma("unroll") for (int k = 0; k < 2; ++k) dst[m][k] = *(const PG8_LAS bf16x8*)(lds + PG8_SA(b, h) + aoff + m * 2048 + k * 1024); } while (0)
; #define PG8_MMA(ai, bj, At, Bt) do { __builtin_amdgcn_s_setprio(1); _Pragma("unroll") for (int m = 0; m < 4; ++m) _Pragma("unroll") for (int n = 0; n < 2; ++n) _Pragma("unroll") for (int k = 0; k < 2; ++k) \
;         acc[ai][bj][m][n] = __builtin_amdgcn_mfma_f32_16x16x32_bf16(Bt[n][k], At[m][k], acc[ai][bj][m][n], 0, 0, 0); __builtin_amdgcn_s_setprio(0); } while (0)
; #define PG8_WAIT_V(n) asm volatile("s_waitcnt vmcnt(" #n ")" ::: "memory")
; #define PG8_WAIT_L(n) asm volatile("s_waitcnt lgkmcnt(" #n ")" ::: "memory")
; #define PG8_BAR __builtin_amdgcn_s_barrier()
; #define PG8_SCHED __builtin_amdgcn_sched_barrier(0)
; template <class Epi, class Sched, bool ALIGN_EPI = false, bool SP2 = false>
; __device__ __forceinline__ void gemm_phase(PG8_LAS unsigned char* lds, const Gemm g, const Sched& S, const Epi& E) {
;     ...
;             PG8_LDA(At, 1, 1); PG8_STAGE(PG8_SB(1, 0), b3, voffB); PG8_STAGE(PG8_SB(1, 1), b3 + hstep, voffB); PG8_STAGE(PG8_SA(1, 0), a3, voffA);
;             PG8_WAIT_V(8); PG8_WAIT_L(0); PG8_BAR; PG8_MMA(1, 0, At, B0); PG8_MMA(1, 1, At, B1); PG8_BAR; PG8_SCHED;
	s_setprio 0
	s_add_i32 s10, s10, s6
	v_lshl_add_u64 v[180:181], v[180:181], 0, s[28:29]
	s_mov_b32 m0, s10
	ds_read_b128 v[194:197], v185 offset:49152
	ds_read_b128 v[198:201], v185 offset:50176
	ds_read_b128 v[202:205], v185 offset:51200
	ds_read_b128 v[206:209], v185 offset:52224
	ds_read_b128 v[210:213], v185 offset:53248
	ds_read_b128 v[214:217], v185 offset:54272
	ds_read_b128 v[218:221], v185 offset:55296
	ds_read_b128 v[222:225], v185 offset:56320
	global_load_lds_dwordx4 v[180:181], off
	s_add_i32 m0, s10, 0x2000
	s_add_u32 s46, s46, 0x40080
	v_lshl_add_u64 v[180:181], v[226:227], 0, s[28:29]
	s_addc_u32 s47, s47, 0
	s_add_i32 s10, s11, s6
	global_load_lds_dwordx4 v[180:181], off
	v_lshl_add_u64 v[180:181], s[46:47], 0, v[0:1]
	s_mov_b32 m0, s10
	s_nop 0
	global_load_lds_dwordx4 v[180:181], off
	v_lshl_add_u64 v[180:181], s[46:47], 0, v[146:147]
	s_add_i32 m0, s10, 0x2000
	s_nop 0
	global_load_lds_dwordx4 v[180:181], off
	v_lshl_add_u64 v[180:181], v[238:239], 0, s[28:29]
	s_mov_b32 m0, s52
	s_nop 0
	global_load_lds_dwordx4 v[180:181], off
	v_lshl_add_u64 v[180:181], v[240:241], 0, s[28:29]
	s_mov_b32 m0, s53
	s_nop 0
	global_load_lds_dwordx4 v[180:181], off
	s_waitcnt vmcnt(8)
	s_waitcnt lgkmcnt(0)
	s_setprio 1
	s_barrier
	v_mfma_f32_16x16x32_bf16 v[62:65], v[90:93], v[194:197], v[62:65]
	v_mfma_f32_16x16x32_bf16 v[58:61], v[98:101], v[194:197], v[58:61]
	v_mfma_f32_16x16x32_bf16 v[46:49], v[90:93], v[202:205], v[46:49]
	v_mfma_f32_16x16x32_bf16 v[42:45], v[98:101], v[202:205], v[42:45]
	v_mfma_f32_16x16x32_bf16 v[30:33], v[90:93], v[210:213], v[30:33]
	v_mfma_f32_16x16x32_bf16 v[26:29], v[98:101], v[210:213], v[26:29]
	v_mfma_f32_16x16x32_bf16 v[14:17], v[90:93], v[218:221], v[14:17]
	v_mfma_f32_16x16x32_bf16 v[10:13], v[98:101], v[218:221], v[10:13]
	v_mfma_f32_16x16x32_bf16 v[62:65], v[94:97], v[198:201], v[62:65]
	v_mfma_f32_16x16x32_bf16 v[58:61], v[102:105], v[198:201], v[58:61]
	v_mfma_f32_16x16x32_bf16 v[46:49], v[94:97], v[206:209], v[46:49]
	v_mfma_f32_16x16x32_bf16 v[42:45], v[102:105], v[206:209], v[42:45]
	v_mfma_f32_16x16x32_bf16 v[30:33], v[94:97], v[214:217], v[30:33]
	v_mfma_f32_16x16x32_bf16 v[26:29], v[102:105], v[214:217], v[26:29]
	v_mfma_f32_16x16x32_bf16 v[14:17], v[94:97], v[222:225], v[14:17]
	v_mfma_f32_16x16x32_bf16 v[10:13], v[102:105], v[222:225], v[10:13]
	v_mfma_f32_16x16x32_bf16 v[54:57], v[158:161], v[194:197], v[54:57]
	v_mfma_f32_16x16x32_bf16 v[50:53], v[186:189], v[194:197], v[50:53]
	v_mfma_f32_16x16x32_bf16 v[38:41], v[158:161], v[202:205], v[38:41]
	v_mfma_f32_16x16x32_bf16 v[34:37], v[186:189], v[202:205], v[34:37]
	v_mfma_f32_16x16x32_bf16 v[22:25], v[158:161], v[210:213], v[22:25]
	v_mfma_f32_16x16x32_bf16 v[18:21], v[186:189], v[210:213], v[18:21]
	v_mfma_f32_16x16x32_bf16 v[6:9], v[158:161], v[218:221], v[6:9]
	v_mfma_f32_16x16x32_bf16 v[2:5], v[186:189], v[218:221], v[2:5]
	v_mfma_f32_16x16x32_bf16 v[54:57], v[176:179], v[198:201], v[54:57]
	v_mfma_f32_16x16x32_bf16 v[50:53], v[190:193], v[198:201], v[50:53]
	v_mfma_f32_16x16x32_bf16 v[38:41], v[176:179], v[206:209], v[38:41]
	v_mfma_f32_16x16x32_bf16 v[34:37], v[190:193], v[206:209], v[34:37]
	v_mfma_f32_16x16x32_bf16 v[22:25], v[176:179], v[214:217], v[22:25]
	v_mfma_f32_16x16x32_bf16 v[18:21], v[190:193], v[214:217], v[18:21]
	v_mfma_f32_16x16x32_bf16 v[6:9], v[176:179], v[222:225], v[6:9]
	v_mfma_f32_16x16x32_bf16 v[2:5], v[190:193], v[222:225], v[2:5]
	s_barrier
	s_setprio 0
	s_add_i32 s59, s59, 2
	s_add_u32 s57, s57, 0x100
	s_addc_u32 s58, s58, 0
	s_add_u32 s44, s44, 0x100
	s_addc_u32 s45, s45, 0
	s_cmp_gt_u32 s59, 13
	s_cbranch_scc0 .LBB0_162
	s_and_b64 vcc, exec, s[22:23]
	s_cbranch_vccz .LBB0_165
	s_barrier

; #define PG8_STAGE(bufoff, gbase, voff) do { _Pragma("unroll") for (int _i = 0; _i < 2; ++_i) \
;         __builtin_amdgcn_global_load_lds((const unsigned*)((const char*)(gbase) + (voff)[_i]), (PG8_LAS unsigned*)(lds + (bufoff) + ldsw + _i * 8192), 16, 0, 0); } while (0)
; #define PG8_LDA(dst, b, h) do { _Pragma("unroll") for (int m = 0; m < 4; ++m) _Pragma("unroll") for (int k = 0; k < 2; ++k) dst[m][k] = *(const PG8_LAS bf16x8*)(lds + PG8_SA(b, h) + aoff + m * 2048 + k * 1024); } while (0)
; #define PG8_LDB(dst, b, h) do { _Pragma("unroll") for (int n = 0; n < 2; ++n) _Pragma("unroll") for (int k = 0; k < 2; ++k) dst[n][k] = *(const PG8_LAS bf16x8*)(lds + PG8_SB(b, h) + boff + n * 2048 + k * 1024); } while (0)
; #define PG8_MMA(ai, bj, At, Bt) do { __builtin_amdgcn_s_setprio(1); _Pragma("unroll") for (int m = 0; m < 4; ++m) _Pragma("unroll") for (int n = 0; n < 2; ++n) _Pragma("unroll") for (int k = 0; k < 2; ++k) \
;         acc[ai][bj][m][n] = __builtin_amdgcn_mfma_f32_16x16x32_bf16(Bt[n][k], At[m][k], acc[ai][bj][m][n], 0, 0, 0); __builtin_amdgcn_s_setprio(0); } while (0)
; #define PG8_WAIT_V(n) asm volatile("s_waitcnt vmcnt(" #n ")" ::: "memory")
; #define PG8_WAIT_L(n) asm volatile("s_waitcnt lgkmcnt(" #n ")" ::: "memory")
; #define PG8_BAR __builtin_amdgcn_s_barrier()
; #define PG8_SCHED __builtin_amdgcn_sched_barrier(0)
; template <class Epi, class Sched, bool ALIGN_EPI = false, bool SP2 = false>
; __device__ __forceinline__ void gemm_phase(PG8_LAS unsigned char* lds, const Gemm g, const Sched& S, const Epi& E) {
;     ...
;             PG8_LDB(B0, 0, 0); PG8_LDB(B1, 0, 1); PG8_SCHED; PG8_LDA(At, 0, 0); PG8_STAGE(PG8_SA(1, 1), a1 + hstep, voffA);
;             PG8_WAIT_V(8); PG8_WAIT_L(0); PG8_BAR; PG8_MMA(0, 0, At, B0); PG8_MMA(0, 1, At, B1); PG8_BAR; PG8_SCHED;
;             PG8_LDA(At, 0, 1); PG8_STAGE(PG8_SB(0, 0), b2, voffB); PG8_STAGE(PG8_SB(0, 1), b2 + hstep, voffB); PG8_STAGE(PG8_SA(0, 0), a2, voffA);
;             PG8_WAIT_V(8); PG8_WAIT_L(0); PG8_BAR; PG8_MMA(1, 0, At, B0); PG8_MMA(1, 1, At, B1); PG8_BAR; PG8_SCHED;
.LBB0_243:
	s_add_u32 s10, s46, 0xfffc0080
	s_addc_u32 s11, s47, -1
	s_add_i32 s58, 16, 0x10000
	s_cmp_eq_u32 s57, 12
	s_cselect_b32 s51, s34, s11
	s_cselect_b32 s50, s35, s10
	s_cselect_b32 s49, s27, s56
	s_cselect_b32 s48, s41, s55
	s_add_i32 s10, 16, 0x14000
	v_add_u32_e32 v156, s58, v141
	v_add_u32_e32 v160, s10, v141
	ds_read_b128 v[144:147], v156
	ds_read_b128 v[148:151], v156 offset:1024
	ds_read_b128 v[152:155], v156 offset:2048
	ds_read_b128 v[156:159], v156 offset:3072
	ds_read_b128 v[176:179], v160
	ds_read_b128 v[180:183], v160 offset:1024
	ds_read_b128 v[184:187], v160 offset:2048
	ds_read_b128 v[188:191], v160 offset:3072
	v_lshl_add_u64 v[160:161], s[46:47], 0, v[138:139]
	s_add_i32 m0, s4, 0xc000
	ds_read_b128 v[192:195], v143
	ds_read_b128 v[196:199], v143 offset:1024
	ds_read_b128 v[200:203], v143 offset:2048
	ds_read_b128 v[204:207], v143 offset:3072
	ds_read_b128 v[208:211], v143 offset:4096
	ds_read_b128 v[212:215], v143 offset:5120
	ds_read_b128 v[216:219], v143 offset:6144
	ds_read_b128 v[220:223], v143 offset:7168
	global_load_lds_dwordx4 v[160:161], off
	v_lshl_add_u64 v[160:161], s[46:47], 0, v[136:137]
	s_add_i32 m0, s4, 0xe000
	s_nop 0
	global_load_lds_dwordx4 v[160:161], off
	s_waitcnt vmcnt(8)
	s_waitcnt lgkmcnt(0)
	s_setprio 1
	s_barrier
	v_mfma_f32_16x16x32_bf16 v[126:129], v[144:147], v[192:195], v[126:129]
	v_mfma_f32_16x16x32_bf16 v[122:125], v[152:155], v[192:195], v[122:125]
	v_mfma_f32_16x16x32_bf16 v[118:121], v[144:147], v[200:203], v[118:121]
	v_mfma_f32_16x16x32_bf16 v[114:117], v[152:155], v[200:203], v[114:117]
	v_mfma_f32_16x16x32_bf16 v[102:105], v[144:147], v[208:211], v[102:105]
	v_mfma_f32_16x16x32_bf16 v[98:101], v[152:155], v[208:211], v[98:101]
	v_mfma_f32_16x16x32_bf16 v[86:89], v[144:147], v[216:219], v[86:89]
	v_mfma_f32_16x16x32_bf16 v[82:85], v[152:155], v[216:219], v[82:85]
	v_mfma_f32_16x16x32_bf16 v[126:129], v[148:151], v[196:199], v[126:129]
	v_mfma_f32_16x16x32_bf16 v[122:125], v[156:159], v[196:199], v[122:125]
	v_mfma_f32_16x16x32_bf16 v[118:121], v[148:151], v[204:207], v[118:121]
	v_mfma_f32_16x16x32_bf16 v[114:117], v[156:159], v[204:207], v[114:117]
	v_mfma_f32_16x16x32_bf16 v[102:105], v[148:151], v[212:215], v[102:105]
	v_mfma_f32_16x16x32_bf16 v[98:101], v[156:159], v[212:215], v[98:101]
	v_mfma_f32_16x16x32_bf16 v[86:89], v[148:151], v[220:223], v[86:89]
	v_mfma_f32_16x16x32_bf16 v[82:85], v[156:159], v[220:223], v[82:85]
	v_mfma_f32_16x16x32_bf16 v[110:113], v[176:179], v[192:195], v[110:113]
	v_mfma_f32_16x16x32_bf16 v[106:109], v[184:187], v[192:195], v[106:109]
	v_mfma_f32_16x16x32_bf16 v[94:97], v[176:179], v[200:203], v[94:97]
	v_mfma_f32_16x16x32_bf16 v[90:93], v[184:187], v[200:203], v[90:93]
	v_mfma_f32_16x16x32_bf16 v[78:81], v[176:179], v[208:211], v[78:81]
	v_mfma_f32_16x16x32_bf16 v[74:77], v[184:187], v[208:211], v[74:77]
	v_mfma_f32_16x16x32_bf16 v[70:73], v[176:179], v[216:219], v[70:73]
	v_mfma_f32_16x16x32_bf16 v[66:69], v[184:187], v[216:219], v[66:69]
	v_mfma_f32_16x16x32_bf16 v[110:113], v[180:183], v[196:199], v[110:113]
	v_mfma_f32_16x16x32_bf16 v[106:109], v[188:191], v[196:199], v[106:109]
	v_mfma_f32_16x16x32_bf16 v[94:97], v[180:183], v[204:207], v[94:97]
	v_mfma_f32_16x16x32_bf16 v[90:93], v[188:191], v[204:207], v[90:93]
	v_mfma_f32_16x16x32_bf16 v[78:81], v[180:183], v[212:215], v[78:81]
	v_mfma_f32_16x16x32_bf16 v[74:77], v[188:191], v[212:215], v[74:77]
	v_mfma_f32_16x16x32_bf16 v[70:73], v[180:183], v[220:223], v[70:73]
	v_mfma_f32_16x16x32_bf16 v[66:69], v[188:191], v[220:223], v[66:69]
	s_barrier
	s_setprio 0
	s_add_i32 s11, s58, s3
	v_lshl_add_u64 v[160:161], s[48:49], 0, v[0:1]
	s_mov_b32 m0, s11
	ds_read_b128 v[192:195], v143 offset:16384
	ds_read_b128 v[196:199], v143 offset:17408
	ds_read_b128 v[200:203], v143 offset:18432
	ds_read_b128 v[204:207], v143 offset:19456
	ds_read_b128 v[208:211], v143 offset:20480
	ds_read_b128 v[212:215], v143 offset:21504
	ds_read_b128 v[216:219], v143 offset:22528
	ds_read_b128 v[220:223], v143 offset:23552
	global_load_lds_dwordx4 v[160:161], off
	s_add_i32 m0, s11, 0x2000
	s_add_u32 s58, s48, 0x40000
	v_lshl_add_u64 v[224:225], s[48:49], 0, v[130:131]
	s_addc_u32 s59, s49, 0
	s_add_i32 s10, s10, s3
	global_load_lds_dwordx4 v[224:225], off
	v_lshl_add_u64 v[226:227], s[58:59], 0, v[0:1]
	s_mov_b32 m0, s10
	v_lshl_add_u64 v[238:239], s[50:51], 0, v[132:133]
	global_load_lds_dwordx4 v[226:227], off
	v_lshl_add_u64 v[226:227], s[58:59], 0, v[130:131]
	s_add_i32 m0, s10, 0x2000
	s_nop 0
	global_load_lds_dwordx4 v[226:227], off
	v_lshl_add_u64 v[226:227], s[50:51], 0, v[134:135]
	s_mov_b32 m0, s4
	s_nop 0
	global_load_lds_dwordx4 v[226:227], off
	s_mov_b32 m0, s5
	s_nop 0
	global_load_lds_dwordx4 v[238:239], off
	s_waitcnt vmcnt(8)
	s_waitcnt lgkmcnt(0)
	s_setprio 1
	s_barrier
; #define PG8_STAGE(bufoff, gbase, voff) do { _Pragma("unroll") for (int _i = 0; _i < 2; ++_i) \
;         __builtin_amdgcn_global_load_lds((const unsigned*)((const char*)(gbase) + (voff)[_i]), (PG8_LAS unsigned*)(lds + (bufoff) + ldsw + _i * 8192), 16, 0, 0); } while (0)
; #define PG8_LDA(dst, b, h) do { _Pragma("unroll") for (int m = 0; m < 4; ++m) _Pragma("unroll") for (int k = 0; k < 2; ++k) dst[m][k] = *(const PG8_LAS bf16x8*)(lds + PG8_SA(b, h) + aoff + m * 2048 + k * 1024); } while (0)
; #define PG8_LDB(dst, b, h) do { _Pragma("unroll") for (int n = 0; n < 2; ++n) _Pragma("unroll") for (int k = 0; k < 2; ++k) dst[n][k] = *(const PG8_LAS bf16x8*)(lds + PG8_SB(b, h) + boff + n * 2048 + k * 1024); } while (0)
; #define PG8_MMA(ai, bj, At, Bt) do { __builtin_amdgcn_s_setprio(1); _Pragma("unroll") for (int m = 0; m < 4; ++m) _Pragma("unroll") for (int n = 0; n < 2; ++n) _Pragma("unroll") for (int k = 0; k < 2; ++k) \
;         acc[ai][bj][m][n] = __builtin_amdgcn_mfma_f32_16x16x32_bf16(Bt[n][k], At[m][k], acc[ai][bj][m][n], 0, 0, 0); __builtin_amdgcn_s_setprio(0); } while (0)
; #define PG8_WAIT_V(n) asm volatile("s_waitcnt vmcnt(" #n ")" ::: "memory")
; #define PG8_WAIT_L(n) asm volatile("s_waitcnt lgkmcnt(" #n ")" ::: "memory")
; #define PG8_BAR __builtin_amdgcn_s_barrier()
; #define PG8_SCHED __builtin_amdgcn_sched_barrier(0)
; template <class Epi, class Sched, bool ALIGN_EPI = false, bool SP2 = false>
; __device__ __forceinline__ void gemm_phase(PG8_LAS unsigned char* lds, const Gemm g, const Sched& S, const Epi& E) {
;     ...
;             PG8_WAIT_V(8); PG8_WAIT_L(0); PG8_BAR; PG8_MMA(1, 0, At, B0); PG8_MMA(1, 1, At, B1); PG8_BAR; PG8_SCHED;
;             PG8_LDB(B0, 1, 0); PG8_LDB(B1, 1, 1); PG8_SCHED; PG8_LDA(At, 1, 0); PG8_STAGE(PG8_SA(0, 1), a2 + hstep, voffA);
;             PG8_WAIT_V(8); PG8_WAIT_L(0); PG8_BAR; PG8_MMA(0, 0, At, B0); PG8_MMA(0, 1, At, B1); PG8_BAR; PG8_SCHED;
	v_mfma_f32_16x16x32_bf16 v[62:65], v[144:147], v[192:195], v[62:65]
	v_mfma_f32_16x16x32_bf16 v[58:61], v[152:155], v[192:195], v[58:61]
	v_mfma_f32_16x16x32_bf16 v[54:57], v[144:147], v[200:203], v[54:57]
	v_mfma_f32_16x16x32_bf16 v[50:53], v[152:155], v[200:203], v[50:53]
	v_mfma_f32_16x16x32_bf16 v[38:41], v[144:147], v[208:211], v[38:41]
	v_mfma_f32_16x16x32_bf16 v[34:37], v[152:155], v[208:211], v[34:37]
	v_mfma_f32_16x16x32_bf16 v[22:25], v[144:147], v[216:219], v[22:25]
	v_mfma_f32_16x16x32_bf16 v[18:21], v[152:155], v[216:219], v[18:21]
	v_mfma_f32_16x16x32_bf16 v[62:65], v[148:151], v[196:199], v[62:65]
	v_mfma_f32_16x16x32_bf16 v[58:61], v[156:159], v[196:199], v[58:61]
	v_mfma_f32_16x16x32_bf16 v[54:57], v[148:151], v[204:207], v[54:57]
	v_mfma_f32_16x16x32_bf16 v[50:53], v[156:159], v[204:207], v[50:53]
	v_mfma_f32_16x16x32_bf16 v[38:41], v[148:151], v[212:215], v[38:41]
	v_mfma_f32_16x16x32_bf16 v[34:37], v[156:159], v[212:215], v[34:37]
	v_mfma_f32_16x16x32_bf16 v[22:25], v[148:151], v[220:223], v[22:25]
	v_mfma_f32_16x16x32_bf16 v[18:21], v[156:159], v[220:223], v[18:21]
	v_mfma_f32_16x16x32_bf16 v[46:49], v[176:179], v[192:195], v[46:49]
	v_mfma_f32_16x16x32_bf16 v[42:45], v[184:187], v[192:195], v[42:45]
	v_mfma_f32_16x16x32_bf16 v[30:33], v[176:179], v[200:203], v[30:33]
	v_mfma_f32_16x16x32_bf16 v[26:29], v[184:187], v[200:203], v[26:29]
	v_mfma_f32_16x16x32_bf16 v[14:17], v[176:179], v[208:211], v[14:17]
	v_mfma_f32_16x16x32_bf16 v[10:13], v[184:187], v[208:211], v[10:13]
	v_mfma_f32_16x16x32_bf16 v[6:9], v[176:179], v[216:219], v[6:9]
	v_mfma_f32_16x16x32_bf16 v[2:5], v[184:187], v[216:219], v[2:5]
	v_mfma_f32_16x16x32_bf16 v[46:49], v[180:183], v[196:199], v[46:49]
	v_mfma_f32_16x16x32_bf16 v[42:45], v[188:191], v[196:199], v[42:45]
	v_mfma_f32_16x16x32_bf16 v[30:33], v[180:183], v[204:207], v[30:33]
	v_mfma_f32_16x16x32_bf16 v[26:29], v[188:191], v[204:207], v[26:29]
	v_mfma_f32_16x16x32_bf16 v[14:17], v[180:183], v[212:215], v[14:17]
	v_mfma_f32_16x16x32_bf16 v[10:13], v[188:191], v[212:215], v[10:13]
	v_mfma_f32_16x16x32_bf16 v[6:9], v[180:183], v[220:223], v[6:9]
	v_mfma_f32_16x16x32_bf16 v[2:5], v[188:191], v[220:223], v[2:5]
	s_barrier
	s_setprio 0
	s_add_i32 s10, 16, 0x18000
	s_add_i32 s11, 16, 0x1c000
	v_add_u32_e32 v156, s10, v141
	v_add_u32_e32 v188, s11, v141
	ds_read_b128 v[144:147], v156
	ds_read_b128 v[148:151], v156 offset:1024
	ds_read_b128 v[152:155], v156 offset:2048
	ds_read_b128 v[156:159], v156 offset:3072
	ds_read_b128 v[176:179], v188
	ds_read_b128 v[180:183], v188 offset:1024
	ds_read_b128 v[184:187], v188 offset:2048
	ds_read_b128 v[188:191], v188 offset:3072
	s_add_u32 s50, s50, 0x40000
	s_addc_u32 s51, s51, 0
	s_mov_b32 m0, s6
	v_lshl_add_u64 v[240:241], s[50:51], 0, v[134:135]
	ds_read_b128 v[192:195], v143 offset:32768
	ds_read_b128 v[196:199], v143 offset:33792
	ds_read_b128 v[200:203], v143 offset:34816
	ds_read_b128 v[204:207], v143 offset:35840
	ds_read_b128 v[208:211], v143 offset:36864
	ds_read_b128 v[212:215], v143 offset:37888
	ds_read_b128 v[216:219], v143 offset:38912
	ds_read_b128 v[220:223], v143 offset:39936
	global_load_lds_dwordx4 v[240:241], off
	v_lshl_add_u64 v[240:241], s[50:51], 0, v[132:133]
	s_mov_b32 m0, s7
	s_nop 0
	global_load_lds_dwordx4 v[240:241], off
	s_waitcnt vmcnt(8)
	s_waitcnt lgkmcnt(0)
	s_setprio 1
	s_barrier
	v_mfma_f32_16x16x32_bf16 v[126:129], v[144:147], v[192:195], v[126:129]
	v_mfma_f32_16x16x32_bf16 v[122:125], v[152:155], v[192:195], v[122:125]
	v_mfma_f32_16x16x32_bf16 v[118:121], v[144:147], v[200:203], v[118:121]
	v_mfma_f32_16x16x32_bf16 v[114:117], v[152:155], v[200:203], v[114:117]
	v_mfma_f32_16x16x32_bf16 v[102:105], v[144:147], v[208:211], v[102:105]
	v_mfma_f32_16x16x32_bf16 v[98:101], v[152:155], v[208:211], v[98:101]
	v_mfma_f32_16x16x32_bf16 v[86:89], v[144:147], v[216:219], v[86:89]
	v_mfma_f32_16x16x32_bf16 v[82:85], v[152:155], v[216:219], v[82:85]
	v_mfma_f32_16x16x32_bf16 v[126:129], v[148:151], v[196:199], v[126:129]
	v_mfma_f32_16x16x32_bf16 v[122:125], v[156:159], v[196:199], v[122:125]
	v_mfma_f32_16x16x32_bf16 v[118:121], v[148:151], v[204:207], v[118:121]
	v_mfma_f32_16x16x32_bf16 v[114:117], v[156:159], v[204:207], v[114:117]
	v_mfma_f32_16x16x32_bf16 v[102:105], v[148:151], v[212:215], v[102:105]
	v_mfma_f32_16x16x32_bf16 v[98:101], v[156:159], v[212:215], v[98:101]
	v_mfma_f32_16x16x32_bf16 v[86:89], v[148:151], v[220:223], v[86:89]
	v_mfma_f32_16x16x32_bf16 v[82:85], v[156:159], v[220:223], v[82:85]
	v_mfma_f32_16x16x32_bf16 v[110:113], v[176:179], v[192:195], v[110:113]
	v_mfma_f32_16x16x32_bf16 v[106:109], v[184:187], v[192:195], v[106:109]
	v_mfma_f32_16x16x32_bf16 v[94:97], v[176:179], v[200:203], v[94:97]
	v_mfma_f32_16x16x32_bf16 v[90:93], v[184:187], v[200:203], v[90:93]
	v_mfma_f32_16x16x32_bf16 v[78:81], v[176:179], v[208:211], v[78:81]
	v_mfma_f32_16x16x32_bf16 v[74:77], v[184:187], v[208:211], v[74:77]
	v_mfma_f32_16x16x32_bf16 v[70:73], v[176:179], v[216:219], v[70:73]
	v_mfma_f32_16x16x32_bf16 v[66:69], v[184:187], v[216:219], v[66:69]
	v_mfma_f32_16x16x32_bf16 v[110:113], v[180:183], v[196:199], v[110:113]
	v_mfma_f32_16x16x32_bf16 v[106:109], v[188:191], v[196:199], v[106:109]
	v_mfma_f32_16x16x32_bf16 v[94:97], v[180:183], v[204:207], v[94:97]
	v_mfma_f32_16x16x32_bf16 v[90:93], v[188:191], v[204:207], v[90:93]
	v_mfma_f32_16x16x32_bf16 v[78:81], v[180:183], v[212:215], v[78:81]
	v_mfma_f32_16x16x32_bf16 v[74:77], v[188:191], v[212:215], v[74:77]
	v_mfma_f32_16x16x32_bf16 v[70:73], v[180:183], v[220:223], v[70:73]
	v_mfma_f32_16x16x32_bf16 v[66:69], v[188:191], v[220:223], v[66:69]
	s_barrier
; #define PG8_STAGE(bufoff, gbase, voff) do { _Pragma("unroll") for (int _i = 0; _i < 2; ++_i) \
;         __builtin_amdgcn_global_load_lds((const unsigned*)((const char*)(gbase) + (voff)[_i]), (PG8_LAS unsigned*)(lds + (bufoff) + ldsw + _i * 8192), 16, 0, 0); } while (0)
; #define PG8_LDA(dst, b, h) do { _Pragma("unroll") for (int m = 0; m < 4; ++m) _Pragma("unroll") for (int k = 0; k < 2; ++k) dst[m][k] = *(const PG8_LAS bf16x8*)(lds + PG8_SA(b, h) + aoff + m * 2048 + k * 1024); } while (0)
; #define PG8_MMA(ai, bj, At, Bt) do { __builtin_amdgcn_s_setprio(1); _Pragma("unroll") for (int m = 0; m < 4; ++m) _Pragma("unroll") for (int n = 0; n < 2; ++n) _Pragma("unroll") for (int k = 0; k < 2; ++k) \
;         acc[ai][bj][m][n] = __builtin_amdgcn_mfma_f32_16x16x32_bf16(Bt[n][k], At[m][k], acc[ai][bj][m][n], 0, 0, 0); __builtin_amdgcn_s_setprio(0); } while (0)
; #define PG8_WAIT_V(n) asm volatile("s_waitcnt vmcnt(" #n ")" ::: "memory")
; #define PG8_WAIT_L(n) asm volatile("s_waitcnt lgkmcnt(" #n ")" ::: "memory")
; #define PG8_BAR __builtin_amdgcn_s_barrier()
; #define PG8_SCHED __builtin_amdgcn_sched_barrier(0)
; template <class Epi, class Sched, bool ALIGN_EPI = false, bool SP2 = false>
; __device__ __forceinline__ void gemm_phase(PG8_LAS unsigned char* lds, const Gemm g, const Sched& S, const Epi& E) {
;     ...
;             PG8_LDA(At, 1, 1); PG8_STAGE(PG8_SB(1, 0), b3, voffB); PG8_STAGE(PG8_SB(1, 1), b3 + hstep, voffB); PG8_STAGE(PG8_SA(1, 0), a3, voffA);
;             PG8_WAIT_V(8); PG8_WAIT_L(0); PG8_BAR; PG8_MMA(1, 0, At, B0); PG8_MMA(1, 1, At, B1); PG8_BAR; PG8_SCHED;
;     ...
;         if constexpr (ALIGN_EPI) { if (wr == 0) PG8_BAR; }
	s_setprio 0
	s_add_i32 s10, s10, s3
	v_lshl_add_u64 v[160:161], v[160:161], 0, s[28:29]
	s_mov_b32 m0, s10
	ds_read_b128 v[192:195], v143 offset:49152
	ds_read_b128 v[196:199], v143 offset:50176
	ds_read_b128 v[200:203], v143 offset:51200
	ds_read_b128 v[204:207], v143 offset:52224
	ds_read_b128 v[208:211], v143 offset:53248
	ds_read_b128 v[212:215], v143 offset:54272
	ds_read_b128 v[216:219], v143 offset:55296
	ds_read_b128 v[220:223], v143 offset:56320
	global_load_lds_dwordx4 v[160:161], off
	s_add_i32 m0, s10, 0x2000
	s_add_u32 s48, s48, 0x40080
	v_lshl_add_u64 v[160:161], v[224:225], 0, s[28:29]
	s_addc_u32 s49, s49, 0
	s_add_i32 s10, s11, s3
	global_load_lds_dwordx4 v[160:161], off
	v_lshl_add_u64 v[160:161], s[48:49], 0, v[0:1]
	s_mov_b32 m0, s10
	s_nop 0
	global_load_lds_dwordx4 v[160:161], off
	v_lshl_add_u64 v[160:161], s[48:49], 0, v[130:131]
	s_add_i32 m0, s10, 0x2000
	s_nop 0
	global_load_lds_dwordx4 v[160:161], off
	v_lshl_add_u64 v[160:161], v[226:227], 0, s[28:29]
	s_mov_b32 m0, s8
	s_nop 0
	global_load_lds_dwordx4 v[160:161], off
	v_lshl_add_u64 v[160:161], v[238:239], 0, s[28:29]
	s_mov_b32 m0, s9
	s_nop 0
	global_load_lds_dwordx4 v[160:161], off
	s_waitcnt vmcnt(8)
	s_waitcnt lgkmcnt(0)
	s_setprio 1
	s_barrier
	v_mfma_f32_16x16x32_bf16 v[62:65], v[144:147], v[192:195], v[62:65]
	v_mfma_f32_16x16x32_bf16 v[58:61], v[152:155], v[192:195], v[58:61]
	v_mfma_f32_16x16x32_bf16 v[54:57], v[144:147], v[200:203], v[54:57]
	v_mfma_f32_16x16x32_bf16 v[50:53], v[152:155], v[200:203], v[50:53]
	v_mfma_f32_16x16x32_bf16 v[38:41], v[144:147], v[208:211], v[38:41]
	v_mfma_f32_16x16x32_bf16 v[34:37], v[152:155], v[208:211], v[34:37]
	v_mfma_f32_16x16x32_bf16 v[22:25], v[144:147], v[216:219], v[22:25]
	v_mfma_f32_16x16x32_bf16 v[18:21], v[152:155], v[216:219], v[18:21]
	v_mfma_f32_16x16x32_bf16 v[62:65], v[148:151], v[196:199], v[62:65]
	v_mfma_f32_16x16x32_bf16 v[58:61], v[156:159], v[196:199], v[58:61]
	v_mfma_f32_16x16x32_bf16 v[54:57], v[148:151], v[204:207], v[54:57]
	v_mfma_f32_16x16x32_bf16 v[50:53], v[156:159], v[204:207], v[50:53]
	v_mfma_f32_16x16x32_bf16 v[38:41], v[148:151], v[212:215], v[38:41]
	v_mfma_f32_16x16x32_bf16 v[34:37], v[156:159], v[212:215], v[34:37]
	v_mfma_f32_16x16x32_bf16 v[22:25], v[148:151], v[220:223], v[22:25]
	v_mfma_f32_16x16x32_bf16 v[18:21], v[156:159], v[220:223], v[18:21]
	v_mfma_f32_16x16x32_bf16 v[46:49], v[176:179], v[192:195], v[46:49]
	v_mfma_f32_16x16x32_bf16 v[42:45], v[184:187], v[192:195], v[42:45]
	v_mfma_f32_16x16x32_bf16 v[30:33], v[176:179], v[200:203], v[30:33]
	v_mfma_f32_16x16x32_bf16 v[26:29], v[184:187], v[200:203], v[26:29]
	v_mfma_f32_16x16x32_bf16 v[14:17], v[176:179], v[208:211], v[14:17]
	v_mfma_f32_16x16x32_bf16 v[10:13], v[184:187], v[208:211], v[10:13]
	v_mfma_f32_16x16x32_bf16 v[6:9], v[176:179], v[216:219], v[6:9]
	v_mfma_f32_16x16x32_bf16 v[2:5], v[184:187], v[216:219], v[2:5]
	v_mfma_f32_16x16x32_bf16 v[46:49], v[180:183], v[196:199], v[46:49]
	v_mfma_f32_16x16x32_bf16 v[42:45], v[188:191], v[196:199], v[42:45]
	v_mfma_f32_16x16x32_bf16 v[30:33], v[180:183], v[204:207], v[30:33]
	v_mfma_f32_16x16x32_bf16 v[26:29], v[188:191], v[204:207], v[26:29]
	v_mfma_f32_16x16x32_bf16 v[14:17], v[180:183], v[212:215], v[14:17]
	v_mfma_f32_16x16x32_bf16 v[10:13], v[188:191], v[212:215], v[10:13]
	v_mfma_f32_16x16x32_bf16 v[6:9], v[180:183], v[220:223], v[6:9]
	v_mfma_f32_16x16x32_bf16 v[2:5], v[188:191], v[220:223], v[2:5]
	s_barrier
	s_setprio 0
	s_add_i32 s57, s57, 2
	s_add_u32 s55, s55, 0x100
	s_addc_u32 s56, s56, 0
	s_add_u32 s46, s46, 0x100
	s_addc_u32 s47, s47, 0
	s_cmp_gt_u32 s57, 13
	s_cbranch_scc0 .LBB0_243
	s_and_b64 vcc, exec, s[24:25]
	s_cbranch_vccz .LBB0_246
	s_barrier

; #define PG8_STAGE(bufoff, gbase, voff) do { _Pragma("unroll") for (int _i = 0; _i < 2; ++_i) \
;         __builtin_amdgcn_global_load_lds((const unsigned*)((const char*)(gbase) + (voff)[_i]), (PG8_LAS unsigned*)(lds + (bufoff) + ldsw + _i * 8192), 16, 0, 0); } while (0)
; #define PG8_LDA(dst, b, h) do { _Pragma("unroll") for (int m = 0; m < 4; ++m) _Pragma("unroll") for (int k = 0; k < 2; ++k) dst[m][k] = *(const PG8_LAS bf16x8*)(lds + PG8_SA(b, h) + aoff + m * 2048 + k * 1024); } while (0)
; #define PG8_LDB(dst, b, h) do { _Pragma("unroll") for (int n = 0; n < 2; ++n) _Pragma("unroll") for (int k = 0; k < 2; ++k) dst[n][k] = *(const PG8_LAS bf16x8*)(lds + PG8_SB(b, h) + boff + n * 2048 + k * 1024); } while (0)
; #define PG8_MMA(ai, bj, At, Bt) do { __builtin_amdgcn_s_setprio(1); _Pragma("unroll") for (int m = 0; m < 4; ++m) _Pragma("unroll") for (int n = 0; n < 2; ++n) _Pragma("unroll") for (int k = 0; k < 2; ++k) \
;         acc[ai][bj][m][n] = __builtin_amdgcn_mfma_f32_16x16x32_bf16(Bt[n][k], At[m][k], acc[ai][bj][m][n], 0, 0, 0); __builtin_amdgcn_s_setprio(0); } while (0)
; #define PG8_WAIT_V(n) asm volatile("s_waitcnt vmcnt(" #n ")" ::: "memory")
; #define PG8_BAR __builtin_amdgcn_s_barrier()
; template <class Epi, class Sched, bool ALIGN_EPI = false, bool SP2 = false>
; __device__ __forceinline__ void gemm_phase(PG8_LAS unsigned char* lds, const Gemm g, const Sched& S, const Epi& E) {
;     ...
;         for (int t = 0; t < nt; t += 2) {
;             const bool last = (t == nt - 2);
;             const char* a1 = cA + (size_t)(t + 1) * kstep;
;             const char* a2 = last ? nA : cA + (size_t)(t + 2) * kstep; const char* b2 = last ? nB : cB + (size_t)(t + 2) * kstep;
;             const char* a3 = a2 + kstep; const char* b3 = b2 + kstep;
;             if (last && has_next) S.a_ready(nxt);
;             if constexpr (SP2) {
;             PG8_LDB(B0, 0, 0); PG8_LDB(B1, 0, 1); PG8_SCHED; PG8_LDA(At, 0, 0); PG8_STAGE(PG8_SA(1, 1), a1 + hstep, voffA);
;             PG8_WAIT_V(8); PG8_WAIT_L(0); PG8_BAR; PG8_MMA(0, 0, At, B0); PG8_MMA(0, 1, At, B1); PG8_BAR; PG8_SCHED;
;             PG8_LDA(At, 0, 1); PG8_STAGE(PG8_SB(0, 0), b2, voffB); PG8_STAGE(PG8_SB(0, 1), b2 + hstep, voffB); PG8_STAGE(PG8_SA(0, 0), a2, voffA);
;             PG8_WAIT_V(8); PG8_WAIT_L(0); PG8_BAR; PG8_MMA(1, 0, At, B0); PG8_MMA(1, 1, At, B1); PG8_BAR; PG8_SCHED;
.LBB0_915:
	s_add_u32 s10, s42, 0xfffc0080
	s_addc_u32 s11, s43, -1
	s_add_i32 s35, 16, 0x10000
	s_cmp_eq_u32 s34, 12
	s_cselect_b32 s73, s0, s11
	s_cselect_b32 s72, s8, s10
	s_cselect_b32 s69, s9, s27
	s_cselect_b32 s68, s23, s25
	s_add_i32 s45, 16, 0x14000
	v_add_u32_e32 v78, s35, v197
	v_add_u32_e32 v94, s45, v197
	ds_read_b128 v[58:61], v78
	ds_read_b128 v[62:65], v78 offset:1024
	ds_read_b128 v[74:77], v78 offset:2048
	ds_read_b128 v[78:81], v78 offset:3072
	ds_read_b128 v[82:85], v94
	ds_read_b128 v[86:89], v94 offset:1024
	ds_read_b128 v[90:93], v94 offset:2048
	ds_read_b128 v[94:97], v94 offset:3072
	v_lshl_add_u64 v[194:195], s[42:43], 0, v[184:185]
	s_add_i32 m0, s77, 0xc000
	ds_read_b128 v[186:189], v199
	ds_read_b128 v[190:193], v199 offset:1024
	ds_read_b128 v[200:203], v199 offset:2048
	ds_read_b128 v[204:207], v199 offset:3072
	ds_read_b128 v[208:211], v199 offset:4096
	ds_read_b128 v[212:215], v199 offset:5120
	ds_read_b128 v[216:219], v199 offset:6144
	ds_read_b128 v[220:223], v199 offset:7168
	global_load_lds_dwordx4 v[194:195], off
	v_lshl_add_u64 v[194:195], s[42:43], 0, v[182:183]
	s_add_i32 m0, s77, 0xe000
	s_nop 0
	global_load_lds_dwordx4 v[194:195], off
	s_waitcnt vmcnt(8)
	s_waitcnt lgkmcnt(0)
	s_setprio 1
	s_barrier
	v_mfma_f32_16x16x32_bf16 v[158:161], v[58:61], v[186:189], v[158:161]
	v_mfma_f32_16x16x32_bf16 v[154:157], v[74:77], v[186:189], v[154:157]
	v_mfma_f32_16x16x32_bf16 v[142:145], v[58:61], v[200:203], v[142:145]
	v_mfma_f32_16x16x32_bf16 v[138:141], v[74:77], v[200:203], v[138:141]
	v_mfma_f32_16x16x32_bf16 v[126:129], v[58:61], v[208:211], v[126:129]
	v_mfma_f32_16x16x32_bf16 v[122:125], v[74:77], v[208:211], v[122:125]
	v_mfma_f32_16x16x32_bf16 v[110:113], v[58:61], v[216:219], v[110:113]
	v_mfma_f32_16x16x32_bf16 v[106:109], v[74:77], v[216:219], v[106:109]
	v_mfma_f32_16x16x32_bf16 v[158:161], v[62:65], v[190:193], v[158:161]
	v_mfma_f32_16x16x32_bf16 v[154:157], v[78:81], v[190:193], v[154:157]
	v_mfma_f32_16x16x32_bf16 v[142:145], v[62:65], v[204:207], v[142:145]
	v_mfma_f32_16x16x32_bf16 v[138:141], v[78:81], v[204:207], v[138:141]
	v_mfma_f32_16x16x32_bf16 v[126:129], v[62:65], v[212:215], v[126:129]
	v_mfma_f32_16x16x32_bf16 v[122:125], v[78:81], v[212:215], v[122:125]
	v_mfma_f32_16x16x32_bf16 v[110:113], v[62:65], v[220:223], v[110:113]
	v_mfma_f32_16x16x32_bf16 v[106:109], v[78:81], v[220:223], v[106:109]
	v_mfma_f32_16x16x32_bf16 v[150:153], v[82:85], v[186:189], v[150:153]
	v_mfma_f32_16x16x32_bf16 v[146:149], v[90:93], v[186:189], v[146:149]
	v_mfma_f32_16x16x32_bf16 v[134:137], v[82:85], v[200:203], v[134:137]
	v_mfma_f32_16x16x32_bf16 v[130:133], v[90:93], v[200:203], v[130:133]
	v_mfma_f32_16x16x32_bf16 v[118:121], v[82:85], v[208:211], v[118:121]
	v_mfma_f32_16x16x32_bf16 v[114:117], v[90:93], v[208:211], v[114:117]
	v_mfma_f32_16x16x32_bf16 v[102:105], v[82:85], v[216:219], v[102:105]
	v_mfma_f32_16x16x32_bf16 v[98:101], v[90:93], v[216:219], v[98:101]
	v_mfma_f32_16x16x32_bf16 v[150:153], v[86:89], v[190:193], v[150:153]
	v_mfma_f32_16x16x32_bf16 v[146:149], v[94:97], v[190:193], v[146:149]
	v_mfma_f32_16x16x32_bf16 v[134:137], v[86:89], v[204:207], v[134:137]
	v_mfma_f32_16x16x32_bf16 v[130:133], v[94:97], v[204:207], v[130:133]
	v_mfma_f32_16x16x32_bf16 v[118:121], v[86:89], v[212:215], v[118:121]
	v_mfma_f32_16x16x32_bf16 v[114:117], v[94:97], v[212:215], v[114:117]
	v_mfma_f32_16x16x32_bf16 v[102:105], v[86:89], v[220:223], v[102:105]
	v_mfma_f32_16x16x32_bf16 v[98:101], v[94:97], v[220:223], v[98:101]
	s_barrier
	s_setprio 0
	s_add_i32 s10, s35, s76
	v_lshl_add_u64 v[194:195], s[68:69], 0, v[0:1]
	s_mov_b32 m0, s10
	ds_read_b128 v[186:189], v199 offset:16384
	ds_read_b128 v[190:193], v199 offset:17408
	ds_read_b128 v[200:203], v199 offset:18432
	ds_read_b128 v[204:207], v199 offset:19456
	ds_read_b128 v[208:211], v199 offset:20480
	ds_read_b128 v[212:215], v199 offset:21504
	ds_read_b128 v[216:219], v199 offset:22528
	ds_read_b128 v[220:223], v199 offset:23552
	global_load_lds_dwordx4 v[194:195], off
	s_add_i32 m0, s10, 0x2000
	s_add_u32 s10, s68, 0x40000
	v_lshl_add_u64 v[224:225], s[68:69], 0, v[180:181]
	s_addc_u32 s11, s69, 0
	s_add_i32 s35, s45, s76
	global_load_lds_dwordx4 v[224:225], off
	v_lshl_add_u64 v[226:227], s[10:11], 0, v[0:1]
	s_mov_b32 m0, s35
	v_lshl_add_u64 v[238:239], s[72:73], 0, v[178:179]
	global_load_lds_dwordx4 v[226:227], off
	v_lshl_add_u64 v[226:227], s[10:11], 0, v[180:181]
	s_add_i32 m0, s35, 0x2000
	s_nop 0
	global_load_lds_dwordx4 v[226:227], off
	v_lshl_add_u64 v[226:227], s[72:73], 0, v[176:177]
	s_mov_b32 m0, s77
	s_nop 0
	global_load_lds_dwordx4 v[226:227], off
	s_mov_b32 m0, s2
	s_nop 0
	global_load_lds_dwordx4 v[238:239], off
	s_waitcnt vmcnt(8)
	s_waitcnt lgkmcnt(0)
	s_setprio 1
	s_barrier
; #define PG8_STAGE(bufoff, gbase, voff) do { _Pragma("unroll") for (int _i = 0; _i < 2; ++_i) \
;         __builtin_amdgcn_global_load_lds((const unsigned*)((const char*)(gbase) + (voff)[_i]), (PG8_LAS unsigned*)(lds + (bufoff) + ldsw + _i * 8192), 16, 0, 0); } while (0)
; #define PG8_LDA(dst, b, h) do { _Pragma("unroll") for (int m = 0; m < 4; ++m) _Pragma("unroll") for (int k = 0; k < 2; ++k) dst[m][k] = *(const PG8_LAS bf16x8*)(lds + PG8_SA(b, h) + aoff + m * 2048 + k * 1024); } while (0)
; #define PG8_LDB(dst, b, h) do { _Pragma("unroll") for (int n = 0; n < 2; ++n) _Pragma("unroll") for (int k = 0; k < 2; ++k) dst[n][k] = *(const PG8_LAS bf16x8*)(lds + PG8_SB(b, h) + boff + n * 2048 + k * 1024); } while (0)
; #define PG8_MMA(ai, bj, At, Bt) do { __builtin_amdgcn_s_setprio(1); _Pragma("unroll") for (int m = 0; m < 4; ++m) _Pragma("unroll") for (int n = 0; n < 2; ++n) _Pragma("unroll") for (int k = 0; k < 2; ++k) \
;         acc[ai][bj][m][n] = __builtin_amdgcn_mfma_f32_16x16x32_bf16(Bt[n][k], At[m][k], acc[ai][bj][m][n], 0, 0, 0); __builtin_amdgcn_s_setprio(0); } while (0)
; #define PG8_WAIT_V(n) asm volatile("s_waitcnt vmcnt(" #n ")" ::: "memory")
; #define PG8_WAIT_L(n) asm volatile("s_waitcnt lgkmcnt(" #n ")" ::: "memory")
; #define PG8_BAR __builtin_amdgcn_s_barrier()
; #define PG8_SCHED __builtin_amdgcn_sched_barrier(0)
; template <class Epi, class Sched, bool ALIGN_EPI = false, bool SP2 = false>
; __device__ __forceinline__ void gemm_phase(PG8_LAS unsigned char* lds, const Gemm g, const Sched& S, const Epi& E) {
;     ...
;             PG8_WAIT_V(8); PG8_WAIT_L(0); PG8_BAR; PG8_MMA(1, 0, At, B0); PG8_MMA(1, 1, At, B1); PG8_BAR; PG8_SCHED;
;             PG8_LDB(B0, 1, 0); PG8_LDB(B1, 1, 1); PG8_SCHED; PG8_LDA(At, 1, 0); PG8_STAGE(PG8_SA(0, 1), a2 + hstep, voffA);
;             PG8_WAIT_V(8); PG8_WAIT_L(0); PG8_BAR; PG8_MMA(0, 0, At, B0); PG8_MMA(0, 1, At, B1); PG8_BAR; PG8_SCHED;
	v_mfma_f32_16x16x32_bf16 v[70:73], v[58:61], v[186:189], v[70:73]
	v_mfma_f32_16x16x32_bf16 v[66:69], v[74:77], v[186:189], v[66:69]
	v_mfma_f32_16x16x32_bf16 v[46:49], v[58:61], v[200:203], v[46:49]
	v_mfma_f32_16x16x32_bf16 v[42:45], v[74:77], v[200:203], v[42:45]
	v_mfma_f32_16x16x32_bf16 v[30:33], v[58:61], v[208:211], v[30:33]
	v_mfma_f32_16x16x32_bf16 v[26:29], v[74:77], v[208:211], v[26:29]
	v_mfma_f32_16x16x32_bf16 v[14:17], v[58:61], v[216:219], v[14:17]
	v_mfma_f32_16x16x32_bf16 v[10:13], v[74:77], v[216:219], v[10:13]
	v_mfma_f32_16x16x32_bf16 v[70:73], v[62:65], v[190:193], v[70:73]
	v_mfma_f32_16x16x32_bf16 v[66:69], v[78:81], v[190:193], v[66:69]
	v_mfma_f32_16x16x32_bf16 v[46:49], v[62:65], v[204:207], v[46:49]
	v_mfma_f32_16x16x32_bf16 v[42:45], v[78:81], v[204:207], v[42:45]
	v_mfma_f32_16x16x32_bf16 v[30:33], v[62:65], v[212:215], v[30:33]
	v_mfma_f32_16x16x32_bf16 v[26:29], v[78:81], v[212:215], v[26:29]
	v_mfma_f32_16x16x32_bf16 v[14:17], v[62:65], v[220:223], v[14:17]
	v_mfma_f32_16x16x32_bf16 v[10:13], v[78:81], v[220:223], v[10:13]
	v_mfma_f32_16x16x32_bf16 v[54:57], v[82:85], v[186:189], v[54:57]
	v_mfma_f32_16x16x32_bf16 v[50:53], v[90:93], v[186:189], v[50:53]
	v_mfma_f32_16x16x32_bf16 v[38:41], v[82:85], v[200:203], v[38:41]
	v_mfma_f32_16x16x32_bf16 v[34:37], v[90:93], v[200:203], v[34:37]
	v_mfma_f32_16x16x32_bf16 v[22:25], v[82:85], v[208:211], v[22:25]
	v_mfma_f32_16x16x32_bf16 v[18:21], v[90:93], v[208:211], v[18:21]
	v_mfma_f32_16x16x32_bf16 v[6:9], v[82:85], v[216:219], v[6:9]
	v_mfma_f32_16x16x32_bf16 v[2:5], v[90:93], v[216:219], v[2:5]
	v_mfma_f32_16x16x32_bf16 v[54:57], v[86:89], v[190:193], v[54:57]
	v_mfma_f32_16x16x32_bf16 v[50:53], v[94:97], v[190:193], v[50:53]
	v_mfma_f32_16x16x32_bf16 v[38:41], v[86:89], v[204:207], v[38:41]
	v_mfma_f32_16x16x32_bf16 v[34:37], v[94:97], v[204:207], v[34:37]
	v_mfma_f32_16x16x32_bf16 v[22:25], v[86:89], v[212:215], v[22:25]
	v_mfma_f32_16x16x32_bf16 v[18:21], v[94:97], v[212:215], v[18:21]
	v_mfma_f32_16x16x32_bf16 v[6:9], v[86:89], v[220:223], v[6:9]
	v_mfma_f32_16x16x32_bf16 v[2:5], v[94:97], v[220:223], v[2:5]
	s_barrier
	s_setprio 0
	s_add_i32 s35, 16, 0x18000
	s_add_i32 s45, 16, 0x1c000
	v_add_u32_e32 v78, s35, v197
	v_add_u32_e32 v94, s45, v197
	ds_read_b128 v[58:61], v78
	ds_read_b128 v[62:65], v78 offset:1024
	ds_read_b128 v[74:77], v78 offset:2048
	ds_read_b128 v[78:81], v78 offset:3072
	ds_read_b128 v[82:85], v94
	ds_read_b128 v[86:89], v94 offset:1024
	ds_read_b128 v[90:93], v94 offset:2048
	ds_read_b128 v[94:97], v94 offset:3072
	s_add_u32 s10, s72, 0x40000
	s_addc_u32 s11, s73, 0
	s_mov_b32 m0, s3
	v_lshl_add_u64 v[240:241], s[10:11], 0, v[176:177]
	ds_read_b128 v[186:189], v199 offset:32768
	ds_read_b128 v[190:193], v199 offset:33792
	ds_read_b128 v[200:203], v199 offset:34816
	ds_read_b128 v[204:207], v199 offset:35840
	ds_read_b128 v[208:211], v199 offset:36864
	ds_read_b128 v[212:215], v199 offset:37888
	ds_read_b128 v[216:219], v199 offset:38912
	ds_read_b128 v[220:223], v199 offset:39936
	global_load_lds_dwordx4 v[240:241], off
	v_lshl_add_u64 v[240:241], s[10:11], 0, v[178:179]
	s_mov_b32 m0, s78
	s_nop 0
	global_load_lds_dwordx4 v[240:241], off
	s_waitcnt vmcnt(8)
	s_waitcnt lgkmcnt(0)
	s_setprio 1
	s_barrier
	v_mfma_f32_16x16x32_bf16 v[158:161], v[58:61], v[186:189], v[158:161]
	v_mfma_f32_16x16x32_bf16 v[154:157], v[74:77], v[186:189], v[154:157]
	v_mfma_f32_16x16x32_bf16 v[142:145], v[58:61], v[200:203], v[142:145]
	v_mfma_f32_16x16x32_bf16 v[138:141], v[74:77], v[200:203], v[138:141]
	v_mfma_f32_16x16x32_bf16 v[126:129], v[58:61], v[208:211], v[126:129]
	v_mfma_f32_16x16x32_bf16 v[122:125], v[74:77], v[208:211], v[122:125]
	v_mfma_f32_16x16x32_bf16 v[110:113], v[58:61], v[216:219], v[110:113]
	v_mfma_f32_16x16x32_bf16 v[106:109], v[74:77], v[216:219], v[106:109]
	v_mfma_f32_16x16x32_bf16 v[158:161], v[62:65], v[190:193], v[158:161]
	v_mfma_f32_16x16x32_bf16 v[154:157], v[78:81], v[190:193], v[154:157]
	v_mfma_f32_16x16x32_bf16 v[142:145], v[62:65], v[204:207], v[142:145]
	v_mfma_f32_16x16x32_bf16 v[138:141], v[78:81], v[204:207], v[138:141]
	v_mfma_f32_16x16x32_bf16 v[126:129], v[62:65], v[212:215], v[126:129]
	v_mfma_f32_16x16x32_bf16 v[122:125], v[78:81], v[212:215], v[122:125]
	v_mfma_f32_16x16x32_bf16 v[110:113], v[62:65], v[220:223], v[110:113]
	v_mfma_f32_16x16x32_bf16 v[106:109], v[78:81], v[220:223], v[106:109]
	v_mfma_f32_16x16x32_bf16 v[150:153], v[82:85], v[186:189], v[150:153]
	v_mfma_f32_16x16x32_bf16 v[146:149], v[90:93], v[186:189], v[146:149]
	v_mfma_f32_16x16x32_bf16 v[134:137], v[82:85], v[200:203], v[134:137]
	v_mfma_f32_16x16x32_bf16 v[130:133], v[90:93], v[200:203], v[130:133]
	v_mfma_f32_16x16x32_bf16 v[118:121], v[82:85], v[208:211], v[118:121]
	v_mfma_f32_16x16x32_bf16 v[114:117], v[90:93], v[208:211], v[114:117]
	v_mfma_f32_16x16x32_bf16 v[102:105], v[82:85], v[216:219], v[102:105]
	v_mfma_f32_16x16x32_bf16 v[98:101], v[90:93], v[216:219], v[98:101]
	v_mfma_f32_16x16x32_bf16 v[150:153], v[86:89], v[190:193], v[150:153]
	v_mfma_f32_16x16x32_bf16 v[146:149], v[94:97], v[190:193], v[146:149]
	v_mfma_f32_16x16x32_bf16 v[134:137], v[86:89], v[204:207], v[134:137]
	v_mfma_f32_16x16x32_bf16 v[130:133], v[94:97], v[204:207], v[130:133]
	v_mfma_f32_16x16x32_bf16 v[118:121], v[86:89], v[212:215], v[118:121]
	v_mfma_f32_16x16x32_bf16 v[114:117], v[94:97], v[212:215], v[114:117]
	v_mfma_f32_16x16x32_bf16 v[102:105], v[86:89], v[220:223], v[102:105]
	v_mfma_f32_16x16x32_bf16 v[98:101], v[94:97], v[220:223], v[98:101]
	s_barrier
; #define PG8_STAGE(bufoff, gbase, voff) do { _Pragma("unroll") for (int _i = 0; _i < 2; ++_i) \
;         __builtin_amdgcn_global_load_lds((const unsigned*)((const char*)(gbase) + (voff)[_i]), (PG8_LAS unsigned*)(lds + (bufoff) + ldsw + _i * 8192), 16, 0, 0); } while (0)
; #define PG8_LDA(dst, b, h) do { _Pragma("unroll") for (int m = 0; m < 4; ++m) _Pragma("unroll") for (int k = 0; k < 2; ++k) dst[m][k] = *(const PG8_LAS bf16x8*)(lds + PG8_SA(b, h) + aoff + m * 2048 + k * 1024); } while (0)
; #define PG8_MMA(ai, bj, At, Bt) do { __builtin_amdgcn_s_setprio(1); _Pragma("unroll") for (int m = 0; m < 4; ++m) _Pragma("unroll") for (int n = 0; n < 2; ++n) _Pragma("unroll") for (int k = 0; k < 2; ++k) \
;         acc[ai][bj][m][n] = __builtin_amdgcn_mfma_f32_16x16x32_bf16(Bt[n][k], At[m][k], acc[ai][bj][m][n], 0, 0, 0); __builtin_amdgcn_s_setprio(0); } while (0)
; #define PG8_WAIT_V(n) asm volatile("s_waitcnt vmcnt(" #n ")" ::: "memory")
; #define PG8_WAIT_L(n) asm volatile("s_waitcnt lgkmcnt(" #n ")" ::: "memory")
; #define PG8_BAR __builtin_amdgcn_s_barrier()
; #define PG8_SCHED __builtin_amdgcn_sched_barrier(0)
; template <class Epi, class Sched, bool ALIGN_EPI = false, bool SP2 = false>
; __device__ __forceinline__ void gemm_phase(PG8_LAS unsigned char* lds, const Gemm g, const Sched& S, const Epi& E) {
;     ...
;             PG8_LDA(At, 1, 1); PG8_STAGE(PG8_SB(1, 0), b3, voffB); PG8_STAGE(PG8_SB(1, 1), b3 + hstep, voffB); PG8_STAGE(PG8_SA(1, 0), a3, voffA);
;             PG8_WAIT_V(8); PG8_WAIT_L(0); PG8_BAR; PG8_MMA(1, 0, At, B0); PG8_MMA(1, 1, At, B1); PG8_BAR; PG8_SCHED;
;     ...
;         if constexpr (ALIGN_EPI) { if (wr == 0) PG8_BAR; }
	s_setprio 0
	s_add_i32 s10, s35, s76
	v_lshl_add_u64 v[194:195], v[194:195], 0, s[28:29]
	s_mov_b32 m0, s10
	ds_read_b128 v[186:189], v199 offset:49152
	ds_read_b128 v[190:193], v199 offset:50176
	ds_read_b128 v[200:203], v199 offset:51200
	ds_read_b128 v[204:207], v199 offset:52224
	ds_read_b128 v[208:211], v199 offset:53248
	ds_read_b128 v[212:215], v199 offset:54272
	ds_read_b128 v[216:219], v199 offset:55296
	ds_read_b128 v[220:223], v199 offset:56320
	global_load_lds_dwordx4 v[194:195], off
	s_add_i32 m0, s10, 0x2000
	s_add_u32 s10, s68, 0x40080
	v_lshl_add_u64 v[194:195], v[224:225], 0, s[28:29]
	s_addc_u32 s11, s69, 0
	s_add_i32 s35, s45, s76
	global_load_lds_dwordx4 v[194:195], off
	v_lshl_add_u64 v[194:195], s[10:11], 0, v[0:1]
	s_mov_b32 m0, s35
	s_nop 0
	global_load_lds_dwordx4 v[194:195], off
	v_lshl_add_u64 v[194:195], s[10:11], 0, v[180:181]
	s_add_i32 m0, s35, 0x2000
	s_nop 0
	global_load_lds_dwordx4 v[194:195], off
	v_lshl_add_u64 v[194:195], v[226:227], 0, s[28:29]
	s_mov_b32 m0, s94
	s_nop 0
	global_load_lds_dwordx4 v[194:195], off
	v_lshl_add_u64 v[194:195], v[238:239], 0, s[28:29]
	s_mov_b32 m0, s95
	s_nop 0
	global_load_lds_dwordx4 v[194:195], off
	s_waitcnt vmcnt(8)
	s_waitcnt lgkmcnt(0)
	s_setprio 1
	s_barrier
	v_mfma_f32_16x16x32_bf16 v[70:73], v[58:61], v[186:189], v[70:73]
	v_mfma_f32_16x16x32_bf16 v[66:69], v[74:77], v[186:189], v[66:69]
	v_mfma_f32_16x16x32_bf16 v[46:49], v[58:61], v[200:203], v[46:49]
	v_mfma_f32_16x16x32_bf16 v[42:45], v[74:77], v[200:203], v[42:45]
	v_mfma_f32_16x16x32_bf16 v[30:33], v[58:61], v[208:211], v[30:33]
	v_mfma_f32_16x16x32_bf16 v[26:29], v[74:77], v[208:211], v[26:29]
	v_mfma_f32_16x16x32_bf16 v[14:17], v[58:61], v[216:219], v[14:17]
	v_mfma_f32_16x16x32_bf16 v[10:13], v[74:77], v[216:219], v[10:13]
	v_mfma_f32_16x16x32_bf16 v[70:73], v[62:65], v[190:193], v[70:73]
	v_mfma_f32_16x16x32_bf16 v[66:69], v[78:81], v[190:193], v[66:69]
	v_mfma_f32_16x16x32_bf16 v[46:49], v[62:65], v[204:207], v[46:49]
	v_mfma_f32_16x16x32_bf16 v[42:45], v[78:81], v[204:207], v[42:45]
	v_mfma_f32_16x16x32_bf16 v[30:33], v[62:65], v[212:215], v[30:33]
	v_mfma_f32_16x16x32_bf16 v[26:29], v[78:81], v[212:215], v[26:29]
	v_mfma_f32_16x16x32_bf16 v[14:17], v[62:65], v[220:223], v[14:17]
	v_mfma_f32_16x16x32_bf16 v[10:13], v[78:81], v[220:223], v[10:13]
	v_mfma_f32_16x16x32_bf16 v[54:57], v[82:85], v[186:189], v[54:57]
	v_mfma_f32_16x16x32_bf16 v[50:53], v[90:93], v[186:189], v[50:53]
	v_mfma_f32_16x16x32_bf16 v[38:41], v[82:85], v[200:203], v[38:41]
	v_mfma_f32_16x16x32_bf16 v[34:37], v[90:93], v[200:203], v[34:37]
	v_mfma_f32_16x16x32_bf16 v[22:25], v[82:85], v[208:211], v[22:25]
	v_mfma_f32_16x16x32_bf16 v[18:21], v[90:93], v[208:211], v[18:21]
	v_mfma_f32_16x16x32_bf16 v[6:9], v[82:85], v[216:219], v[6:9]
	v_mfma_f32_16x16x32_bf16 v[2:5], v[90:93], v[216:219], v[2:5]
	v_mfma_f32_16x16x32_bf16 v[54:57], v[86:89], v[190:193], v[54:57]
	v_mfma_f32_16x16x32_bf16 v[50:53], v[94:97], v[190:193], v[50:53]
	v_mfma_f32_16x16x32_bf16 v[38:41], v[86:89], v[204:207], v[38:41]
	v_mfma_f32_16x16x32_bf16 v[34:37], v[94:97], v[204:207], v[34:37]
	v_mfma_f32_16x16x32_bf16 v[22:25], v[86:89], v[212:215], v[22:25]
	v_mfma_f32_16x16x32_bf16 v[18:21], v[94:97], v[212:215], v[18:21]
	v_mfma_f32_16x16x32_bf16 v[6:9], v[86:89], v[220:223], v[6:9]
	v_mfma_f32_16x16x32_bf16 v[2:5], v[94:97], v[220:223], v[2:5]
	s_barrier
	s_setprio 0
	s_add_i32 s34, s34, 2
	s_add_u32 s25, s25, 0x100
	s_addc_u32 s27, s27, 0
	s_add_u32 s42, s42, 0x100
	s_addc_u32 s43, s43, 0
	s_cmp_gt_u32 s34, 13
	s_cbranch_scc0 .LBB0_915
	s_and_b64 vcc, exec, s[20:21]
	s_cbranch_vccz .LBB0_918
	s_barrier

; #define PG8_STAGE(bufoff, gbase, voff) do { _Pragma("unroll") for (int _i = 0; _i < 2; ++_i) \
;         __builtin_amdgcn_global_load_lds((const unsigned*)((const char*)(gbase) + (voff)[_i]), (PG8_LAS unsigned*)(lds + (bufoff) + ldsw + _i * 8192), 16, 0, 0); } while (0)
; #define PG8_LDA(dst, b, h) do { _Pragma("unroll") for (int m = 0; m < 4; ++m) _Pragma("unroll") for (int k = 0; k < 2; ++k) dst[m][k] = *(const PG8_LAS bf16x8*)(lds + PG8_SA(b, h) + aoff + m * 2048 + k * 1024); } while (0)
; #define PG8_LDB(dst, b, h) do { _Pragma("unroll") for (int n = 0; n < 2; ++n) _Pragma("unroll") for (int k = 0; k < 2; ++k) dst[n][k] = *(const PG8_LAS bf16x8*)(lds + PG8_SB(b, h) + boff + n * 2048 + k * 1024); } while (0)
; #define PG8_MMA(ai, bj, At, Bt) do { __builtin_amdgcn_s_setprio(1); _Pragma("unroll") for (int m = 0; m < 4; ++m) _Pragma("unroll") for (int n = 0; n < 2; ++n) _Pragma("unroll") for (int k = 0; k < 2; ++k) \
;         acc[ai][bj][m][n] = __builtin_amdgcn_mfma_f32_16x16x32_bf16(Bt[n][k], At[m][k], acc[ai][bj][m][n], 0, 0, 0); __builtin_amdgcn_s_setprio(0); } while (0)
; #define PG8_WAIT_V(n) asm volatile("s_waitcnt vmcnt(" #n ")" ::: "memory")
; #define PG8_BAR __builtin_amdgcn_s_barrier()
; template <class Epi, class Sched, bool ALIGN_EPI = false, bool SP2 = false>
; __device__ __forceinline__ void gemm_phase(PG8_LAS unsigned char* lds, const Gemm g, const Sched& S, const Epi& E) {
;     ...
;         for (int t = 0; t < nt; t += 2) {
;             const bool last = (t == nt - 2);
;             const char* a1 = cA + (size_t)(t + 1) * kstep;
;             const char* a2 = last ? nA : cA + (size_t)(t + 2) * kstep; const char* b2 = last ? nB : cB + (size_t)(t + 2) * kstep;
;             const char* a3 = a2 + kstep; const char* b3 = b2 + kstep;
;             if (last && has_next) S.a_ready(nxt);
;             if constexpr (SP2) {
;             PG8_LDB(B0, 0, 0); PG8_LDB(B1, 0, 1); PG8_SCHED; PG8_LDA(At, 0, 0); PG8_STAGE(PG8_SA(1, 1), a1 + hstep, voffA);
;             PG8_WAIT_V(8); PG8_WAIT_L(0); PG8_BAR; PG8_MMA(0, 0, At, B0); PG8_MMA(0, 1, At, B1); PG8_BAR; PG8_SCHED;
;             PG8_LDA(At, 0, 1); PG8_STAGE(PG8_SB(0, 0), b2, voffB); PG8_STAGE(PG8_SB(0, 1), b2 + hstep, voffB); PG8_STAGE(PG8_SA(0, 0), a2, voffA);
;             PG8_WAIT_V(8); PG8_WAIT_L(0); PG8_BAR; PG8_MMA(1, 0, At, B0); PG8_MMA(1, 1, At, B1); PG8_BAR; PG8_SCHED;
.LBB0_1033:
	s_add_u32 s10, s50, 0xfffc0080
	s_addc_u32 s11, s51, -1
	s_add_i32 s69, 16, 0x10000
	s_cmp_eq_u32 s68, 12
	s_cselect_b32 s61, s34, s11
	s_cselect_b32 s60, s35, s10
	s_cselect_b32 s59, s27, s67
	s_cselect_b32 s58, s43, s66
	s_add_i32 s72, 16, 0x14000
	v_add_u32_e32 v142, s69, v177
	v_add_u32_e32 v188, s72, v177
	ds_read_b128 v[130:133], v142
	ds_read_b128 v[134:137], v142 offset:1024
	ds_read_b128 v[138:141], v142 offset:2048
	ds_read_b128 v[142:145], v142 offset:3072
	ds_read_b128 v[158:161], v188
	ds_read_b128 v[180:183], v188 offset:1024
	ds_read_b128 v[184:187], v188 offset:2048
	ds_read_b128 v[188:191], v188 offset:3072
	v_lshl_add_u64 v[224:225], s[50:51], 0, v[156:157]
	s_add_i32 m0, s9, 0xc000
	ds_read_b128 v[192:195], v179
	ds_read_b128 v[196:199], v179 offset:1024
	ds_read_b128 v[200:203], v179 offset:2048
	ds_read_b128 v[204:207], v179 offset:3072
	ds_read_b128 v[208:211], v179 offset:4096
	ds_read_b128 v[212:215], v179 offset:5120
	ds_read_b128 v[216:219], v179 offset:6144
	ds_read_b128 v[220:223], v179 offset:7168
	global_load_lds_dwordx4 v[224:225], off
	v_lshl_add_u64 v[224:225], s[50:51], 0, v[154:155]
	s_add_i32 m0, s9, 0xe000
	s_nop 0
	global_load_lds_dwordx4 v[224:225], off
	s_waitcnt vmcnt(8)
	s_waitcnt lgkmcnt(0)
	s_setprio 1
	s_barrier
	v_mfma_f32_16x16x32_bf16 v[126:129], v[130:133], v[192:195], v[126:129]
	v_mfma_f32_16x16x32_bf16 v[122:125], v[138:141], v[192:195], v[122:125]
	v_mfma_f32_16x16x32_bf16 v[110:113], v[130:133], v[200:203], v[110:113]
	v_mfma_f32_16x16x32_bf16 v[106:109], v[138:141], v[200:203], v[106:109]
	v_mfma_f32_16x16x32_bf16 v[94:97], v[130:133], v[208:211], v[94:97]
	v_mfma_f32_16x16x32_bf16 v[90:93], v[138:141], v[208:211], v[90:93]
	v_mfma_f32_16x16x32_bf16 v[78:81], v[130:133], v[216:219], v[78:81]
	v_mfma_f32_16x16x32_bf16 v[74:77], v[138:141], v[216:219], v[74:77]
	v_mfma_f32_16x16x32_bf16 v[126:129], v[134:137], v[196:199], v[126:129]
	v_mfma_f32_16x16x32_bf16 v[122:125], v[142:145], v[196:199], v[122:125]
	v_mfma_f32_16x16x32_bf16 v[110:113], v[134:137], v[204:207], v[110:113]
	v_mfma_f32_16x16x32_bf16 v[106:109], v[142:145], v[204:207], v[106:109]
	v_mfma_f32_16x16x32_bf16 v[94:97], v[134:137], v[212:215], v[94:97]
	v_mfma_f32_16x16x32_bf16 v[90:93], v[142:145], v[212:215], v[90:93]
	v_mfma_f32_16x16x32_bf16 v[78:81], v[134:137], v[220:223], v[78:81]
	v_mfma_f32_16x16x32_bf16 v[74:77], v[142:145], v[220:223], v[74:77]
	v_mfma_f32_16x16x32_bf16 v[118:121], v[158:161], v[192:195], v[118:121]
	v_mfma_f32_16x16x32_bf16 v[114:117], v[184:187], v[192:195], v[114:117]
	v_mfma_f32_16x16x32_bf16 v[102:105], v[158:161], v[200:203], v[102:105]
	v_mfma_f32_16x16x32_bf16 v[98:101], v[184:187], v[200:203], v[98:101]
	v_mfma_f32_16x16x32_bf16 v[86:89], v[158:161], v[208:211], v[86:89]
	v_mfma_f32_16x16x32_bf16 v[82:85], v[184:187], v[208:211], v[82:85]
	v_mfma_f32_16x16x32_bf16 v[70:73], v[158:161], v[216:219], v[70:73]
	v_mfma_f32_16x16x32_bf16 v[66:69], v[184:187], v[216:219], v[66:69]
	v_mfma_f32_16x16x32_bf16 v[118:121], v[180:183], v[196:199], v[118:121]
	v_mfma_f32_16x16x32_bf16 v[114:117], v[188:191], v[196:199], v[114:117]
	v_mfma_f32_16x16x32_bf16 v[102:105], v[180:183], v[204:207], v[102:105]
	v_mfma_f32_16x16x32_bf16 v[98:101], v[188:191], v[204:207], v[98:101]
	v_mfma_f32_16x16x32_bf16 v[86:89], v[180:183], v[212:215], v[86:89]
	v_mfma_f32_16x16x32_bf16 v[82:85], v[188:191], v[212:215], v[82:85]
	v_mfma_f32_16x16x32_bf16 v[70:73], v[180:183], v[220:223], v[70:73]
	v_mfma_f32_16x16x32_bf16 v[66:69], v[188:191], v[220:223], v[66:69]
	s_barrier
	s_setprio 0
	s_add_i32 s10, s69, s6
	v_lshl_add_u64 v[224:225], s[58:59], 0, v[0:1]
	s_mov_b32 m0, s10
	ds_read_b128 v[192:195], v179 offset:16384
	ds_read_b128 v[196:199], v179 offset:17408
	ds_read_b128 v[200:203], v179 offset:18432
	ds_read_b128 v[204:207], v179 offset:19456
	ds_read_b128 v[208:211], v179 offset:20480
	ds_read_b128 v[212:215], v179 offset:21504
	ds_read_b128 v[216:219], v179 offset:22528
	ds_read_b128 v[220:223], v179 offset:23552
	global_load_lds_dwordx4 v[224:225], off
	s_add_i32 m0, s10, 0x2000
	s_add_u32 s10, s58, 0x40000
	v_lshl_add_u64 v[226:227], s[58:59], 0, v[146:147]
	s_addc_u32 s11, s59, 0
	s_add_i32 s69, s72, s6
	global_load_lds_dwordx4 v[226:227], off
	v_lshl_add_u64 v[238:239], s[10:11], 0, v[0:1]
	s_mov_b32 m0, s69
	v_lshl_add_u64 v[240:241], s[60:61], 0, v[148:149]
	global_load_lds_dwordx4 v[238:239], off
	v_lshl_add_u64 v[238:239], s[10:11], 0, v[146:147]
	s_add_i32 m0, s69, 0x2000
	s_nop 0
	global_load_lds_dwordx4 v[238:239], off
	v_lshl_add_u64 v[238:239], s[60:61], 0, v[150:151]
	s_mov_b32 m0, s9
	s_nop 0
	global_load_lds_dwordx4 v[238:239], off
	s_mov_b32 m0, s54
	s_nop 0
	global_load_lds_dwordx4 v[240:241], off
	s_waitcnt vmcnt(8)
	s_waitcnt lgkmcnt(0)
	s_setprio 1
	s_barrier
; #define PG8_STAGE(bufoff, gbase, voff) do { _Pragma("unroll") for (int _i = 0; _i < 2; ++_i) \
;         __builtin_amdgcn_global_load_lds((const unsigned*)((const char*)(gbase) + (voff)[_i]), (PG8_LAS unsigned*)(lds + (bufoff) + ldsw + _i * 8192), 16, 0, 0); } while (0)
; #define PG8_LDA(dst, b, h) do { _Pragma("unroll") for (int m = 0; m < 4; ++m) _Pragma("unroll") for (int k = 0; k < 2; ++k) dst[m][k] = *(const PG8_LAS bf16x8*)(lds + PG8_SA(b, h) + aoff + m * 2048 + k * 1024); } while (0)
; #define PG8_LDB(dst, b, h) do { _Pragma("unroll") for (int n = 0; n < 2; ++n) _Pragma("unroll") for (int k = 0; k < 2; ++k) dst[n][k] = *(const PG8_LAS bf16x8*)(lds + PG8_SB(b, h) + boff + n * 2048 + k * 1024); } while (0)
; #define PG8_MMA(ai, bj, At, Bt) do { __builtin_amdgcn_s_setprio(1); _Pragma("unroll") for (int m = 0; m < 4; ++m) _Pragma("unroll") for (int n = 0; n < 2; ++n) _Pragma("unroll") for (int k = 0; k < 2; ++k) \
;         acc[ai][bj][m][n] = __builtin_amdgcn_mfma_f32_16x16x32_bf16(Bt[n][k], At[m][k], acc[ai][bj][m][n], 0, 0, 0); __builtin_amdgcn_s_setprio(0); } while (0)
; #define PG8_WAIT_V(n) asm volatile("s_waitcnt vmcnt(" #n ")" ::: "memory")
; #define PG8_WAIT_L(n) asm volatile("s_waitcnt lgkmcnt(" #n ")" ::: "memory")
; #define PG8_BAR __builtin_amdgcn_s_barrier()
; #define PG8_SCHED __builtin_amdgcn_sched_barrier(0)
; template <class Epi, class Sched, bool ALIGN_EPI = false, bool SP2 = false>
; __device__ __forceinline__ void gemm_phase(PG8_LAS unsigned char* lds, const Gemm g, const Sched& S, const Epi& E) {
;     ...
;             PG8_WAIT_V(8); PG8_WAIT_L(0); PG8_BAR; PG8_MMA(1, 0, At, B0); PG8_MMA(1, 1, At, B1); PG8_BAR; PG8_SCHED;
;             PG8_LDB(B0, 1, 0); PG8_LDB(B1, 1, 1); PG8_SCHED; PG8_LDA(At, 1, 0); PG8_STAGE(PG8_SA(0, 1), a2 + hstep, voffA);
;             PG8_WAIT_V(8); PG8_WAIT_L(0); PG8_BAR; PG8_MMA(0, 0, At, B0); PG8_MMA(0, 1, At, B1); PG8_BAR; PG8_SCHED;
	v_mfma_f32_16x16x32_bf16 v[62:65], v[130:133], v[192:195], v[62:65]
	v_mfma_f32_16x16x32_bf16 v[58:61], v[138:141], v[192:195], v[58:61]
	v_mfma_f32_16x16x32_bf16 v[46:49], v[130:133], v[200:203], v[46:49]
	v_mfma_f32_16x16x32_bf16 v[42:45], v[138:141], v[200:203], v[42:45]
	v_mfma_f32_16x16x32_bf16 v[30:33], v[130:133], v[208:211], v[30:33]
	v_mfma_f32_16x16x32_bf16 v[26:29], v[138:141], v[208:211], v[26:29]
	v_mfma_f32_16x16x32_bf16 v[14:17], v[130:133], v[216:219], v[14:17]
	v_mfma_f32_16x16x32_bf16 v[10:13], v[138:141], v[216:219], v[10:13]
	v_mfma_f32_16x16x32_bf16 v[62:65], v[134:137], v[196:199], v[62:65]
	v_mfma_f32_16x16x32_bf16 v[58:61], v[142:145], v[196:199], v[58:61]
	v_mfma_f32_16x16x32_bf16 v[46:49], v[134:137], v[204:207], v[46:49]
	v_mfma_f32_16x16x32_bf16 v[42:45], v[142:145], v[204:207], v[42:45]
	v_mfma_f32_16x16x32_bf16 v[30:33], v[134:137], v[212:215], v[30:33]
	v_mfma_f32_16x16x32_bf16 v[26:29], v[142:145], v[212:215], v[26:29]
	v_mfma_f32_16x16x32_bf16 v[14:17], v[134:137], v[220:223], v[14:17]
	v_mfma_f32_16x16x32_bf16 v[10:13], v[142:145], v[220:223], v[10:13]
	v_mfma_f32_16x16x32_bf16 v[54:57], v[158:161], v[192:195], v[54:57]
	v_mfma_f32_16x16x32_bf16 v[50:53], v[184:187], v[192:195], v[50:53]
	v_mfma_f32_16x16x32_bf16 v[38:41], v[158:161], v[200:203], v[38:41]
	v_mfma_f32_16x16x32_bf16 v[34:37], v[184:187], v[200:203], v[34:37]
	v_mfma_f32_16x16x32_bf16 v[22:25], v[158:161], v[208:211], v[22:25]
	v_mfma_f32_16x16x32_bf16 v[18:21], v[184:187], v[208:211], v[18:21]
	v_mfma_f32_16x16x32_bf16 v[6:9], v[158:161], v[216:219], v[6:9]
	v_mfma_f32_16x16x32_bf16 v[2:5], v[184:187], v[216:219], v[2:5]
	v_mfma_f32_16x16x32_bf16 v[54:57], v[180:183], v[196:199], v[54:57]
	v_mfma_f32_16x16x32_bf16 v[50:53], v[188:191], v[196:199], v[50:53]
	v_mfma_f32_16x16x32_bf16 v[38:41], v[180:183], v[204:207], v[38:41]
	v_mfma_f32_16x16x32_bf16 v[34:37], v[188:191], v[204:207], v[34:37]
	v_mfma_f32_16x16x32_bf16 v[22:25], v[180:183], v[212:215], v[22:25]
	v_mfma_f32_16x16x32_bf16 v[18:21], v[188:191], v[212:215], v[18:21]
	v_mfma_f32_16x16x32_bf16 v[6:9], v[180:183], v[220:223], v[6:9]
	v_mfma_f32_16x16x32_bf16 v[2:5], v[188:191], v[220:223], v[2:5]
	s_barrier
	s_setprio 0
	s_add_i32 s69, 16, 0x18000
	s_add_i32 s72, 16, 0x1c000
	v_add_u32_e32 v142, s69, v177
	v_add_u32_e32 v188, s72, v177
	ds_read_b128 v[130:133], v142
	ds_read_b128 v[134:137], v142 offset:1024
	ds_read_b128 v[138:141], v142 offset:2048
	ds_read_b128 v[142:145], v142 offset:3072
	ds_read_b128 v[158:161], v188
	ds_read_b128 v[180:183], v188 offset:1024
	ds_read_b128 v[184:187], v188 offset:2048
	ds_read_b128 v[188:191], v188 offset:3072
	s_add_u32 s10, s60, 0x40000
	s_addc_u32 s11, s61, 0
	s_mov_b32 m0, s55
	v_lshl_add_u64 v[242:243], s[10:11], 0, v[150:151]
	ds_read_b128 v[192:195], v179 offset:32768
	ds_read_b128 v[196:199], v179 offset:33792
	ds_read_b128 v[200:203], v179 offset:34816
	ds_read_b128 v[204:207], v179 offset:35840
	ds_read_b128 v[208:211], v179 offset:36864
	ds_read_b128 v[212:215], v179 offset:37888
	ds_read_b128 v[216:219], v179 offset:38912
	ds_read_b128 v[220:223], v179 offset:39936
	global_load_lds_dwordx4 v[242:243], off
	v_lshl_add_u64 v[242:243], s[10:11], 0, v[148:149]
	s_mov_b32 m0, s56
	s_nop 0
	global_load_lds_dwordx4 v[242:243], off
	s_waitcnt vmcnt(8)
	s_waitcnt lgkmcnt(0)
	s_setprio 1
	s_barrier
	v_mfma_f32_16x16x32_bf16 v[126:129], v[130:133], v[192:195], v[126:129]
	v_mfma_f32_16x16x32_bf16 v[122:125], v[138:141], v[192:195], v[122:125]
	v_mfma_f32_16x16x32_bf16 v[110:113], v[130:133], v[200:203], v[110:113]
	v_mfma_f32_16x16x32_bf16 v[106:109], v[138:141], v[200:203], v[106:109]
	v_mfma_f32_16x16x32_bf16 v[94:97], v[130:133], v[208:211], v[94:97]
	v_mfma_f32_16x16x32_bf16 v[90:93], v[138:141], v[208:211], v[90:93]
	v_mfma_f32_16x16x32_bf16 v[78:81], v[130:133], v[216:219], v[78:81]
	v_mfma_f32_16x16x32_bf16 v[74:77], v[138:141], v[216:219], v[74:77]
	v_mfma_f32_16x16x32_bf16 v[126:129], v[134:137], v[196:199], v[126:129]
	v_mfma_f32_16x16x32_bf16 v[122:125], v[142:145], v[196:199], v[122:125]
	v_mfma_f32_16x16x32_bf16 v[110:113], v[134:137], v[204:207], v[110:113]
	v_mfma_f32_16x16x32_bf16 v[106:109], v[142:145], v[204:207], v[106:109]
	v_mfma_f32_16x16x32_bf16 v[94:97], v[134:137], v[212:215], v[94:97]
	v_mfma_f32_16x16x32_bf16 v[90:93], v[142:145], v[212:215], v[90:93]
	v_mfma_f32_16x16x32_bf16 v[78:81], v[134:137], v[220:223], v[78:81]
	v_mfma_f32_16x16x32_bf16 v[74:77], v[142:145], v[220:223], v[74:77]
	v_mfma_f32_16x16x32_bf16 v[118:121], v[158:161], v[192:195], v[118:121]
	v_mfma_f32_16x16x32_bf16 v[114:117], v[184:187], v[192:195], v[114:117]
	v_mfma_f32_16x16x32_bf16 v[102:105], v[158:161], v[200:203], v[102:105]
	v_mfma_f32_16x16x32_bf16 v[98:101], v[184:187], v[200:203], v[98:101]
	v_mfma_f32_16x16x32_bf16 v[86:89], v[158:161], v[208:211], v[86:89]
	v_mfma_f32_16x16x32_bf16 v[82:85], v[184:187], v[208:211], v[82:85]
	v_mfma_f32_16x16x32_bf16 v[70:73], v[158:161], v[216:219], v[70:73]
	v_mfma_f32_16x16x32_bf16 v[66:69], v[184:187], v[216:219], v[66:69]
	v_mfma_f32_16x16x32_bf16 v[118:121], v[180:183], v[196:199], v[118:121]
	v_mfma_f32_16x16x32_bf16 v[114:117], v[188:191], v[196:199], v[114:117]
	v_mfma_f32_16x16x32_bf16 v[102:105], v[180:183], v[204:207], v[102:105]
	v_mfma_f32_16x16x32_bf16 v[98:101], v[188:191], v[204:207], v[98:101]
	v_mfma_f32_16x16x32_bf16 v[86:89], v[180:183], v[212:215], v[86:89]
	v_mfma_f32_16x16x32_bf16 v[82:85], v[188:191], v[212:215], v[82:85]
	v_mfma_f32_16x16x32_bf16 v[70:73], v[180:183], v[220:223], v[70:73]
	v_mfma_f32_16x16x32_bf16 v[66:69], v[188:191], v[220:223], v[66:69]
	s_barrier
; #define PG8_STAGE(bufoff, gbase, voff) do { _Pragma("unroll") for (int _i = 0; _i < 2; ++_i) \
;         __builtin_amdgcn_global_load_lds((const unsigned*)((const char*)(gbase) + (voff)[_i]), (PG8_LAS unsigned*)(lds + (bufoff) + ldsw + _i * 8192), 16, 0, 0); } while (0)
; #define PG8_LDA(dst, b, h) do { _Pragma("unroll") for (int m = 0; m < 4; ++m) _Pragma("unroll") for (int k = 0; k < 2; ++k) dst[m][k] = *(const PG8_LAS bf16x8*)(lds + PG8_SA(b, h) + aoff + m * 2048 + k * 1024); } while (0)
; #define PG8_MMA(ai, bj, At, Bt) do { __builtin_amdgcn_s_setprio(1); _Pragma("unroll") for (int m = 0; m < 4; ++m) _Pragma("unroll") for (int n = 0; n < 2; ++n) _Pragma("unroll") for (int k = 0; k < 2; ++k) \
;         acc[ai][bj][m][n] = __builtin_amdgcn_mfma_f32_16x16x32_bf16(Bt[n][k], At[m][k], acc[ai][bj][m][n], 0, 0, 0); __builtin_amdgcn_s_setprio(0); } while (0)
; #define PG8_WAIT_V(n) asm volatile("s_waitcnt vmcnt(" #n ")" ::: "memory")
; #define PG8_WAIT_L(n) asm volatile("s_waitcnt lgkmcnt(" #n ")" ::: "memory")
; #define PG8_BAR __builtin_amdgcn_s_barrier()
; #define PG8_SCHED __builtin_amdgcn_sched_barrier(0)
; template <class Epi, class Sched, bool ALIGN_EPI = false, bool SP2 = false>
; __device__ __forceinline__ void gemm_phase(PG8_LAS unsigned char* lds, const Gemm g, const Sched& S, const Epi& E) {
;     ...
;             PG8_LDA(At, 1, 1); PG8_STAGE(PG8_SB(1, 0), b3, voffB); PG8_STAGE(PG8_SB(1, 1), b3 + hstep, voffB); PG8_STAGE(PG8_SA(1, 0), a3, voffA);
;             PG8_WAIT_V(8); PG8_WAIT_L(0); PG8_BAR; PG8_MMA(1, 0, At, B0); PG8_MMA(1, 1, At, B1); PG8_BAR; PG8_SCHED;
;     ...
;         if constexpr (ALIGN_EPI) { if (wr == 0) PG8_BAR; }
	s_setprio 0
	s_add_i32 s10, s69, s6
	v_lshl_add_u64 v[224:225], v[224:225], 0, s[28:29]
	s_mov_b32 m0, s10
	ds_read_b128 v[192:195], v179 offset:49152
	ds_read_b128 v[196:199], v179 offset:50176
	ds_read_b128 v[200:203], v179 offset:51200
	ds_read_b128 v[204:207], v179 offset:52224
	ds_read_b128 v[208:211], v179 offset:53248
	ds_read_b128 v[212:215], v179 offset:54272
	ds_read_b128 v[216:219], v179 offset:55296
	ds_read_b128 v[220:223], v179 offset:56320
	global_load_lds_dwordx4 v[224:225], off
	s_add_i32 m0, s10, 0x2000
	s_add_u32 s10, s58, 0x40080
	v_lshl_add_u64 v[224:225], v[226:227], 0, s[28:29]
	s_addc_u32 s11, s59, 0
	s_add_i32 s58, s72, s6
	global_load_lds_dwordx4 v[224:225], off
	v_lshl_add_u64 v[224:225], s[10:11], 0, v[0:1]
	s_mov_b32 m0, s58
	s_nop 0
	global_load_lds_dwordx4 v[224:225], off
	v_lshl_add_u64 v[224:225], s[10:11], 0, v[146:147]
	s_add_i32 m0, s58, 0x2000
	s_nop 0
	global_load_lds_dwordx4 v[224:225], off
	v_lshl_add_u64 v[224:225], v[238:239], 0, s[28:29]
	s_mov_b32 m0, s63
	s_nop 0
	global_load_lds_dwordx4 v[224:225], off
	v_lshl_add_u64 v[224:225], v[240:241], 0, s[28:29]
	s_mov_b32 m0, s64
	s_nop 0
	global_load_lds_dwordx4 v[224:225], off
	s_waitcnt vmcnt(8)
	s_waitcnt lgkmcnt(0)
	s_setprio 1
	s_barrier
	v_mfma_f32_16x16x32_bf16 v[62:65], v[130:133], v[192:195], v[62:65]
	v_mfma_f32_16x16x32_bf16 v[58:61], v[138:141], v[192:195], v[58:61]
	v_mfma_f32_16x16x32_bf16 v[46:49], v[130:133], v[200:203], v[46:49]
	v_mfma_f32_16x16x32_bf16 v[42:45], v[138:141], v[200:203], v[42:45]
	v_mfma_f32_16x16x32_bf16 v[30:33], v[130:133], v[208:211], v[30:33]
	v_mfma_f32_16x16x32_bf16 v[26:29], v[138:141], v[208:211], v[26:29]
	v_mfma_f32_16x16x32_bf16 v[14:17], v[130:133], v[216:219], v[14:17]
	v_mfma_f32_16x16x32_bf16 v[10:13], v[138:141], v[216:219], v[10:13]
	v_mfma_f32_16x16x32_bf16 v[62:65], v[134:137], v[196:199], v[62:65]
	v_mfma_f32_16x16x32_bf16 v[58:61], v[142:145], v[196:199], v[58:61]
	v_mfma_f32_16x16x32_bf16 v[46:49], v[134:137], v[204:207], v[46:49]
	v_mfma_f32_16x16x32_bf16 v[42:45], v[142:145], v[204:207], v[42:45]
	v_mfma_f32_16x16x32_bf16 v[30:33], v[134:137], v[212:215], v[30:33]
	v_mfma_f32_16x16x32_bf16 v[26:29], v[142:145], v[212:215], v[26:29]
	v_mfma_f32_16x16x32_bf16 v[14:17], v[134:137], v[220:223], v[14:17]
	v_mfma_f32_16x16x32_bf16 v[10:13], v[142:145], v[220:223], v[10:13]
	v_mfma_f32_16x16x32_bf16 v[54:57], v[158:161], v[192:195], v[54:57]
	v_mfma_f32_16x16x32_bf16 v[50:53], v[184:187], v[192:195], v[50:53]
	v_mfma_f32_16x16x32_bf16 v[38:41], v[158:161], v[200:203], v[38:41]
	v_mfma_f32_16x16x32_bf16 v[34:37], v[184:187], v[200:203], v[34:37]
	v_mfma_f32_16x16x32_bf16 v[22:25], v[158:161], v[208:211], v[22:25]
	v_mfma_f32_16x16x32_bf16 v[18:21], v[184:187], v[208:211], v[18:21]
	v_mfma_f32_16x16x32_bf16 v[6:9], v[158:161], v[216:219], v[6:9]
	v_mfma_f32_16x16x32_bf16 v[2:5], v[184:187], v[216:219], v[2:5]
	v_mfma_f32_16x16x32_bf16 v[54:57], v[180:183], v[196:199], v[54:57]
	v_mfma_f32_16x16x32_bf16 v[50:53], v[188:191], v[196:199], v[50:53]
	v_mfma_f32_16x16x32_bf16 v[38:41], v[180:183], v[204:207], v[38:41]
	v_mfma_f32_16x16x32_bf16 v[34:37], v[188:191], v[204:207], v[34:37]
	v_mfma_f32_16x16x32_bf16 v[22:25], v[180:183], v[212:215], v[22:25]
	v_mfma_f32_16x16x32_bf16 v[18:21], v[188:191], v[212:215], v[18:21]
	v_mfma_f32_16x16x32_bf16 v[6:9], v[180:183], v[220:223], v[6:9]
	v_mfma_f32_16x16x32_bf16 v[2:5], v[188:191], v[220:223], v[2:5]
	s_barrier
	s_setprio 0
	s_add_i32 s68, s68, 2
	s_add_u32 s66, s66, 0x100
	s_addc_u32 s67, s67, 0
	s_add_u32 s50, s50, 0x100
	s_addc_u32 s51, s51, 0
	s_cmp_gt_u32 s68, 13
	s_cbranch_scc0 .LBB0_1033
	s_and_b64 vcc, exec, s[24:25]
	s_cbranch_vccz .LBB0_1036
	s_barrier

; #define PG8_STAGE(bufoff, gbase, voff) do { _Pragma("unroll") for (int _i = 0; _i < 2; ++_i) \
;         __builtin_amdgcn_global_load_lds((const unsigned*)((const char*)(gbase) + (voff)[_i]), (PG8_LAS unsigned*)(lds + (bufoff) + ldsw + _i * 8192), 16, 0, 0); } while (0)
; #define PG8_LDA(dst, b, h) do { _Pragma("unroll") for (int m = 0; m < 4; ++m) _Pragma("unroll") for (int k = 0; k < 2; ++k) dst[m][k] = *(const PG8_LAS bf16x8*)(lds + PG8_SA(b, h) + aoff + m * 2048 + k * 1024); } while (0)
; #define PG8_LDB(dst, b, h) do { _Pragma("unroll") for (int n = 0; n < 2; ++n) _Pragma("unroll") for (int k = 0; k < 2; ++k) dst[n][k] = *(const PG8_LAS bf16x8*)(lds + PG8_SB(b, h) + boff + n * 2048 + k * 1024); } while (0)
; #define PG8_MMA(ai, bj, At, Bt) do { __builtin_amdgcn_s_setprio(1); _Pragma("unroll") for (int m = 0; m < 4; ++m) _Pragma("unroll") for (int n = 0; n < 2; ++n) _Pragma("unroll") for (int k = 0; k < 2; ++k) \
;         acc[ai][bj][m][n] = __builtin_amdgcn_mfma_f32_16x16x32_bf16(Bt[n][k], At[m][k], acc[ai][bj][m][n], 0, 0, 0); __builtin_amdgcn_s_setprio(0); } while (0)
; #define PG8_WAIT_V(n) asm volatile("s_waitcnt vmcnt(" #n ")" ::: "memory")
; #define PG8_BAR __builtin_amdgcn_s_barrier()
; template <class Epi, class Sched, bool ALIGN_EPI = false, bool SP2 = false>
; __device__ __forceinline__ void gemm_phase(PG8_LAS unsigned char* lds, const Gemm g, const Sched& S, const Epi& E) {
;     ...
;         for (int t = 0; t < nt; t += 2) {
;             const bool last = (t == nt - 2);
;             const char* a1 = cA + (size_t)(t + 1) * kstep;
;             const char* a2 = last ? nA : cA + (size_t)(t + 2) * kstep; const char* b2 = last ? nB : cB + (size_t)(t + 2) * kstep;
;             const char* a3 = a2 + kstep; const char* b3 = b2 + kstep;
;             if (last && has_next) S.a_ready(nxt);
;             if constexpr (SP2) {
;             PG8_LDB(B0, 0, 0); PG8_LDB(B1, 0, 1); PG8_SCHED; PG8_LDA(At, 0, 0); PG8_STAGE(PG8_SA(1, 1), a1 + hstep, voffA);
;             PG8_WAIT_V(8); PG8_WAIT_L(0); PG8_BAR; PG8_MMA(0, 0, At, B0); PG8_MMA(0, 1, At, B1); PG8_BAR; PG8_SCHED;
;             PG8_LDA(At, 0, 1); PG8_STAGE(PG8_SB(0, 0), b2, voffB); PG8_STAGE(PG8_SB(0, 1), b2 + hstep, voffB); PG8_STAGE(PG8_SA(0, 0), a2, voffA);
;             PG8_WAIT_V(8); PG8_WAIT_L(0); PG8_BAR; PG8_MMA(1, 0, At, B0); PG8_MMA(1, 1, At, B1); PG8_BAR; PG8_SCHED;
.LBB0_1208:
	s_add_u32 s42, s24, 0x100
	s_addc_u32 s43, s25, 0
	s_add_i32 s10, 16, 0x10000
	s_cmp_eq_u32 s73, 40
	s_cselect_b32 s69, s23, s43
	s_cselect_b32 s68, s22, s42
	s_cselect_b32 s45, s27, s72
	s_cselect_b32 s44, s26, s35
	s_add_i32 vcc_lo, 16, 0x14000
	v_add_u32_e32 v78, s10, v197
	v_add_u32_e32 v94, vcc_lo, v197
	ds_read_b128 v[58:61], v78
	ds_read_b128 v[62:65], v78 offset:1024
	ds_read_b128 v[74:77], v78 offset:2048
	ds_read_b128 v[78:81], v78 offset:3072
	ds_read_b128 v[82:85], v94
	ds_read_b128 v[86:89], v94 offset:1024
	ds_read_b128 v[90:93], v94 offset:2048
	ds_read_b128 v[94:97], v94 offset:3072
	v_lshl_add_u64 v[194:195], s[24:25], 0, v[184:185]
	s_add_i32 m0, s95, 0xc000
	ds_read_b128 v[186:189], v199
	ds_read_b128 v[190:193], v199 offset:1024
	ds_read_b128 v[200:203], v199 offset:2048
	ds_read_b128 v[204:207], v199 offset:3072
	ds_read_b128 v[208:211], v199 offset:4096
	ds_read_b128 v[212:215], v199 offset:5120
	ds_read_b128 v[216:219], v199 offset:6144
	ds_read_b128 v[220:223], v199 offset:7168
	global_load_lds_dwordx4 v[194:195], off
	v_lshl_add_u64 v[194:195], s[24:25], 0, v[182:183]
	s_add_i32 m0, s95, 0xe000
	s_nop 0
	global_load_lds_dwordx4 v[194:195], off
	s_waitcnt vmcnt(8)
	s_waitcnt lgkmcnt(0)
	s_setprio 1
	s_barrier
	v_mfma_f32_16x16x32_bf16 v[158:161], v[58:61], v[186:189], v[158:161]
	v_mfma_f32_16x16x32_bf16 v[154:157], v[74:77], v[186:189], v[154:157]
	v_mfma_f32_16x16x32_bf16 v[142:145], v[58:61], v[200:203], v[142:145]
	v_mfma_f32_16x16x32_bf16 v[138:141], v[74:77], v[200:203], v[138:141]
	v_mfma_f32_16x16x32_bf16 v[126:129], v[58:61], v[208:211], v[126:129]
	v_mfma_f32_16x16x32_bf16 v[122:125], v[74:77], v[208:211], v[122:125]
	v_mfma_f32_16x16x32_bf16 v[110:113], v[58:61], v[216:219], v[110:113]
	v_mfma_f32_16x16x32_bf16 v[106:109], v[74:77], v[216:219], v[106:109]
	v_mfma_f32_16x16x32_bf16 v[158:161], v[62:65], v[190:193], v[158:161]
	v_mfma_f32_16x16x32_bf16 v[154:157], v[78:81], v[190:193], v[154:157]
	v_mfma_f32_16x16x32_bf16 v[142:145], v[62:65], v[204:207], v[142:145]
	v_mfma_f32_16x16x32_bf16 v[138:141], v[78:81], v[204:207], v[138:141]
	v_mfma_f32_16x16x32_bf16 v[126:129], v[62:65], v[212:215], v[126:129]
	v_mfma_f32_16x16x32_bf16 v[122:125], v[78:81], v[212:215], v[122:125]
	v_mfma_f32_16x16x32_bf16 v[110:113], v[62:65], v[220:223], v[110:113]
	v_mfma_f32_16x16x32_bf16 v[106:109], v[78:81], v[220:223], v[106:109]
	v_mfma_f32_16x16x32_bf16 v[150:153], v[82:85], v[186:189], v[150:153]
	v_mfma_f32_16x16x32_bf16 v[146:149], v[90:93], v[186:189], v[146:149]
	v_mfma_f32_16x16x32_bf16 v[134:137], v[82:85], v[200:203], v[134:137]
	v_mfma_f32_16x16x32_bf16 v[130:133], v[90:93], v[200:203], v[130:133]
	v_mfma_f32_16x16x32_bf16 v[118:121], v[82:85], v[208:211], v[118:121]
	v_mfma_f32_16x16x32_bf16 v[114:117], v[90:93], v[208:211], v[114:117]
	v_mfma_f32_16x16x32_bf16 v[102:105], v[82:85], v[216:219], v[102:105]
	v_mfma_f32_16x16x32_bf16 v[98:101], v[90:93], v[216:219], v[98:101]
	v_mfma_f32_16x16x32_bf16 v[150:153], v[86:89], v[190:193], v[150:153]
	v_mfma_f32_16x16x32_bf16 v[146:149], v[94:97], v[190:193], v[146:149]
	v_mfma_f32_16x16x32_bf16 v[134:137], v[86:89], v[204:207], v[134:137]
	v_mfma_f32_16x16x32_bf16 v[130:133], v[94:97], v[204:207], v[130:133]
	v_mfma_f32_16x16x32_bf16 v[118:121], v[86:89], v[212:215], v[118:121]
	v_mfma_f32_16x16x32_bf16 v[114:117], v[94:97], v[212:215], v[114:117]
	v_mfma_f32_16x16x32_bf16 v[102:105], v[86:89], v[220:223], v[102:105]
	v_mfma_f32_16x16x32_bf16 v[98:101], v[94:97], v[220:223], v[98:101]
	s_barrier
	s_setprio 0
	s_add_i32 s10, s10, s94
	v_lshl_add_u64 v[194:195], s[44:45], 0, v[0:1]
	s_mov_b32 m0, s10
	ds_read_b128 v[186:189], v199 offset:16384
	ds_read_b128 v[190:193], v199 offset:17408
	ds_read_b128 v[200:203], v199 offset:18432
	ds_read_b128 v[204:207], v199 offset:19456
	ds_read_b128 v[208:211], v199 offset:20480
	ds_read_b128 v[212:215], v199 offset:21504
	ds_read_b128 v[216:219], v199 offset:22528
	ds_read_b128 v[220:223], v199 offset:23552
	global_load_lds_dwordx4 v[194:195], off
	s_add_i32 m0, s10, 0x2000
	s_add_u32 s10, s44, 0xb0000
	v_lshl_add_u64 v[224:225], s[44:45], 0, v[180:181]
	s_addc_u32 s11, s45, 0
	s_add_i32 s24, vcc_lo, s94
	global_load_lds_dwordx4 v[224:225], off
	v_lshl_add_u64 v[226:227], s[10:11], 0, v[0:1]
	s_mov_b32 m0, s24
	v_lshl_add_u64 v[238:239], s[68:69], 0, v[178:179]
	global_load_lds_dwordx4 v[226:227], off
	v_lshl_add_u64 v[226:227], s[10:11], 0, v[180:181]
	s_add_i32 m0, s24, 0x2000
	s_nop 0
	global_load_lds_dwordx4 v[226:227], off
	v_lshl_add_u64 v[226:227], s[68:69], 0, v[176:177]
	s_mov_b32 m0, s95
	s_nop 0
	global_load_lds_dwordx4 v[226:227], off
	s_mov_b32 m0, s2
	s_nop 0
	global_load_lds_dwordx4 v[238:239], off
	s_waitcnt vmcnt(8)
	s_waitcnt lgkmcnt(0)
	s_setprio 1
	s_barrier
; #define PG8_STAGE(bufoff, gbase, voff) do { _Pragma("unroll") for (int _i = 0; _i < 2; ++_i) \
;         __builtin_amdgcn_global_load_lds((const unsigned*)((const char*)(gbase) + (voff)[_i]), (PG8_LAS unsigned*)(lds + (bufoff) + ldsw + _i * 8192), 16, 0, 0); } while (0)
; #define PG8_LDA(dst, b, h) do { _Pragma("unroll") for (int m = 0; m < 4; ++m) _Pragma("unroll") for (int k = 0; k < 2; ++k) dst[m][k] = *(const PG8_LAS bf16x8*)(lds + PG8_SA(b, h) + aoff + m * 2048 + k * 1024); } while (0)
; #define PG8_LDB(dst, b, h) do { _Pragma("unroll") for (int n = 0; n < 2; ++n) _Pragma("unroll") for (int k = 0; k < 2; ++k) dst[n][k] = *(const PG8_LAS bf16x8*)(lds + PG8_SB(b, h) + boff + n * 2048 + k * 1024); } while (0)
; #define PG8_MMA(ai, bj, At, Bt) do { __builtin_amdgcn_s_setprio(1); _Pragma("unroll") for (int m = 0; m < 4; ++m) _Pragma("unroll") for (int n = 0; n < 2; ++n) _Pragma("unroll") for (int k = 0; k < 2; ++k) \
;         acc[ai][bj][m][n] = __builtin_amdgcn_mfma_f32_16x16x32_bf16(Bt[n][k], At[m][k], acc[ai][bj][m][n], 0, 0, 0); __builtin_amdgcn_s_setprio(0); } while (0)
; #define PG8_WAIT_V(n) asm volatile("s_waitcnt vmcnt(" #n ")" ::: "memory")
; #define PG8_WAIT_L(n) asm volatile("s_waitcnt lgkmcnt(" #n ")" ::: "memory")
; #define PG8_BAR __builtin_amdgcn_s_barrier()
; #define PG8_SCHED __builtin_amdgcn_sched_barrier(0)
; template <class Epi, class Sched, bool ALIGN_EPI = false, bool SP2 = false>
; __device__ __forceinline__ void gemm_phase(PG8_LAS unsigned char* lds, const Gemm g, const Sched& S, const Epi& E) {
;     ...
;             PG8_WAIT_V(8); PG8_WAIT_L(0); PG8_BAR; PG8_MMA(1, 0, At, B0); PG8_MMA(1, 1, At, B1); PG8_BAR; PG8_SCHED;
;             PG8_LDB(B0, 1, 0); PG8_LDB(B1, 1, 1); PG8_SCHED; PG8_LDA(At, 1, 0); PG8_STAGE(PG8_SA(0, 1), a2 + hstep, voffA);
;             PG8_WAIT_V(8); PG8_WAIT_L(0); PG8_BAR; PG8_MMA(0, 0, At, B0); PG8_MMA(0, 1, At, B1); PG8_BAR; PG8_SCHED;
	v_mfma_f32_16x16x32_bf16 v[70:73], v[58:61], v[186:189], v[70:73]
	v_mfma_f32_16x16x32_bf16 v[66:69], v[74:77], v[186:189], v[66:69]
	v_mfma_f32_16x16x32_bf16 v[46:49], v[58:61], v[200:203], v[46:49]
	v_mfma_f32_16x16x32_bf16 v[42:45], v[74:77], v[200:203], v[42:45]
	v_mfma_f32_16x16x32_bf16 v[30:33], v[58:61], v[208:211], v[30:33]
	v_mfma_f32_16x16x32_bf16 v[26:29], v[74:77], v[208:211], v[26:29]
	v_mfma_f32_16x16x32_bf16 v[14:17], v[58:61], v[216:219], v[14:17]
	v_mfma_f32_16x16x32_bf16 v[10:13], v[74:77], v[216:219], v[10:13]
	v_mfma_f32_16x16x32_bf16 v[70:73], v[62:65], v[190:193], v[70:73]
	v_mfma_f32_16x16x32_bf16 v[66:69], v[78:81], v[190:193], v[66:69]
	v_mfma_f32_16x16x32_bf16 v[46:49], v[62:65], v[204:207], v[46:49]
	v_mfma_f32_16x16x32_bf16 v[42:45], v[78:81], v[204:207], v[42:45]
	v_mfma_f32_16x16x32_bf16 v[30:33], v[62:65], v[212:215], v[30:33]
	v_mfma_f32_16x16x32_bf16 v[26:29], v[78:81], v[212:215], v[26:29]
	v_mfma_f32_16x16x32_bf16 v[14:17], v[62:65], v[220:223], v[14:17]
	v_mfma_f32_16x16x32_bf16 v[10:13], v[78:81], v[220:223], v[10:13]
	v_mfma_f32_16x16x32_bf16 v[54:57], v[82:85], v[186:189], v[54:57]
	v_mfma_f32_16x16x32_bf16 v[50:53], v[90:93], v[186:189], v[50:53]
	v_mfma_f32_16x16x32_bf16 v[38:41], v[82:85], v[200:203], v[38:41]
	v_mfma_f32_16x16x32_bf16 v[34:37], v[90:93], v[200:203], v[34:37]
	v_mfma_f32_16x16x32_bf16 v[22:25], v[82:85], v[208:211], v[22:25]
	v_mfma_f32_16x16x32_bf16 v[18:21], v[90:93], v[208:211], v[18:21]
	v_mfma_f32_16x16x32_bf16 v[6:9], v[82:85], v[216:219], v[6:9]
	v_mfma_f32_16x16x32_bf16 v[2:5], v[90:93], v[216:219], v[2:5]
	v_mfma_f32_16x16x32_bf16 v[54:57], v[86:89], v[190:193], v[54:57]
	v_mfma_f32_16x16x32_bf16 v[50:53], v[94:97], v[190:193], v[50:53]
	v_mfma_f32_16x16x32_bf16 v[38:41], v[86:89], v[204:207], v[38:41]
	v_mfma_f32_16x16x32_bf16 v[34:37], v[94:97], v[204:207], v[34:37]
	v_mfma_f32_16x16x32_bf16 v[22:25], v[86:89], v[212:215], v[22:25]
	v_mfma_f32_16x16x32_bf16 v[18:21], v[94:97], v[212:215], v[18:21]
	v_mfma_f32_16x16x32_bf16 v[6:9], v[86:89], v[220:223], v[6:9]
	v_mfma_f32_16x16x32_bf16 v[2:5], v[94:97], v[220:223], v[2:5]
	s_barrier
	s_setprio 0
	s_add_i32 s24, 16, 0x18000
	s_add_i32 s25, 16, 0x1c000
	v_add_u32_e32 v78, s24, v197
	v_add_u32_e32 v94, s25, v197
	ds_read_b128 v[58:61], v78
	ds_read_b128 v[62:65], v78 offset:1024
	ds_read_b128 v[74:77], v78 offset:2048
	ds_read_b128 v[78:81], v78 offset:3072
	ds_read_b128 v[82:85], v94
	ds_read_b128 v[86:89], v94 offset:1024
	ds_read_b128 v[90:93], v94 offset:2048
	ds_read_b128 v[94:97], v94 offset:3072
	s_add_u32 s10, s68, 0xb0000
	s_addc_u32 s11, s69, 0
	s_mov_b32 m0, s3
	v_lshl_add_u64 v[240:241], s[10:11], 0, v[176:177]
	ds_read_b128 v[186:189], v199 offset:32768
	ds_read_b128 v[190:193], v199 offset:33792
	ds_read_b128 v[200:203], v199 offset:34816
	ds_read_b128 v[204:207], v199 offset:35840
	ds_read_b128 v[208:211], v199 offset:36864
	ds_read_b128 v[212:215], v199 offset:37888
	ds_read_b128 v[216:219], v199 offset:38912
	ds_read_b128 v[220:223], v199 offset:39936
	global_load_lds_dwordx4 v[240:241], off
	v_lshl_add_u64 v[240:241], s[10:11], 0, v[178:179]
	s_mov_b32 m0, s96
	s_nop 0
	global_load_lds_dwordx4 v[240:241], off
	s_waitcnt vmcnt(8)
	s_waitcnt lgkmcnt(0)
	s_setprio 1
	s_barrier
	v_mfma_f32_16x16x32_bf16 v[158:161], v[58:61], v[186:189], v[158:161]
	v_mfma_f32_16x16x32_bf16 v[154:157], v[74:77], v[186:189], v[154:157]
	v_mfma_f32_16x16x32_bf16 v[142:145], v[58:61], v[200:203], v[142:145]
	v_mfma_f32_16x16x32_bf16 v[138:141], v[74:77], v[200:203], v[138:141]
	v_mfma_f32_16x16x32_bf16 v[126:129], v[58:61], v[208:211], v[126:129]
	v_mfma_f32_16x16x32_bf16 v[122:125], v[74:77], v[208:211], v[122:125]
	v_mfma_f32_16x16x32_bf16 v[110:113], v[58:61], v[216:219], v[110:113]
	v_mfma_f32_16x16x32_bf16 v[106:109], v[74:77], v[216:219], v[106:109]
	v_mfma_f32_16x16x32_bf16 v[158:161], v[62:65], v[190:193], v[158:161]
	v_mfma_f32_16x16x32_bf16 v[154:157], v[78:81], v[190:193], v[154:157]
	v_mfma_f32_16x16x32_bf16 v[142:145], v[62:65], v[204:207], v[142:145]
	v_mfma_f32_16x16x32_bf16 v[138:141], v[78:81], v[204:207], v[138:141]
	v_mfma_f32_16x16x32_bf16 v[126:129], v[62:65], v[212:215], v[126:129]
	v_mfma_f32_16x16x32_bf16 v[122:125], v[78:81], v[212:215], v[122:125]
	v_mfma_f32_16x16x32_bf16 v[110:113], v[62:65], v[220:223], v[110:113]
	v_mfma_f32_16x16x32_bf16 v[106:109], v[78:81], v[220:223], v[106:109]
	v_mfma_f32_16x16x32_bf16 v[150:153], v[82:85], v[186:189], v[150:153]
	v_mfma_f32_16x16x32_bf16 v[146:149], v[90:93], v[186:189], v[146:149]
	v_mfma_f32_16x16x32_bf16 v[134:137], v[82:85], v[200:203], v[134:137]
	v_mfma_f32_16x16x32_bf16 v[130:133], v[90:93], v[200:203], v[130:133]
	v_mfma_f32_16x16x32_bf16 v[118:121], v[82:85], v[208:211], v[118:121]
	v_mfma_f32_16x16x32_bf16 v[114:117], v[90:93], v[208:211], v[114:117]
	v_mfma_f32_16x16x32_bf16 v[102:105], v[82:85], v[216:219], v[102:105]
	v_mfma_f32_16x16x32_bf16 v[98:101], v[90:93], v[216:219], v[98:101]
	v_mfma_f32_16x16x32_bf16 v[150:153], v[86:89], v[190:193], v[150:153]
	v_mfma_f32_16x16x32_bf16 v[146:149], v[94:97], v[190:193], v[146:149]
	v_mfma_f32_16x16x32_bf16 v[134:137], v[86:89], v[204:207], v[134:137]
	v_mfma_f32_16x16x32_bf16 v[130:133], v[94:97], v[204:207], v[130:133]
	v_mfma_f32_16x16x32_bf16 v[118:121], v[86:89], v[212:215], v[118:121]
	v_mfma_f32_16x16x32_bf16 v[114:117], v[94:97], v[212:215], v[114:117]
	v_mfma_f32_16x16x32_bf16 v[102:105], v[86:89], v[220:223], v[102:105]
	v_mfma_f32_16x16x32_bf16 v[98:101], v[94:97], v[220:223], v[98:101]
	s_barrier
; #define PG8_STAGE(bufoff, gbase, voff) do { _Pragma("unroll") for (int _i = 0; _i < 2; ++_i) \
;         __builtin_amdgcn_global_load_lds((const unsigned*)((const char*)(gbase) + (voff)[_i]), (PG8_LAS unsigned*)(lds + (bufoff) + ldsw + _i * 8192), 16, 0, 0); } while (0)
; #define PG8_LDA(dst, b, h) do { _Pragma("unroll") for (int m = 0; m < 4; ++m) _Pragma("unroll") for (int k = 0; k < 2; ++k) dst[m][k] = *(const PG8_LAS bf16x8*)(lds + PG8_SA(b, h) + aoff + m * 2048 + k * 1024); } while (0)
; #define PG8_MMA(ai, bj, At, Bt) do { __builtin_amdgcn_s_setprio(1); _Pragma("unroll") for (int m = 0; m < 4; ++m) _Pragma("unroll") for (int n = 0; n < 2; ++n) _Pragma("unroll") for (int k = 0; k < 2; ++k) \
;         acc[ai][bj][m][n] = __builtin_amdgcn_mfma_f32_16x16x32_bf16(Bt[n][k], At[m][k], acc[ai][bj][m][n], 0, 0, 0); __builtin_amdgcn_s_setprio(0); } while (0)
; #define PG8_WAIT_V(n) asm volatile("s_waitcnt vmcnt(" #n ")" ::: "memory")
; #define PG8_WAIT_L(n) asm volatile("s_waitcnt lgkmcnt(" #n ")" ::: "memory")
; #define PG8_BAR __builtin_amdgcn_s_barrier()
; #define PG8_SCHED __builtin_amdgcn_sched_barrier(0)
; template <class Epi, class Sched, bool ALIGN_EPI = false, bool SP2 = false>
; __device__ __forceinline__ void gemm_phase(PG8_LAS unsigned char* lds, const Gemm g, const Sched& S, const Epi& E) {
;     ...
;             PG8_LDA(At, 1, 1); PG8_STAGE(PG8_SB(1, 0), b3, voffB); PG8_STAGE(PG8_SB(1, 1), b3 + hstep, voffB); PG8_STAGE(PG8_SA(1, 0), a3, voffA);
;             PG8_WAIT_V(8); PG8_WAIT_L(0); PG8_BAR; PG8_MMA(1, 0, At, B0); PG8_MMA(1, 1, At, B1); PG8_BAR; PG8_SCHED;
;     ...
;         if constexpr (ALIGN_EPI) { if (wr == 0) PG8_BAR; }
	s_setprio 0
	s_add_i32 s10, s24, s94
	v_lshl_add_u64 v[194:195], v[194:195], 0, s[28:29]
	s_mov_b32 m0, s10
	ds_read_b128 v[186:189], v199 offset:49152
	ds_read_b128 v[190:193], v199 offset:50176
	ds_read_b128 v[200:203], v199 offset:51200
	ds_read_b128 v[204:207], v199 offset:52224
	ds_read_b128 v[208:211], v199 offset:53248
	ds_read_b128 v[212:215], v199 offset:54272
	ds_read_b128 v[216:219], v199 offset:55296
	ds_read_b128 v[220:223], v199 offset:56320
	global_load_lds_dwordx4 v[194:195], off
	s_add_i32 m0, s10, 0x2000
	s_add_u32 s10, s44, 0xb0080
	v_lshl_add_u64 v[194:195], v[224:225], 0, s[28:29]
	s_addc_u32 s11, s45, 0
	s_add_i32 s24, s25, s94
	global_load_lds_dwordx4 v[194:195], off
	v_lshl_add_u64 v[194:195], s[10:11], 0, v[0:1]
	s_mov_b32 m0, s24
	s_nop 0
	global_load_lds_dwordx4 v[194:195], off
	v_lshl_add_u64 v[194:195], s[10:11], 0, v[180:181]
	s_add_i32 m0, s24, 0x2000
	s_nop 0
	global_load_lds_dwordx4 v[194:195], off
	v_lshl_add_u64 v[194:195], v[226:227], 0, s[28:29]
	s_mov_b32 m0, s57
	s_nop 0
	global_load_lds_dwordx4 v[194:195], off
	v_lshl_add_u64 v[194:195], v[238:239], 0, s[28:29]
	s_mov_b32 m0, s78
	s_nop 0
	global_load_lds_dwordx4 v[194:195], off
	s_waitcnt vmcnt(8)
	s_waitcnt lgkmcnt(0)
	s_setprio 1
	s_barrier
	v_mfma_f32_16x16x32_bf16 v[70:73], v[58:61], v[186:189], v[70:73]
	v_mfma_f32_16x16x32_bf16 v[66:69], v[74:77], v[186:189], v[66:69]
	v_mfma_f32_16x16x32_bf16 v[46:49], v[58:61], v[200:203], v[46:49]
	v_mfma_f32_16x16x32_bf16 v[42:45], v[74:77], v[200:203], v[42:45]
	v_mfma_f32_16x16x32_bf16 v[30:33], v[58:61], v[208:211], v[30:33]
	v_mfma_f32_16x16x32_bf16 v[26:29], v[74:77], v[208:211], v[26:29]
	v_mfma_f32_16x16x32_bf16 v[14:17], v[58:61], v[216:219], v[14:17]
	v_mfma_f32_16x16x32_bf16 v[10:13], v[74:77], v[216:219], v[10:13]
	v_mfma_f32_16x16x32_bf16 v[70:73], v[62:65], v[190:193], v[70:73]
	v_mfma_f32_16x16x32_bf16 v[66:69], v[78:81], v[190:193], v[66:69]
	v_mfma_f32_16x16x32_bf16 v[46:49], v[62:65], v[204:207], v[46:49]
	v_mfma_f32_16x16x32_bf16 v[42:45], v[78:81], v[204:207], v[42:45]
	v_mfma_f32_16x16x32_bf16 v[30:33], v[62:65], v[212:215], v[30:33]
	v_mfma_f32_16x16x32_bf16 v[26:29], v[78:81], v[212:215], v[26:29]
	v_mfma_f32_16x16x32_bf16 v[14:17], v[62:65], v[220:223], v[14:17]
	v_mfma_f32_16x16x32_bf16 v[10:13], v[78:81], v[220:223], v[10:13]
	v_mfma_f32_16x16x32_bf16 v[54:57], v[82:85], v[186:189], v[54:57]
	v_mfma_f32_16x16x32_bf16 v[50:53], v[90:93], v[186:189], v[50:53]
	v_mfma_f32_16x16x32_bf16 v[38:41], v[82:85], v[200:203], v[38:41]
	v_mfma_f32_16x16x32_bf16 v[34:37], v[90:93], v[200:203], v[34:37]
	v_mfma_f32_16x16x32_bf16 v[22:25], v[82:85], v[208:211], v[22:25]
	v_mfma_f32_16x16x32_bf16 v[18:21], v[90:93], v[208:211], v[18:21]
	v_mfma_f32_16x16x32_bf16 v[6:9], v[82:85], v[216:219], v[6:9]
	v_mfma_f32_16x16x32_bf16 v[2:5], v[90:93], v[216:219], v[2:5]
	v_mfma_f32_16x16x32_bf16 v[54:57], v[86:89], v[190:193], v[54:57]
	v_mfma_f32_16x16x32_bf16 v[50:53], v[94:97], v[190:193], v[50:53]
	v_mfma_f32_16x16x32_bf16 v[38:41], v[86:89], v[204:207], v[38:41]
	v_mfma_f32_16x16x32_bf16 v[34:37], v[94:97], v[204:207], v[34:37]
	v_mfma_f32_16x16x32_bf16 v[22:25], v[86:89], v[212:215], v[22:25]
	v_mfma_f32_16x16x32_bf16 v[18:21], v[94:97], v[212:215], v[18:21]
	v_mfma_f32_16x16x32_bf16 v[6:9], v[86:89], v[220:223], v[6:9]
	v_mfma_f32_16x16x32_bf16 v[2:5], v[94:97], v[220:223], v[2:5]
	s_barrier
	s_setprio 0
	s_add_i32 s73, s73, 2
	s_add_u32 s35, s35, 0x100
	s_addc_u32 s72, s72, 0
	s_cmp_gt_u32 s73, 41
	s_mov_b64 s[24:25], s[42:43]
	s_cbranch_scc0 .LBB0_1208
	s_and_b64 vcc, exec, s[20:21]
	s_cbranch_vccz .LBB0_1211
	s_barrier

; #define PG8_STAGE(bufoff, gbase, voff) do { _Pragma("unroll") for (int _i = 0; _i < 2; ++_i) \
;         __builtin_amdgcn_global_load_lds((const unsigned*)((const char*)(gbase) + (voff)[_i]), (PG8_LAS unsigned*)(lds + (bufoff) + ldsw + _i * 8192), 16, 0, 0); } while (0)
; #define PG8_LDA(dst, b, h) do { _Pragma("unroll") for (int m = 0; m < 4; ++m) _Pragma("unroll") for (int k = 0; k < 2; ++k) dst[m][k] = *(const PG8_LAS bf16x8*)(lds + PG8_SA(b, h) + aoff + m * 2048 + k * 1024); } while (0)
; #define PG8_LDB(dst, b, h) do { _Pragma("unroll") for (int n = 0; n < 2; ++n) _Pragma("unroll") for (int k = 0; k < 2; ++k) dst[n][k] = *(const PG8_LAS bf16x8*)(lds + PG8_SB(b, h) + boff + n * 2048 + k * 1024); } while (0)
; #define PG8_MMA(ai, bj, At, Bt) do { __builtin_amdgcn_s_setprio(1); _Pragma("unroll") for (int m = 0; m < 4; ++m) _Pragma("unroll") for (int n = 0; n < 2; ++n) _Pragma("unroll") for (int k = 0; k < 2; ++k) \
;         acc[ai][bj][m][n] = __builtin_amdgcn_mfma_f32_16x16x32_bf16(Bt[n][k], At[m][k], acc[ai][bj][m][n], 0, 0, 0); __builtin_amdgcn_s_setprio(0); } while (0)
; #define PG8_WAIT_V(n) asm volatile("s_waitcnt vmcnt(" #n ")" ::: "memory")
; #define PG8_BAR __builtin_amdgcn_s_barrier()
; template <class Epi, class Sched, bool ALIGN_EPI = false, bool SP2 = false>
; __device__ __forceinline__ void gemm_phase(PG8_LAS unsigned char* lds, const Gemm g, const Sched& S, const Epi& E) {
;     ...
;         for (int t = 0; t < nt; t += 2) {
;             const bool last = (t == nt - 2);
;             const char* a1 = cA + (size_t)(t + 1) * kstep;
;             const char* a2 = last ? nA : cA + (size_t)(t + 2) * kstep; const char* b2 = last ? nB : cB + (size_t)(t + 2) * kstep;
;             const char* a3 = a2 + kstep; const char* b3 = b2 + kstep;
;             if (last && has_next) S.a_ready(nxt);
;             if constexpr (SP2) {
;             PG8_LDB(B0, 0, 0); PG8_LDB(B1, 0, 1); PG8_SCHED; PG8_LDA(At, 0, 0); PG8_STAGE(PG8_SA(1, 1), a1 + hstep, voffA);
;             PG8_WAIT_V(8); PG8_WAIT_L(0); PG8_BAR; PG8_MMA(0, 0, At, B0); PG8_MMA(0, 1, At, B1); PG8_BAR; PG8_SCHED;
;             PG8_LDA(At, 0, 1); PG8_STAGE(PG8_SB(0, 0), b2, voffB); PG8_STAGE(PG8_SB(0, 1), b2 + hstep, voffB); PG8_STAGE(PG8_SA(0, 0), a2, voffA);
;             PG8_WAIT_V(8); PG8_WAIT_L(0); PG8_BAR; PG8_MMA(1, 0, At, B0); PG8_MMA(1, 1, At, B1); PG8_BAR; PG8_SCHED;
.LBB0_1275:
	s_add_u32 s10, s40, 0xfffc0080
	s_addc_u32 s11, s41, -1
	s_add_i32 s64, 16, 0x10000
	s_cmp_eq_u32 s63, 12
	s_cselect_b32 s51, s34, s11
	s_cselect_b32 s50, s35, s10
	s_cselect_b32 s49, s27, s62
	s_cselect_b32 s48, s43, s59
	s_add_i32 s65, 16, 0x14000
	v_add_u32_e32 v142, s64, v179
	v_add_u32_e32 v176, s65, v179
	ds_read_b128 v[130:133], v142
	ds_read_b128 v[134:137], v142 offset:1024
	ds_read_b128 v[138:141], v142 offset:2048
	ds_read_b128 v[142:145], v142 offset:3072
	ds_read_b128 v[158:161], v176
	ds_read_b128 v[182:185], v176 offset:1024
	ds_read_b128 v[186:189], v176 offset:2048
	ds_read_b128 v[190:193], v176 offset:3072
	v_lshl_add_u64 v[176:177], s[40:41], 0, v[156:157]
	s_add_i32 m0, s4, 0xc000
	ds_read_b128 v[194:197], v181
	ds_read_b128 v[198:201], v181 offset:1024
	ds_read_b128 v[202:205], v181 offset:2048
	ds_read_b128 v[206:209], v181 offset:3072
	ds_read_b128 v[210:213], v181 offset:4096
	ds_read_b128 v[214:217], v181 offset:5120
	ds_read_b128 v[218:221], v181 offset:6144
	ds_read_b128 v[222:225], v181 offset:7168
	global_load_lds_dwordx4 v[176:177], off
	v_lshl_add_u64 v[176:177], s[40:41], 0, v[154:155]
	s_add_i32 m0, s4, 0xe000
	s_nop 0
	global_load_lds_dwordx4 v[176:177], off
	s_waitcnt vmcnt(8)
	s_waitcnt lgkmcnt(0)
	s_setprio 1
	s_barrier
	v_mfma_f32_16x16x32_bf16 v[126:129], v[130:133], v[194:197], v[126:129]
	v_mfma_f32_16x16x32_bf16 v[122:125], v[138:141], v[194:197], v[122:125]
	v_mfma_f32_16x16x32_bf16 v[110:113], v[130:133], v[202:205], v[110:113]
	v_mfma_f32_16x16x32_bf16 v[106:109], v[138:141], v[202:205], v[106:109]
	v_mfma_f32_16x16x32_bf16 v[94:97], v[130:133], v[210:213], v[94:97]
	v_mfma_f32_16x16x32_bf16 v[90:93], v[138:141], v[210:213], v[90:93]
	v_mfma_f32_16x16x32_bf16 v[78:81], v[130:133], v[218:221], v[78:81]
	v_mfma_f32_16x16x32_bf16 v[74:77], v[138:141], v[218:221], v[74:77]
	v_mfma_f32_16x16x32_bf16 v[126:129], v[134:137], v[198:201], v[126:129]
	v_mfma_f32_16x16x32_bf16 v[122:125], v[142:145], v[198:201], v[122:125]
	v_mfma_f32_16x16x32_bf16 v[110:113], v[134:137], v[206:209], v[110:113]
	v_mfma_f32_16x16x32_bf16 v[106:109], v[142:145], v[206:209], v[106:109]
	v_mfma_f32_16x16x32_bf16 v[94:97], v[134:137], v[214:217], v[94:97]
	v_mfma_f32_16x16x32_bf16 v[90:93], v[142:145], v[214:217], v[90:93]
	v_mfma_f32_16x16x32_bf16 v[78:81], v[134:137], v[222:225], v[78:81]
	v_mfma_f32_16x16x32_bf16 v[74:77], v[142:145], v[222:225], v[74:77]
	v_mfma_f32_16x16x32_bf16 v[118:121], v[158:161], v[194:197], v[118:121]
	v_mfma_f32_16x16x32_bf16 v[114:117], v[186:189], v[194:197], v[114:117]
	v_mfma_f32_16x16x32_bf16 v[102:105], v[158:161], v[202:205], v[102:105]
	v_mfma_f32_16x16x32_bf16 v[98:101], v[186:189], v[202:205], v[98:101]
	v_mfma_f32_16x16x32_bf16 v[86:89], v[158:161], v[210:213], v[86:89]
	v_mfma_f32_16x16x32_bf16 v[82:85], v[186:189], v[210:213], v[82:85]
	v_mfma_f32_16x16x32_bf16 v[70:73], v[158:161], v[218:221], v[70:73]
	v_mfma_f32_16x16x32_bf16 v[66:69], v[186:189], v[218:221], v[66:69]
	v_mfma_f32_16x16x32_bf16 v[118:121], v[182:185], v[198:201], v[118:121]
	v_mfma_f32_16x16x32_bf16 v[114:117], v[190:193], v[198:201], v[114:117]
	v_mfma_f32_16x16x32_bf16 v[102:105], v[182:185], v[206:209], v[102:105]
	v_mfma_f32_16x16x32_bf16 v[98:101], v[190:193], v[206:209], v[98:101]
	v_mfma_f32_16x16x32_bf16 v[86:89], v[182:185], v[214:217], v[86:89]
	v_mfma_f32_16x16x32_bf16 v[82:85], v[190:193], v[214:217], v[82:85]
	v_mfma_f32_16x16x32_bf16 v[70:73], v[182:185], v[222:225], v[70:73]
	v_mfma_f32_16x16x32_bf16 v[66:69], v[190:193], v[222:225], v[66:69]
	s_barrier
	s_setprio 0
	s_add_i32 s10, s64, s3
	v_lshl_add_u64 v[176:177], s[48:49], 0, v[0:1]
	s_mov_b32 m0, s10
	ds_read_b128 v[194:197], v181 offset:16384
	ds_read_b128 v[198:201], v181 offset:17408
	ds_read_b128 v[202:205], v181 offset:18432
	ds_read_b128 v[206:209], v181 offset:19456
	ds_read_b128 v[210:213], v181 offset:20480
	ds_read_b128 v[214:217], v181 offset:21504
	ds_read_b128 v[218:221], v181 offset:22528
	ds_read_b128 v[222:225], v181 offset:23552
	global_load_lds_dwordx4 v[176:177], off
	s_add_i32 m0, s10, 0x2000
	s_add_u32 s10, s48, 0x40000
	v_lshl_add_u64 v[226:227], s[48:49], 0, v[146:147]
	s_addc_u32 s11, s49, 0
	s_add_i32 s64, s65, s3
	global_load_lds_dwordx4 v[226:227], off
	v_lshl_add_u64 v[238:239], s[10:11], 0, v[0:1]
	s_mov_b32 m0, s64
	v_lshl_add_u64 v[240:241], s[50:51], 0, v[148:149]
	global_load_lds_dwordx4 v[238:239], off
	v_lshl_add_u64 v[238:239], s[10:11], 0, v[146:147]
	s_add_i32 m0, s64, 0x2000
	s_nop 0
	global_load_lds_dwordx4 v[238:239], off
	v_lshl_add_u64 v[238:239], s[50:51], 0, v[150:151]
	s_mov_b32 m0, s4
	s_nop 0
	global_load_lds_dwordx4 v[238:239], off
	s_mov_b32 m0, s5
	s_nop 0
	global_load_lds_dwordx4 v[240:241], off
	s_waitcnt vmcnt(8)
	s_waitcnt lgkmcnt(0)
	s_setprio 1
	s_barrier
; #define PG8_STAGE(bufoff, gbase, voff) do { _Pragma("unroll") for (int _i = 0; _i < 2; ++_i) \
;         __builtin_amdgcn_global_load_lds((const unsigned*)((const char*)(gbase) + (voff)[_i]), (PG8_LAS unsigned*)(lds + (bufoff) + ldsw + _i * 8192), 16, 0, 0); } while (0)
; #define PG8_LDA(dst, b, h) do { _Pragma("unroll") for (int m = 0; m < 4; ++m) _Pragma("unroll") for (int k = 0; k < 2; ++k) dst[m][k] = *(const PG8_LAS bf16x8*)(lds + PG8_SA(b, h) + aoff + m * 2048 + k * 1024); } while (0)
; #define PG8_LDB(dst, b, h) do { _Pragma("unroll") for (int n = 0; n < 2; ++n) _Pragma("unroll") for (int k = 0; k < 2; ++k) dst[n][k] = *(const PG8_LAS bf16x8*)(lds + PG8_SB(b, h) + boff + n * 2048 + k * 1024); } while (0)
; #define PG8_MMA(ai, bj, At, Bt) do { __builtin_amdgcn_s_setprio(1); _Pragma("unroll") for (int m = 0; m < 4; ++m) _Pragma("unroll") for (int n = 0; n < 2; ++n) _Pragma("unroll") for (int k = 0; k < 2; ++k) \
;         acc[ai][bj][m][n] = __builtin_amdgcn_mfma_f32_16x16x32_bf16(Bt[n][k], At[m][k], acc[ai][bj][m][n], 0, 0, 0); __builtin_amdgcn_s_setprio(0); } while (0)
; #define PG8_WAIT_V(n) asm volatile("s_waitcnt vmcnt(" #n ")" ::: "memory")
; #define PG8_WAIT_L(n) asm volatile("s_waitcnt lgkmcnt(" #n ")" ::: "memory")
; #define PG8_BAR __builtin_amdgcn_s_barrier()
; #define PG8_SCHED __builtin_amdgcn_sched_barrier(0)
; template <class Epi, class Sched, bool ALIGN_EPI = false, bool SP2 = false>
; __device__ __forceinline__ void gemm_phase(PG8_LAS unsigned char* lds, const Gemm g, const Sched& S, const Epi& E) {
;     ...
;             PG8_WAIT_V(8); PG8_WAIT_L(0); PG8_BAR; PG8_MMA(1, 0, At, B0); PG8_MMA(1, 1, At, B1); PG8_BAR; PG8_SCHED;
;             PG8_LDB(B0, 1, 0); PG8_LDB(B1, 1, 1); PG8_SCHED; PG8_LDA(At, 1, 0); PG8_STAGE(PG8_SA(0, 1), a2 + hstep, voffA);
;             PG8_WAIT_V(8); PG8_WAIT_L(0); PG8_BAR; PG8_MMA(0, 0, At, B0); PG8_MMA(0, 1, At, B1); PG8_BAR; PG8_SCHED;
	v_mfma_f32_16x16x32_bf16 v[62:65], v[130:133], v[194:197], v[62:65]
	v_mfma_f32_16x16x32_bf16 v[58:61], v[138:141], v[194:197], v[58:61]
	v_mfma_f32_16x16x32_bf16 v[46:49], v[130:133], v[202:205], v[46:49]
	v_mfma_f32_16x16x32_bf16 v[42:45], v[138:141], v[202:205], v[42:45]
	v_mfma_f32_16x16x32_bf16 v[30:33], v[130:133], v[210:213], v[30:33]
	v_mfma_f32_16x16x32_bf16 v[26:29], v[138:141], v[210:213], v[26:29]
	v_mfma_f32_16x16x32_bf16 v[14:17], v[130:133], v[218:221], v[14:17]
	v_mfma_f32_16x16x32_bf16 v[10:13], v[138:141], v[218:221], v[10:13]
	v_mfma_f32_16x16x32_bf16 v[62:65], v[134:137], v[198:201], v[62:65]
	v_mfma_f32_16x16x32_bf16 v[58:61], v[142:145], v[198:201], v[58:61]
	v_mfma_f32_16x16x32_bf16 v[46:49], v[134:137], v[206:209], v[46:49]
	v_mfma_f32_16x16x32_bf16 v[42:45], v[142:145], v[206:209], v[42:45]
	v_mfma_f32_16x16x32_bf16 v[30:33], v[134:137], v[214:217], v[30:33]
	v_mfma_f32_16x16x32_bf16 v[26:29], v[142:145], v[214:217], v[26:29]
	v_mfma_f32_16x16x32_bf16 v[14:17], v[134:137], v[222:225], v[14:17]
	v_mfma_f32_16x16x32_bf16 v[10:13], v[142:145], v[222:225], v[10:13]
	v_mfma_f32_16x16x32_bf16 v[54:57], v[158:161], v[194:197], v[54:57]
	v_mfma_f32_16x16x32_bf16 v[50:53], v[186:189], v[194:197], v[50:53]
	v_mfma_f32_16x16x32_bf16 v[38:41], v[158:161], v[202:205], v[38:41]
	v_mfma_f32_16x16x32_bf16 v[34:37], v[186:189], v[202:205], v[34:37]
	v_mfma_f32_16x16x32_bf16 v[22:25], v[158:161], v[210:213], v[22:25]
	v_mfma_f32_16x16x32_bf16 v[18:21], v[186:189], v[210:213], v[18:21]
	v_mfma_f32_16x16x32_bf16 v[6:9], v[158:161], v[218:221], v[6:9]
	v_mfma_f32_16x16x32_bf16 v[2:5], v[186:189], v[218:221], v[2:5]
	v_mfma_f32_16x16x32_bf16 v[54:57], v[182:185], v[198:201], v[54:57]
	v_mfma_f32_16x16x32_bf16 v[50:53], v[190:193], v[198:201], v[50:53]
	v_mfma_f32_16x16x32_bf16 v[38:41], v[182:185], v[206:209], v[38:41]
	v_mfma_f32_16x16x32_bf16 v[34:37], v[190:193], v[206:209], v[34:37]
	v_mfma_f32_16x16x32_bf16 v[22:25], v[182:185], v[214:217], v[22:25]
	v_mfma_f32_16x16x32_bf16 v[18:21], v[190:193], v[214:217], v[18:21]
	v_mfma_f32_16x16x32_bf16 v[6:9], v[182:185], v[222:225], v[6:9]
	v_mfma_f32_16x16x32_bf16 v[2:5], v[190:193], v[222:225], v[2:5]
	s_barrier
	s_setprio 0
	s_add_i32 s64, 16, 0x18000
	s_add_i32 s65, 16, 0x1c000
	v_add_u32_e32 v142, s64, v179
	v_add_u32_e32 v190, s65, v179
	ds_read_b128 v[130:133], v142
	ds_read_b128 v[134:137], v142 offset:1024
	ds_read_b128 v[138:141], v142 offset:2048
	ds_read_b128 v[142:145], v142 offset:3072
	ds_read_b128 v[158:161], v190
	ds_read_b128 v[182:185], v190 offset:1024
	ds_read_b128 v[186:189], v190 offset:2048
	ds_read_b128 v[190:193], v190 offset:3072
	s_add_u32 s10, s50, 0x40000
	s_addc_u32 s11, s51, 0
	s_mov_b32 m0, s6
	v_lshl_add_u64 v[242:243], s[10:11], 0, v[150:151]
	ds_read_b128 v[194:197], v181 offset:32768
	ds_read_b128 v[198:201], v181 offset:33792
	ds_read_b128 v[202:205], v181 offset:34816
	ds_read_b128 v[206:209], v181 offset:35840
	ds_read_b128 v[210:213], v181 offset:36864
	ds_read_b128 v[214:217], v181 offset:37888
	ds_read_b128 v[218:221], v181 offset:38912
	ds_read_b128 v[222:225], v181 offset:39936
	global_load_lds_dwordx4 v[242:243], off
	v_lshl_add_u64 v[242:243], s[10:11], 0, v[148:149]
	s_mov_b32 m0, s7
	s_nop 0
	global_load_lds_dwordx4 v[242:243], off
	s_waitcnt vmcnt(8)
	s_waitcnt lgkmcnt(0)
	s_setprio 1
	s_barrier
	v_mfma_f32_16x16x32_bf16 v[126:129], v[130:133], v[194:197], v[126:129]
	v_mfma_f32_16x16x32_bf16 v[122:125], v[138:141], v[194:197], v[122:125]
	v_mfma_f32_16x16x32_bf16 v[110:113], v[130:133], v[202:205], v[110:113]
	v_mfma_f32_16x16x32_bf16 v[106:109], v[138:141], v[202:205], v[106:109]
	v_mfma_f32_16x16x32_bf16 v[94:97], v[130:133], v[210:213], v[94:97]
	v_mfma_f32_16x16x32_bf16 v[90:93], v[138:141], v[210:213], v[90:93]
	v_mfma_f32_16x16x32_bf16 v[78:81], v[130:133], v[218:221], v[78:81]
	v_mfma_f32_16x16x32_bf16 v[74:77], v[138:141], v[218:221], v[74:77]
	v_mfma_f32_16x16x32_bf16 v[126:129], v[134:137], v[198:201], v[126:129]
	v_mfma_f32_16x16x32_bf16 v[122:125], v[142:145], v[198:201], v[122:125]
	v_mfma_f32_16x16x32_bf16 v[110:113], v[134:137], v[206:209], v[110:113]
	v_mfma_f32_16x16x32_bf16 v[106:109], v[142:145], v[206:209], v[106:109]
	v_mfma_f32_16x16x32_bf16 v[94:97], v[134:137], v[214:217], v[94:97]
	v_mfma_f32_16x16x32_bf16 v[90:93], v[142:145], v[214:217], v[90:93]
	v_mfma_f32_16x16x32_bf16 v[78:81], v[134:137], v[222:225], v[78:81]
	v_mfma_f32_16x16x32_bf16 v[74:77], v[142:145], v[222:225], v[74:77]
	v_mfma_f32_16x16x32_bf16 v[118:121], v[158:161], v[194:197], v[118:121]
	v_mfma_f32_16x16x32_bf16 v[114:117], v[186:189], v[194:197], v[114:117]
	v_mfma_f32_16x16x32_bf16 v[102:105], v[158:161], v[202:205], v[102:105]
	v_mfma_f32_16x16x32_bf16 v[98:101], v[186:189], v[202:205], v[98:101]
	v_mfma_f32_16x16x32_bf16 v[86:89], v[158:161], v[210:213], v[86:89]
	v_mfma_f32_16x16x32_bf16 v[82:85], v[186:189], v[210:213], v[82:85]
	v_mfma_f32_16x16x32_bf16 v[70:73], v[158:161], v[218:221], v[70:73]
	v_mfma_f32_16x16x32_bf16 v[66:69], v[186:189], v[218:221], v[66:69]
	v_mfma_f32_16x16x32_bf16 v[118:121], v[182:185], v[198:201], v[118:121]
	v_mfma_f32_16x16x32_bf16 v[114:117], v[190:193], v[198:201], v[114:117]
	v_mfma_f32_16x16x32_bf16 v[102:105], v[182:185], v[206:209], v[102:105]
	v_mfma_f32_16x16x32_bf16 v[98:101], v[190:193], v[206:209], v[98:101]
	v_mfma_f32_16x16x32_bf16 v[86:89], v[182:185], v[214:217], v[86:89]
	v_mfma_f32_16x16x32_bf16 v[82:85], v[190:193], v[214:217], v[82:85]
	v_mfma_f32_16x16x32_bf16 v[70:73], v[182:185], v[222:225], v[70:73]
	v_mfma_f32_16x16x32_bf16 v[66:69], v[190:193], v[222:225], v[66:69]
	s_barrier
; #define PG8_STAGE(bufoff, gbase, voff) do { _Pragma("unroll") for (int _i = 0; _i < 2; ++_i) \
;         __builtin_amdgcn_global_load_lds((const unsigned*)((const char*)(gbase) + (voff)[_i]), (PG8_LAS unsigned*)(lds + (bufoff) + ldsw + _i * 8192), 16, 0, 0); } while (0)
; #define PG8_LDA(dst, b, h) do { _Pragma("unroll") for (int m = 0; m < 4; ++m) _Pragma("unroll") for (int k = 0; k < 2; ++k) dst[m][k] = *(const PG8_LAS bf16x8*)(lds + PG8_SA(b, h) + aoff + m * 2048 + k * 1024); } while (0)
; #define PG8_MMA(ai, bj, At, Bt) do { __builtin_amdgcn_s_setprio(1); _Pragma("unroll") for (int m = 0; m < 4; ++m) _Pragma("unroll") for (int n = 0; n < 2; ++n) _Pragma("unroll") for (int k = 0; k < 2; ++k) \
;         acc[ai][bj][m][n] = __builtin_amdgcn_mfma_f32_16x16x32_bf16(Bt[n][k], At[m][k], acc[ai][bj][m][n], 0, 0, 0); __builtin_amdgcn_s_setprio(0); } while (0)
; #define PG8_WAIT_V(n) asm volatile("s_waitcnt vmcnt(" #n ")" ::: "memory")
; #define PG8_WAIT_L(n) asm volatile("s_waitcnt lgkmcnt(" #n ")" ::: "memory")
; #define PG8_BAR __builtin_amdgcn_s_barrier()
; #define PG8_SCHED __builtin_amdgcn_sched_barrier(0)
; template <class Epi, class Sched, bool ALIGN_EPI = false, bool SP2 = false>
; __device__ __forceinline__ void gemm_phase(PG8_LAS unsigned char* lds, const Gemm g, const Sched& S, const Epi& E) {
;     ...
;             PG8_LDA(At, 1, 1); PG8_STAGE(PG8_SB(1, 0), b3, voffB); PG8_STAGE(PG8_SB(1, 1), b3 + hstep, voffB); PG8_STAGE(PG8_SA(1, 0), a3, voffA);
;             PG8_WAIT_V(8); PG8_WAIT_L(0); PG8_BAR; PG8_MMA(1, 0, At, B0); PG8_MMA(1, 1, At, B1); PG8_BAR; PG8_SCHED;
;     ...
;         if constexpr (ALIGN_EPI) { if (wr == 0) PG8_BAR; }
	s_setprio 0
	s_add_i32 s10, s64, s3
	v_lshl_add_u64 v[176:177], v[176:177], 0, s[28:29]
	s_mov_b32 m0, s10
	ds_read_b128 v[194:197], v181 offset:49152
	ds_read_b128 v[198:201], v181 offset:50176
	ds_read_b128 v[202:205], v181 offset:51200
	ds_read_b128 v[206:209], v181 offset:52224
	ds_read_b128 v[210:213], v181 offset:53248
	ds_read_b128 v[214:217], v181 offset:54272
	ds_read_b128 v[218:221], v181 offset:55296
	ds_read_b128 v[222:225], v181 offset:56320
	global_load_lds_dwordx4 v[176:177], off
	s_add_i32 m0, s10, 0x2000
	s_add_u32 s10, s48, 0x40080
	v_lshl_add_u64 v[176:177], v[226:227], 0, s[28:29]
	s_addc_u32 s11, s49, 0
	s_add_i32 s48, s65, s3
	global_load_lds_dwordx4 v[176:177], off
	v_lshl_add_u64 v[176:177], s[10:11], 0, v[0:1]
	s_mov_b32 m0, s48
	s_nop 0
	global_load_lds_dwordx4 v[176:177], off
	v_lshl_add_u64 v[176:177], s[10:11], 0, v[146:147]
	s_add_i32 m0, s48, 0x2000
	s_nop 0
	global_load_lds_dwordx4 v[176:177], off
	v_lshl_add_u64 v[176:177], v[238:239], 0, s[28:29]
	s_mov_b32 m0, s54
	s_nop 0
	global_load_lds_dwordx4 v[176:177], off
	v_lshl_add_u64 v[176:177], v[240:241], 0, s[28:29]
	s_mov_b32 m0, s55
	s_nop 0
	global_load_lds_dwordx4 v[176:177], off
	s_waitcnt vmcnt(8)
	s_waitcnt lgkmcnt(0)
	s_setprio 1
	s_barrier
	v_mfma_f32_16x16x32_bf16 v[62:65], v[130:133], v[194:197], v[62:65]
	v_mfma_f32_16x16x32_bf16 v[58:61], v[138:141], v[194:197], v[58:61]
	v_mfma_f32_16x16x32_bf16 v[46:49], v[130:133], v[202:205], v[46:49]
	v_mfma_f32_16x16x32_bf16 v[42:45], v[138:141], v[202:205], v[42:45]
	v_mfma_f32_16x16x32_bf16 v[30:33], v[130:133], v[210:213], v[30:33]
	v_mfma_f32_16x16x32_bf16 v[26:29], v[138:141], v[210:213], v[26:29]
	v_mfma_f32_16x16x32_bf16 v[14:17], v[130:133], v[218:221], v[14:17]
	v_mfma_f32_16x16x32_bf16 v[10:13], v[138:141], v[218:221], v[10:13]
	v_mfma_f32_16x16x32_bf16 v[62:65], v[134:137], v[198:201], v[62:65]
	v_mfma_f32_16x16x32_bf16 v[58:61], v[142:145], v[198:201], v[58:61]
	v_mfma_f32_16x16x32_bf16 v[46:49], v[134:137], v[206:209], v[46:49]
	v_mfma_f32_16x16x32_bf16 v[42:45], v[142:145], v[206:209], v[42:45]
	v_mfma_f32_16x16x32_bf16 v[30:33], v[134:137], v[214:217], v[30:33]
	v_mfma_f32_16x16x32_bf16 v[26:29], v[142:145], v[214:217], v[26:29]
	v_mfma_f32_16x16x32_bf16 v[14:17], v[134:137], v[222:225], v[14:17]
	v_mfma_f32_16x16x32_bf16 v[10:13], v[142:145], v[222:225], v[10:13]
	v_mfma_f32_16x16x32_bf16 v[54:57], v[158:161], v[194:197], v[54:57]
	v_mfma_f32_16x16x32_bf16 v[50:53], v[186:189], v[194:197], v[50:53]
	v_mfma_f32_16x16x32_bf16 v[38:41], v[158:161], v[202:205], v[38:41]
	v_mfma_f32_16x16x32_bf16 v[34:37], v[186:189], v[202:205], v[34:37]
	v_mfma_f32_16x16x32_bf16 v[22:25], v[158:161], v[210:213], v[22:25]
	v_mfma_f32_16x16x32_bf16 v[18:21], v[186:189], v[210:213], v[18:21]
	v_mfma_f32_16x16x32_bf16 v[6:9], v[158:161], v[218:221], v[6:9]
	v_mfma_f32_16x16x32_bf16 v[2:5], v[186:189], v[218:221], v[2:5]
	v_mfma_f32_16x16x32_bf16 v[54:57], v[182:185], v[198:201], v[54:57]
	v_mfma_f32_16x16x32_bf16 v[50:53], v[190:193], v[198:201], v[50:53]
	v_mfma_f32_16x16x32_bf16 v[38:41], v[182:185], v[206:209], v[38:41]
	v_mfma_f32_16x16x32_bf16 v[34:37], v[190:193], v[206:209], v[34:37]
	v_mfma_f32_16x16x32_bf16 v[22:25], v[182:185], v[214:217], v[22:25]
	v_mfma_f32_16x16x32_bf16 v[18:21], v[190:193], v[214:217], v[18:21]
	v_mfma_f32_16x16x32_bf16 v[6:9], v[182:185], v[222:225], v[6:9]
	v_mfma_f32_16x16x32_bf16 v[2:5], v[190:193], v[222:225], v[2:5]
	s_barrier
	s_setprio 0
	s_add_i32 s63, s63, 2
	s_add_u32 s59, s59, 0x100
	s_addc_u32 s62, s62, 0
	s_add_u32 s40, s40, 0x100
	s_addc_u32 s41, s41, 0
	s_cmp_gt_u32 s63, 13
	s_cbranch_scc0 .LBB0_1275
	s_and_b64 vcc, exec, s[24:25]
	s_cbranch_vccz .LBB0_1278
	s_barrier

; #define PG8_STAGE(bufoff, gbase, voff) do { _Pragma("unroll") for (int _i = 0; _i < 2; ++_i) \
;         __builtin_amdgcn_global_load_lds((const unsigned*)((const char*)(gbase) + (voff)[_i]), (PG8_LAS unsigned*)(lds + (bufoff) + ldsw + _i * 8192), 16, 0, 0); } while (0)
; #define PG8_LDA(dst, b, h) do { _Pragma("unroll") for (int m = 0; m < 4; ++m) _Pragma("unroll") for (int k = 0; k < 2; ++k) dst[m][k] = *(const PG8_LAS bf16x8*)(lds + PG8_SA(b, h) + aoff + m * 2048 + k * 1024); } while (0)
; #define PG8_LDB(dst, b, h) do { _Pragma("unroll") for (int n = 0; n < 2; ++n) _Pragma("unroll") for (int k = 0; k < 2; ++k) dst[n][k] = *(const PG8_LAS bf16x8*)(lds + PG8_SB(b, h) + boff + n * 2048 + k * 1024); } while (0)
; #define PG8_MMA(ai, bj, At, Bt) do { __builtin_amdgcn_s_setprio(1); _Pragma("unroll") for (int m = 0; m < 4; ++m) _Pragma("unroll") for (int n = 0; n < 2; ++n) _Pragma("unroll") for (int k = 0; k < 2; ++k) \
;         acc[ai][bj][m][n] = __builtin_amdgcn_mfma_f32_16x16x32_bf16(Bt[n][k], At[m][k], acc[ai][bj][m][n], 0, 0, 0); __builtin_amdgcn_s_setprio(0); } while (0)
; #define PG8_WAIT_V(n) asm volatile("s_waitcnt vmcnt(" #n ")" ::: "memory")
; #define PG8_BAR __builtin_amdgcn_s_barrier()
; template <class Epi, class Sched, bool ALIGN_EPI = false, bool SP2 = false>
; __device__ __forceinline__ void gemm_phase(PG8_LAS unsigned char* lds, const Gemm g, const Sched& S, const Epi& E) {
;     ...
;         for (int t = 0; t < nt; t += 2) {
;             const bool last = (t == nt - 2);
;             const char* a1 = cA + (size_t)(t + 1) * kstep;
;             const char* a2 = last ? nA : cA + (size_t)(t + 2) * kstep; const char* b2 = last ? nB : cB + (size_t)(t + 2) * kstep;
;             const char* a3 = a2 + kstep; const char* b3 = b2 + kstep;
;             if (last && has_next) S.a_ready(nxt);
;             if constexpr (SP2) {
;             PG8_LDB(B0, 0, 0); PG8_LDB(B1, 0, 1); PG8_SCHED; PG8_LDA(At, 0, 0); PG8_STAGE(PG8_SA(1, 1), a1 + hstep, voffA);
;             PG8_WAIT_V(8); PG8_WAIT_L(0); PG8_BAR; PG8_MMA(0, 0, At, B0); PG8_MMA(0, 1, At, B1); PG8_BAR; PG8_SCHED;
;             PG8_LDA(At, 0, 1); PG8_STAGE(PG8_SB(0, 0), b2, voffB); PG8_STAGE(PG8_SB(0, 1), b2 + hstep, voffB); PG8_STAGE(PG8_SA(0, 0), a2, voffA);
;             PG8_WAIT_V(8); PG8_WAIT_L(0); PG8_BAR; PG8_MMA(1, 0, At, B0); PG8_MMA(1, 1, At, B1); PG8_BAR; PG8_SCHED;
.LBB0_1295:
	s_add_u32 s40, s42, 0x100
	s_addc_u32 s41, s43, 0
	s_add_i32 s10, 16, 0x10000
	s_cmp_eq_u32 s68, 40
	s_cselect_b32 s49, s25, s41
	s_cselect_b32 s48, s24, s40
	v_add_u32_e32 v140, s10, v143
	s_cselect_b32 s47, s27, s67
	s_cselect_b32 s46, s26, s66
	s_add_i32 s69, 16, 0x14000
	ds_read_b128 v[146:149], v140
	ds_read_b128 v[150:153], v140 offset:1024
	ds_read_b128 v[154:157], v140 offset:2048
	ds_read_b128 v[158:161], v140 offset:3072
	v_add_u32_e32 v140, s69, v143
	ds_read_b128 v[176:179], v140
	ds_read_b128 v[180:183], v140 offset:1024
	ds_read_b128 v[184:187], v140 offset:2048
	ds_read_b128 v[188:191], v140 offset:3072
	v_lshl_add_u64 v[140:141], s[42:43], 0, v[138:139]
	s_add_i32 m0, s9, 0xc000
	ds_read_b128 v[192:195], v145
	ds_read_b128 v[196:199], v145 offset:1024
	ds_read_b128 v[200:203], v145 offset:2048
	ds_read_b128 v[204:207], v145 offset:3072
	ds_read_b128 v[208:211], v145 offset:4096
	ds_read_b128 v[212:215], v145 offset:5120
	ds_read_b128 v[216:219], v145 offset:6144
	ds_read_b128 v[220:223], v145 offset:7168
	global_load_lds_dwordx4 v[140:141], off
	v_lshl_add_u64 v[140:141], s[42:43], 0, v[136:137]
	s_add_i32 m0, s9, 0xe000
	s_nop 0
	global_load_lds_dwordx4 v[140:141], off
	s_waitcnt vmcnt(8)
	s_waitcnt lgkmcnt(0)
	s_setprio 1
	s_barrier
	v_mfma_f32_16x16x32_bf16 v[126:129], v[146:149], v[192:195], v[126:129]
	v_mfma_f32_16x16x32_bf16 v[122:125], v[154:157], v[192:195], v[122:125]
	v_mfma_f32_16x16x32_bf16 v[114:117], v[146:149], v[200:203], v[114:117]
	v_mfma_f32_16x16x32_bf16 v[110:113], v[154:157], v[200:203], v[110:113]
	v_mfma_f32_16x16x32_bf16 v[98:101], v[146:149], v[208:211], v[98:101]
	v_mfma_f32_16x16x32_bf16 v[94:97], v[154:157], v[208:211], v[94:97]
	v_mfma_f32_16x16x32_bf16 v[82:85], v[146:149], v[216:219], v[82:85]
	v_mfma_f32_16x16x32_bf16 v[78:81], v[154:157], v[216:219], v[78:81]
	v_mfma_f32_16x16x32_bf16 v[126:129], v[150:153], v[196:199], v[126:129]
	v_mfma_f32_16x16x32_bf16 v[122:125], v[158:161], v[196:199], v[122:125]
	v_mfma_f32_16x16x32_bf16 v[114:117], v[150:153], v[204:207], v[114:117]
	v_mfma_f32_16x16x32_bf16 v[110:113], v[158:161], v[204:207], v[110:113]
	v_mfma_f32_16x16x32_bf16 v[98:101], v[150:153], v[212:215], v[98:101]
	v_mfma_f32_16x16x32_bf16 v[94:97], v[158:161], v[212:215], v[94:97]
	v_mfma_f32_16x16x32_bf16 v[82:85], v[150:153], v[220:223], v[82:85]
	v_mfma_f32_16x16x32_bf16 v[78:81], v[158:161], v[220:223], v[78:81]
	v_mfma_f32_16x16x32_bf16 v[118:121], v[176:179], v[192:195], v[118:121]
	v_mfma_f32_16x16x32_bf16 v[106:109], v[184:187], v[192:195], v[106:109]
	v_mfma_f32_16x16x32_bf16 v[102:105], v[176:179], v[200:203], v[102:105]
	v_mfma_f32_16x16x32_bf16 v[90:93], v[184:187], v[200:203], v[90:93]
	v_mfma_f32_16x16x32_bf16 v[86:89], v[176:179], v[208:211], v[86:89]
	v_mfma_f32_16x16x32_bf16 v[74:77], v[184:187], v[208:211], v[74:77]
	v_mfma_f32_16x16x32_bf16 v[70:73], v[176:179], v[216:219], v[70:73]
	v_mfma_f32_16x16x32_bf16 v[66:69], v[184:187], v[216:219], v[66:69]
	v_mfma_f32_16x16x32_bf16 v[118:121], v[180:183], v[196:199], v[118:121]
	v_mfma_f32_16x16x32_bf16 v[106:109], v[188:191], v[196:199], v[106:109]
	v_mfma_f32_16x16x32_bf16 v[102:105], v[180:183], v[204:207], v[102:105]
	v_mfma_f32_16x16x32_bf16 v[90:93], v[188:191], v[204:207], v[90:93]
	v_mfma_f32_16x16x32_bf16 v[86:89], v[180:183], v[212:215], v[86:89]
	v_mfma_f32_16x16x32_bf16 v[74:77], v[188:191], v[212:215], v[74:77]
	v_mfma_f32_16x16x32_bf16 v[70:73], v[180:183], v[220:223], v[70:73]
	v_mfma_f32_16x16x32_bf16 v[66:69], v[188:191], v[220:223], v[66:69]
	s_barrier
	s_setprio 0
	s_add_i32 s10, s10, s6
	v_lshl_add_u64 v[140:141], s[46:47], 0, v[0:1]
	s_mov_b32 m0, s10
	ds_read_b128 v[192:195], v145 offset:16384
	ds_read_b128 v[196:199], v145 offset:17408
	ds_read_b128 v[200:203], v145 offset:18432
	ds_read_b128 v[204:207], v145 offset:19456
	ds_read_b128 v[208:211], v145 offset:20480
	ds_read_b128 v[212:215], v145 offset:21504
	ds_read_b128 v[216:219], v145 offset:22528
	ds_read_b128 v[220:223], v145 offset:23552
	global_load_lds_dwordx4 v[140:141], off
	s_add_i32 m0, s10, 0x2000
	s_add_u32 s10, s46, 0xb0000
	v_lshl_add_u64 v[224:225], s[46:47], 0, v[130:131]
	s_addc_u32 s11, s47, 0
	s_add_i32 s42, s69, s6
	global_load_lds_dwordx4 v[224:225], off
	v_lshl_add_u64 v[226:227], s[10:11], 0, v[0:1]
	s_mov_b32 m0, s42
	v_lshl_add_u64 v[238:239], s[48:49], 0, v[132:133]
	global_load_lds_dwordx4 v[226:227], off
	v_lshl_add_u64 v[226:227], s[10:11], 0, v[130:131]
	s_add_i32 m0, s42, 0x2000
	s_nop 0
	global_load_lds_dwordx4 v[226:227], off
	v_lshl_add_u64 v[226:227], s[48:49], 0, v[134:135]
	s_mov_b32 m0, s9
	s_nop 0
	global_load_lds_dwordx4 v[226:227], off
	s_mov_b32 m0, s50
	s_nop 0
	global_load_lds_dwordx4 v[238:239], off
	s_waitcnt vmcnt(8)
	s_waitcnt lgkmcnt(0)
	s_setprio 1
	s_barrier
; #define PG8_STAGE(bufoff, gbase, voff) do { _Pragma("unroll") for (int _i = 0; _i < 2; ++_i) \
;         __builtin_amdgcn_global_load_lds((const unsigned*)((const char*)(gbase) + (voff)[_i]), (PG8_LAS unsigned*)(lds + (bufoff) + ldsw + _i * 8192), 16, 0, 0); } while (0)
; #define PG8_LDA(dst, b, h) do { _Pragma("unroll") for (int m = 0; m < 4; ++m) _Pragma("unroll") for (int k = 0; k < 2; ++k) dst[m][k] = *(const PG8_LAS bf16x8*)(lds + PG8_SA(b, h) + aoff + m * 2048 + k * 1024); } while (0)
; #define PG8_LDB(dst, b, h) do { _Pragma("unroll") for (int n = 0; n < 2; ++n) _Pragma("unroll") for (int k = 0; k < 2; ++k) dst[n][k] = *(const PG8_LAS bf16x8*)(lds + PG8_SB(b, h) + boff + n * 2048 + k * 1024); } while (0)
; #define PG8_MMA(ai, bj, At, Bt) do { __builtin_amdgcn_s_setprio(1); _Pragma("unroll") for (int m = 0; m < 4; ++m) _Pragma("unroll") for (int n = 0; n < 2; ++n) _Pragma("unroll") for (int k = 0; k < 2; ++k) \
;         acc[ai][bj][m][n] = __builtin_amdgcn_mfma_f32_16x16x32_bf16(Bt[n][k], At[m][k], acc[ai][bj][m][n], 0, 0, 0); __builtin_amdgcn_s_setprio(0); } while (0)
; #define PG8_WAIT_V(n) asm volatile("s_waitcnt vmcnt(" #n ")" ::: "memory")
; #define PG8_WAIT_L(n) asm volatile("s_waitcnt lgkmcnt(" #n ")" ::: "memory")
; #define PG8_BAR __builtin_amdgcn_s_barrier()
; #define PG8_SCHED __builtin_amdgcn_sched_barrier(0)
; template <class Epi, class Sched, bool ALIGN_EPI = false, bool SP2 = false>
; __device__ __forceinline__ void gemm_phase(PG8_LAS unsigned char* lds, const Gemm g, const Sched& S, const Epi& E) {
;     ...
;             PG8_WAIT_V(8); PG8_WAIT_L(0); PG8_BAR; PG8_MMA(1, 0, At, B0); PG8_MMA(1, 1, At, B1); PG8_BAR; PG8_SCHED;
;             PG8_LDB(B0, 1, 0); PG8_LDB(B1, 1, 1); PG8_SCHED; PG8_LDA(At, 1, 0); PG8_STAGE(PG8_SA(0, 1), a2 + hstep, voffA);
;             PG8_WAIT_V(8); PG8_WAIT_L(0); PG8_BAR; PG8_MMA(0, 0, At, B0); PG8_MMA(0, 1, At, B1); PG8_BAR; PG8_SCHED;
	v_mfma_f32_16x16x32_bf16 v[62:65], v[146:149], v[192:195], v[62:65]
	v_mfma_f32_16x16x32_bf16 v[58:61], v[154:157], v[192:195], v[58:61]
	v_mfma_f32_16x16x32_bf16 v[50:53], v[146:149], v[200:203], v[50:53]
	v_mfma_f32_16x16x32_bf16 v[46:49], v[154:157], v[200:203], v[46:49]
	v_mfma_f32_16x16x32_bf16 v[34:37], v[146:149], v[208:211], v[34:37]
	v_mfma_f32_16x16x32_bf16 v[30:33], v[154:157], v[208:211], v[30:33]
	v_mfma_f32_16x16x32_bf16 v[18:21], v[146:149], v[216:219], v[18:21]
	v_mfma_f32_16x16x32_bf16 v[14:17], v[154:157], v[216:219], v[14:17]
	v_mfma_f32_16x16x32_bf16 v[62:65], v[150:153], v[196:199], v[62:65]
	v_mfma_f32_16x16x32_bf16 v[58:61], v[158:161], v[196:199], v[58:61]
	v_mfma_f32_16x16x32_bf16 v[50:53], v[150:153], v[204:207], v[50:53]
	v_mfma_f32_16x16x32_bf16 v[46:49], v[158:161], v[204:207], v[46:49]
	v_mfma_f32_16x16x32_bf16 v[34:37], v[150:153], v[212:215], v[34:37]
	v_mfma_f32_16x16x32_bf16 v[30:33], v[158:161], v[212:215], v[30:33]
	v_mfma_f32_16x16x32_bf16 v[18:21], v[150:153], v[220:223], v[18:21]
	v_mfma_f32_16x16x32_bf16 v[14:17], v[158:161], v[220:223], v[14:17]
	v_mfma_f32_16x16x32_bf16 v[54:57], v[176:179], v[192:195], v[54:57]
	v_mfma_f32_16x16x32_bf16 v[42:45], v[184:187], v[192:195], v[42:45]
	v_mfma_f32_16x16x32_bf16 v[38:41], v[176:179], v[200:203], v[38:41]
	v_mfma_f32_16x16x32_bf16 v[26:29], v[184:187], v[200:203], v[26:29]
	v_mfma_f32_16x16x32_bf16 v[22:25], v[176:179], v[208:211], v[22:25]
	v_mfma_f32_16x16x32_bf16 v[10:13], v[184:187], v[208:211], v[10:13]
	v_mfma_f32_16x16x32_bf16 v[6:9], v[176:179], v[216:219], v[6:9]
	v_mfma_f32_16x16x32_bf16 v[2:5], v[184:187], v[216:219], v[2:5]
	v_mfma_f32_16x16x32_bf16 v[54:57], v[180:183], v[196:199], v[54:57]
	v_mfma_f32_16x16x32_bf16 v[42:45], v[188:191], v[196:199], v[42:45]
	v_mfma_f32_16x16x32_bf16 v[38:41], v[180:183], v[204:207], v[38:41]
	v_mfma_f32_16x16x32_bf16 v[26:29], v[188:191], v[204:207], v[26:29]
	v_mfma_f32_16x16x32_bf16 v[22:25], v[180:183], v[212:215], v[22:25]
	v_mfma_f32_16x16x32_bf16 v[10:13], v[188:191], v[212:215], v[10:13]
	v_mfma_f32_16x16x32_bf16 v[6:9], v[180:183], v[220:223], v[6:9]
	v_mfma_f32_16x16x32_bf16 v[2:5], v[188:191], v[220:223], v[2:5]
	s_barrier
	s_setprio 0
	s_add_i32 s42, 16, 0x18000
	s_add_i32 s43, 16, 0x1c000
	v_add_u32_e32 v158, s42, v143
	v_add_u32_e32 v188, s43, v143
	ds_read_b128 v[146:149], v158
	ds_read_b128 v[150:153], v158 offset:1024
	ds_read_b128 v[154:157], v158 offset:2048
	ds_read_b128 v[158:161], v158 offset:3072
	ds_read_b128 v[176:179], v188
	ds_read_b128 v[180:183], v188 offset:1024
	ds_read_b128 v[184:187], v188 offset:2048
	ds_read_b128 v[188:191], v188 offset:3072
	s_add_u32 s10, s48, 0xb0000
	s_addc_u32 s11, s49, 0
	s_mov_b32 m0, s51
	v_lshl_add_u64 v[240:241], s[10:11], 0, v[134:135]
	ds_read_b128 v[192:195], v145 offset:32768
	ds_read_b128 v[196:199], v145 offset:33792
	ds_read_b128 v[200:203], v145 offset:34816
	ds_read_b128 v[204:207], v145 offset:35840
	ds_read_b128 v[208:211], v145 offset:36864
	ds_read_b128 v[212:215], v145 offset:37888
	ds_read_b128 v[216:219], v145 offset:38912
	ds_read_b128 v[220:223], v145 offset:39936
	global_load_lds_dwordx4 v[240:241], off
	v_lshl_add_u64 v[240:241], s[10:11], 0, v[132:133]
	s_mov_b32 m0, s54
	s_nop 0
	global_load_lds_dwordx4 v[240:241], off
	s_waitcnt vmcnt(8)
	s_waitcnt lgkmcnt(0)
	s_setprio 1
	s_barrier
	v_mfma_f32_16x16x32_bf16 v[126:129], v[146:149], v[192:195], v[126:129]
	v_mfma_f32_16x16x32_bf16 v[122:125], v[154:157], v[192:195], v[122:125]
	v_mfma_f32_16x16x32_bf16 v[114:117], v[146:149], v[200:203], v[114:117]
	v_mfma_f32_16x16x32_bf16 v[110:113], v[154:157], v[200:203], v[110:113]
	v_mfma_f32_16x16x32_bf16 v[98:101], v[146:149], v[208:211], v[98:101]
	v_mfma_f32_16x16x32_bf16 v[94:97], v[154:157], v[208:211], v[94:97]
	v_mfma_f32_16x16x32_bf16 v[82:85], v[146:149], v[216:219], v[82:85]
	v_mfma_f32_16x16x32_bf16 v[78:81], v[154:157], v[216:219], v[78:81]
	v_mfma_f32_16x16x32_bf16 v[126:129], v[150:153], v[196:199], v[126:129]
	v_mfma_f32_16x16x32_bf16 v[122:125], v[158:161], v[196:199], v[122:125]
	v_mfma_f32_16x16x32_bf16 v[114:117], v[150:153], v[204:207], v[114:117]
	v_mfma_f32_16x16x32_bf16 v[110:113], v[158:161], v[204:207], v[110:113]
	v_mfma_f32_16x16x32_bf16 v[98:101], v[150:153], v[212:215], v[98:101]
	v_mfma_f32_16x16x32_bf16 v[94:97], v[158:161], v[212:215], v[94:97]
	v_mfma_f32_16x16x32_bf16 v[82:85], v[150:153], v[220:223], v[82:85]
	v_mfma_f32_16x16x32_bf16 v[78:81], v[158:161], v[220:223], v[78:81]
	v_mfma_f32_16x16x32_bf16 v[118:121], v[176:179], v[192:195], v[118:121]
	v_mfma_f32_16x16x32_bf16 v[106:109], v[184:187], v[192:195], v[106:109]
	v_mfma_f32_16x16x32_bf16 v[102:105], v[176:179], v[200:203], v[102:105]
	v_mfma_f32_16x16x32_bf16 v[90:93], v[184:187], v[200:203], v[90:93]
	v_mfma_f32_16x16x32_bf16 v[86:89], v[176:179], v[208:211], v[86:89]
	v_mfma_f32_16x16x32_bf16 v[74:77], v[184:187], v[208:211], v[74:77]
	v_mfma_f32_16x16x32_bf16 v[70:73], v[176:179], v[216:219], v[70:73]
	v_mfma_f32_16x16x32_bf16 v[66:69], v[184:187], v[216:219], v[66:69]
	v_mfma_f32_16x16x32_bf16 v[118:121], v[180:183], v[196:199], v[118:121]
	v_mfma_f32_16x16x32_bf16 v[106:109], v[188:191], v[196:199], v[106:109]
	v_mfma_f32_16x16x32_bf16 v[102:105], v[180:183], v[204:207], v[102:105]
	v_mfma_f32_16x16x32_bf16 v[90:93], v[188:191], v[204:207], v[90:93]
	v_mfma_f32_16x16x32_bf16 v[86:89], v[180:183], v[212:215], v[86:89]
	v_mfma_f32_16x16x32_bf16 v[74:77], v[188:191], v[212:215], v[74:77]
	v_mfma_f32_16x16x32_bf16 v[70:73], v[180:183], v[220:223], v[70:73]
	v_mfma_f32_16x16x32_bf16 v[66:69], v[188:191], v[220:223], v[66:69]
	s_barrier
; #define PG8_STAGE(bufoff, gbase, voff) do { _Pragma("unroll") for (int _i = 0; _i < 2; ++_i) \
;         __builtin_amdgcn_global_load_lds((const unsigned*)((const char*)(gbase) + (voff)[_i]), (PG8_LAS unsigned*)(lds + (bufoff) + ldsw + _i * 8192), 16, 0, 0); } while (0)
; #define PG8_LDA(dst, b, h) do { _Pragma("unroll") for (int m = 0; m < 4; ++m) _Pragma("unroll") for (int k = 0; k < 2; ++k) dst[m][k] = *(const PG8_LAS bf16x8*)(lds + PG8_SA(b, h) + aoff + m * 2048 + k * 1024); } while (0)
; #define PG8_MMA(ai, bj, At, Bt) do { __builtin_amdgcn_s_setprio(1); _Pragma("unroll") for (int m = 0; m < 4; ++m) _Pragma("unroll") for (int n = 0; n < 2; ++n) _Pragma("unroll") for (int k = 0; k < 2; ++k) \
;         acc[ai][bj][m][n] = __builtin_amdgcn_mfma_f32_16x16x32_bf16(Bt[n][k], At[m][k], acc[ai][bj][m][n], 0, 0, 0); __builtin_amdgcn_s_setprio(0); } while (0)
; #define PG8_WAIT_V(n) asm volatile("s_waitcnt vmcnt(" #n ")" ::: "memory")
; #define PG8_WAIT_L(n) asm volatile("s_waitcnt lgkmcnt(" #n ")" ::: "memory")
; #define PG8_BAR __builtin_amdgcn_s_barrier()
; #define PG8_SCHED __builtin_amdgcn_sched_barrier(0)
; template <class Epi, class Sched, bool ALIGN_EPI = false, bool SP2 = false>
; __device__ __forceinline__ void gemm_phase(PG8_LAS unsigned char* lds, const Gemm g, const Sched& S, const Epi& E) {
;     ...
;             PG8_LDA(At, 1, 1); PG8_STAGE(PG8_SB(1, 0), b3, voffB); PG8_STAGE(PG8_SB(1, 1), b3 + hstep, voffB); PG8_STAGE(PG8_SA(1, 0), a3, voffA);
;             PG8_WAIT_V(8); PG8_WAIT_L(0); PG8_BAR; PG8_MMA(1, 0, At, B0); PG8_MMA(1, 1, At, B1); PG8_BAR; PG8_SCHED;
;     ...
;         if constexpr (ALIGN_EPI) { if (wr == 0) PG8_BAR; }
	s_setprio 0
	s_add_i32 s10, s42, s6
	v_lshl_add_u64 v[140:141], v[140:141], 0, s[28:29]
	s_mov_b32 m0, s10
	ds_read_b128 v[192:195], v145 offset:49152
	ds_read_b128 v[196:199], v145 offset:50176
	ds_read_b128 v[200:203], v145 offset:51200
	ds_read_b128 v[204:207], v145 offset:52224
	ds_read_b128 v[208:211], v145 offset:53248
	ds_read_b128 v[212:215], v145 offset:54272
	ds_read_b128 v[216:219], v145 offset:55296
	ds_read_b128 v[220:223], v145 offset:56320
	global_load_lds_dwordx4 v[140:141], off
	s_add_i32 m0, s10, 0x2000
	s_add_u32 s10, s46, 0xb0080
	v_lshl_add_u64 v[140:141], v[224:225], 0, s[28:29]
	s_addc_u32 s11, s47, 0
	s_add_i32 s42, s43, s6
	global_load_lds_dwordx4 v[140:141], off
	v_lshl_add_u64 v[140:141], s[10:11], 0, v[0:1]
	s_mov_b32 m0, s42
	s_nop 0
	global_load_lds_dwordx4 v[140:141], off
	v_lshl_add_u64 v[140:141], s[10:11], 0, v[130:131]
	s_add_i32 m0, s42, 0x2000
	s_nop 0
	global_load_lds_dwordx4 v[140:141], off
	v_lshl_add_u64 v[140:141], v[226:227], 0, s[28:29]
	s_mov_b32 m0, s57
	s_nop 0
	global_load_lds_dwordx4 v[140:141], off
	v_lshl_add_u64 v[140:141], v[238:239], 0, s[28:29]
	s_mov_b32 m0, s58
	s_nop 0
	global_load_lds_dwordx4 v[140:141], off
	s_waitcnt vmcnt(8)
	s_waitcnt lgkmcnt(0)
	s_setprio 1
	s_barrier
	v_mfma_f32_16x16x32_bf16 v[62:65], v[146:149], v[192:195], v[62:65]
	v_mfma_f32_16x16x32_bf16 v[58:61], v[154:157], v[192:195], v[58:61]
	v_mfma_f32_16x16x32_bf16 v[50:53], v[146:149], v[200:203], v[50:53]
	v_mfma_f32_16x16x32_bf16 v[46:49], v[154:157], v[200:203], v[46:49]
	v_mfma_f32_16x16x32_bf16 v[34:37], v[146:149], v[208:211], v[34:37]
	v_mfma_f32_16x16x32_bf16 v[30:33], v[154:157], v[208:211], v[30:33]
	v_mfma_f32_16x16x32_bf16 v[18:21], v[146:149], v[216:219], v[18:21]
	v_mfma_f32_16x16x32_bf16 v[14:17], v[154:157], v[216:219], v[14:17]
	v_mfma_f32_16x16x32_bf16 v[62:65], v[150:153], v[196:199], v[62:65]
	v_mfma_f32_16x16x32_bf16 v[58:61], v[158:161], v[196:199], v[58:61]
	v_mfma_f32_16x16x32_bf16 v[50:53], v[150:153], v[204:207], v[50:53]
	v_mfma_f32_16x16x32_bf16 v[46:49], v[158:161], v[204:207], v[46:49]
	v_mfma_f32_16x16x32_bf16 v[34:37], v[150:153], v[212:215], v[34:37]
	v_mfma_f32_16x16x32_bf16 v[30:33], v[158:161], v[212:215], v[30:33]
	v_mfma_f32_16x16x32_bf16 v[18:21], v[150:153], v[220:223], v[18:21]
	v_mfma_f32_16x16x32_bf16 v[14:17], v[158:161], v[220:223], v[14:17]
	v_mfma_f32_16x16x32_bf16 v[54:57], v[176:179], v[192:195], v[54:57]
	v_mfma_f32_16x16x32_bf16 v[42:45], v[184:187], v[192:195], v[42:45]
	v_mfma_f32_16x16x32_bf16 v[38:41], v[176:179], v[200:203], v[38:41]
	v_mfma_f32_16x16x32_bf16 v[26:29], v[184:187], v[200:203], v[26:29]
	v_mfma_f32_16x16x32_bf16 v[22:25], v[176:179], v[208:211], v[22:25]
	v_mfma_f32_16x16x32_bf16 v[10:13], v[184:187], v[208:211], v[10:13]
	v_mfma_f32_16x16x32_bf16 v[6:9], v[176:179], v[216:219], v[6:9]
	v_mfma_f32_16x16x32_bf16 v[2:5], v[184:187], v[216:219], v[2:5]
	v_mfma_f32_16x16x32_bf16 v[54:57], v[180:183], v[196:199], v[54:57]
	v_mfma_f32_16x16x32_bf16 v[42:45], v[188:191], v[196:199], v[42:45]
	v_mfma_f32_16x16x32_bf16 v[38:41], v[180:183], v[204:207], v[38:41]
	v_mfma_f32_16x16x32_bf16 v[26:29], v[188:191], v[204:207], v[26:29]
	v_mfma_f32_16x16x32_bf16 v[22:25], v[180:183], v[212:215], v[22:25]
	v_mfma_f32_16x16x32_bf16 v[10:13], v[188:191], v[212:215], v[10:13]
	v_mfma_f32_16x16x32_bf16 v[6:9], v[180:183], v[220:223], v[6:9]
	v_mfma_f32_16x16x32_bf16 v[2:5], v[188:191], v[220:223], v[2:5]
	s_barrier
	s_setprio 0
	s_add_i32 s68, s68, 2
	s_add_u32 s66, s66, 0x100
	s_addc_u32 s67, s67, 0
	s_cmp_gt_u32 s68, 41
	s_mov_b64 s[42:43], s[40:41]
	s_cbranch_scc0 .LBB0_1295
	s_and_b64 vcc, exec, s[22:23]
	s_cbranch_vccz .LBB0_1298
	s_barrier
